# priority raised in the load segments instead of the MFMA segments (8 GEMM K-loops)
# baseline (speedup 1.0000x reference)
;     __device__ __forceinline__ int nt(const Unit& u) const { return (u.pn >> 1) < 2 ? 22 : 20; }
; #define PG8_STAGE(bufoff, gbase, voff) do { _Pragma("unroll") for (int _i = 0; _i < 2; ++_i) \
;         __builtin_amdgcn_global_load_lds((const unsigned*)((const char*)(gbase) + (voff)[_i]), (LAS unsigned*)(lds + (bufoff) + ldsw + _i * 8192), 16, 0, 0); } while (0)
; #define PG8_LDA(dst, b, h) do { _Pragma("unroll") for (int m = 0; m < 4; ++m) _Pragma("unroll") for (int k = 0; k < 2; ++k) dst[m][k] = *(const LAS bf16x8*)(pA + PG8_SA(b, h) + m * 2048 + k * 1024); } while (0)
; #define PG8_LDB(dst, b, h) do { _Pragma("unroll") for (int n = 0; n < 2; ++n) _Pragma("unroll") for (int k = 0; k < 2; ++k) dst[n][k] = *(const LAS bf16x8*)(pB + (PG8_SB(b, h) - 4 * HTB) + n * 2048 + k * 1024); } while (0)
; #define PG8_MMA(ai, bj, At, Bt) do { __builtin_amdgcn_s_setprio(1); _Pragma("unroll") for (int m = 0; m < 4; ++m) _Pragma("unroll") for (int n = 0; n < 2; ++n) _Pragma("unroll") for (int k = 0; k < 2; ++k) \
;         acc[ai][bj][m][n] = __builtin_amdgcn_mfma_f32_16x16x32_bf16(Bt[n][k], At[m][k], acc[ai][bj][m][n], 0, 0, 0); __builtin_amdgcn_s_setprio(0); } while (0)
; #define PG8_WAIT_V(n) asm volatile("s_waitcnt vmcnt(" #n ")" ::: "memory")
; #define PG8_WAIT_L(n) asm volatile("s_waitcnt lgkmcnt(" #n ")" ::: "memory")
; template <class Desc, class Epi, bool ALIGN_EPI>
; __device__ __forceinline__ void gemm_phase(LAS unsigned char* lds, const Desc& D, const Epi& E, int G, int c) {
;     ...
;             const bool last = (t == nt - 2);
;             if (last && has_next) PG8_AWAIT(nxt);
;             const char* a1 = cA + (size_t)(t + 1) * kstep;
;             const char* a2 = last ? nA : cA + (size_t)(t + 2) * kstep; const char* b2 = last ? nB : cB + (size_t)(t + 2) * kstep;
;             const char* a3 = a2 + kstep; const char* b3 = b2 + kstep;
;             PG8_LDB(B0, 0, 0); PG8_LDB(B1, 0, 1); PG8_SCHED; PG8_LDA(At, 0, 0); PG8_STAGE(PG8_SA(1, 1), a1 + hstepA, voffA);
;             PG8_WAIT_V(8); PG8_WAIT_L(0); PG8_BAR; PG8_MMA(0, 0, At, B0); PG8_MMA(0, 1, At, B1); PG8_BAR; PG8_SCHED;
;             PG8_LDA(At, 0, 1); PG8_STAGE(PG8_SB(0, 0), b2, voffB); PG8_STAGE(PG8_SB(0, 1), b2 + hstepB, voffB); PG8_STAGE(PG8_SA(0, 0), a2, voffA);
;             PG8_WAIT_V(8); PG8_WAIT_L(0); PG8_BAR; PG8_MMA(1, 0, At, B0); PG8_MMA(1, 1, At, B1); PG8_BAR; PG8_SCHED;
.LBB0_172:
	s_or_b32 s14, s17, 1
	s_lshl_b64 s[26:27], s[14:15], 7
	s_add_i32 s14, s17, 2
	s_lshl_b64 s[40:41], s[14:15], 7
	s_add_u32 s17, s12, s40
	ds_read_b128 v[134:137], v169
	ds_read_b128 v[138:141], v169 offset:1024
	ds_read_b128 v[142:145], v169 offset:2048
	ds_read_b128 v[146:149], v169 offset:3072
	ds_read_b128 v[160:163], v169 offset:16384
	ds_read_b128 v[164:167], v169 offset:17408
	ds_read_b128 v[174:177], v169 offset:18432
	ds_read_b128 v[178:181], v169 offset:19456
	s_addc_u32 s21, s13, s41
	s_and_b64 s[38:39], s[30:31], exec
	s_cselect_b32 s39, s61, s21
	s_cselect_b32 s38, s60, s17
	s_add_u32 s17, s18, s40
	s_addc_u32 s21, s19, s41
	s_and_b64 s[30:31], s[30:31], exec
	s_cselect_b32 s31, s63, s21
	s_cselect_b32 s30, s62, s17
	s_add_u32 s17, s12, s26
	s_addc_u32 s21, s13, s27
	s_add_u32 s26, s17, 0x100000
	s_addc_u32 s27, s21, 0
	s_mov_b32 m0, s50
	v_lshl_add_u64 v[150:151], s[26:27], 0, v[152:153]
	ds_read_b128 v[182:185], v168
	ds_read_b128 v[186:189], v168 offset:1024
	ds_read_b128 v[190:193], v168 offset:2048
	ds_read_b128 v[194:197], v168 offset:3072
	ds_read_b128 v[198:201], v168 offset:4096
	ds_read_b128 v[202:205], v168 offset:5120
	ds_read_b128 v[206:209], v168 offset:6144
	ds_read_b128 v[210:213], v168 offset:7168
	global_load_lds_dwordx4 v[150:151], off
	v_lshl_add_u64 v[150:151], s[26:27], 0, v[156:157]
	s_mov_b32 m0, s51
	s_nop 0
	global_load_lds_dwordx4 v[150:151], off
	s_waitcnt vmcnt(8)
	s_waitcnt lgkmcnt(0)
	s_setprio 0
	s_barrier
	v_mfma_f32_16x16x32_bf16 v[128:131], v[134:137], v[182:185], v[128:131]
	v_mfma_f32_16x16x32_bf16 v[124:127], v[142:145], v[182:185], v[124:127]
	v_mfma_f32_16x16x32_bf16 v[120:123], v[134:137], v[190:193], v[120:123]
	v_mfma_f32_16x16x32_bf16 v[116:119], v[142:145], v[190:193], v[116:119]
	v_mfma_f32_16x16x32_bf16 v[112:115], v[134:137], v[198:201], v[112:115]
	v_mfma_f32_16x16x32_bf16 v[108:111], v[142:145], v[198:201], v[108:111]
	v_mfma_f32_16x16x32_bf16 v[104:107], v[134:137], v[206:209], v[104:107]
	v_mfma_f32_16x16x32_bf16 v[100:103], v[142:145], v[206:209], v[100:103]
	v_mfma_f32_16x16x32_bf16 v[128:131], v[138:141], v[186:189], v[128:131]
	v_mfma_f32_16x16x32_bf16 v[124:127], v[146:149], v[186:189], v[124:127]
	v_mfma_f32_16x16x32_bf16 v[120:123], v[138:141], v[194:197], v[120:123]
	v_mfma_f32_16x16x32_bf16 v[116:119], v[146:149], v[194:197], v[116:119]
	v_mfma_f32_16x16x32_bf16 v[112:115], v[138:141], v[202:205], v[112:115]
	v_mfma_f32_16x16x32_bf16 v[108:111], v[146:149], v[202:205], v[108:111]
	v_mfma_f32_16x16x32_bf16 v[104:107], v[138:141], v[210:213], v[104:107]
	v_mfma_f32_16x16x32_bf16 v[100:103], v[146:149], v[210:213], v[100:103]
	v_mfma_f32_16x16x32_bf16 v[96:99], v[160:163], v[182:185], v[96:99]
	v_mfma_f32_16x16x32_bf16 v[92:95], v[174:177], v[182:185], v[92:95]
	v_mfma_f32_16x16x32_bf16 v[88:91], v[160:163], v[190:193], v[88:91]
	v_mfma_f32_16x16x32_bf16 v[84:87], v[174:177], v[190:193], v[84:87]
	v_mfma_f32_16x16x32_bf16 v[80:83], v[160:163], v[198:201], v[80:83]
	v_mfma_f32_16x16x32_bf16 v[76:79], v[174:177], v[198:201], v[76:79]
	v_mfma_f32_16x16x32_bf16 v[72:75], v[160:163], v[206:209], v[72:75]
	v_mfma_f32_16x16x32_bf16 v[68:71], v[174:177], v[206:209], v[68:71]
	v_mfma_f32_16x16x32_bf16 v[96:99], v[164:167], v[186:189], v[96:99]
	v_mfma_f32_16x16x32_bf16 v[92:95], v[178:181], v[186:189], v[92:95]
	v_mfma_f32_16x16x32_bf16 v[88:91], v[164:167], v[194:197], v[88:91]
	v_mfma_f32_16x16x32_bf16 v[84:87], v[178:181], v[194:197], v[84:87]
	v_mfma_f32_16x16x32_bf16 v[80:83], v[164:167], v[202:205], v[80:83]
	v_mfma_f32_16x16x32_bf16 v[76:79], v[178:181], v[202:205], v[76:79]
	v_mfma_f32_16x16x32_bf16 v[72:75], v[164:167], v[210:213], v[72:75]
	v_mfma_f32_16x16x32_bf16 v[68:71], v[178:181], v[210:213], v[68:71]
	s_barrier
	s_setprio 1
	s_mov_b32 m0, s84
	v_lshl_add_u64 v[150:151], s[30:31], 0, v[154:155]
	s_add_u32 s26, s30, 0x100000
	ds_read_b128 v[182:185], v168 offset:16384
	ds_read_b128 v[186:189], v168 offset:17408
	ds_read_b128 v[190:193], v168 offset:18432
	ds_read_b128 v[194:197], v168 offset:19456
	ds_read_b128 v[198:201], v168 offset:20480
	ds_read_b128 v[202:205], v168 offset:21504
	ds_read_b128 v[206:209], v168 offset:22528
	ds_read_b128 v[210:213], v168 offset:23552
	global_load_lds_dwordx4 v[150:151], off
	v_lshl_add_u64 v[214:215], s[30:31], 0, v[158:159]
	s_mov_b32 m0, s85
	s_addc_u32 s27, s31, 0
	global_load_lds_dwordx4 v[214:215], off
	v_lshl_add_u64 v[216:217], s[26:27], 0, v[154:155]
	s_mov_b32 m0, s86
	v_lshl_add_u64 v[218:219], s[38:39], 0, v[156:157]
	global_load_lds_dwordx4 v[216:217], off
	v_lshl_add_u64 v[216:217], s[26:27], 0, v[158:159]
	s_mov_b32 m0, s87
	s_nop 0
	global_load_lds_dwordx4 v[216:217], off
	v_lshl_add_u64 v[216:217], s[38:39], 0, v[152:153]
	s_mov_b32 m0, s83
	s_nop 0
	global_load_lds_dwordx4 v[216:217], off
	s_mov_b32 m0, s88
	s_nop 0
	global_load_lds_dwordx4 v[218:219], off
	s_waitcnt vmcnt(8)
	s_waitcnt lgkmcnt(0)
	s_setprio 0
	s_barrier
; #define PG8_STAGE(bufoff, gbase, voff) do { _Pragma("unroll") for (int _i = 0; _i < 2; ++_i) \
;         __builtin_amdgcn_global_load_lds((const unsigned*)((const char*)(gbase) + (voff)[_i]), (LAS unsigned*)(lds + (bufoff) + ldsw + _i * 8192), 16, 0, 0); } while (0)
; #define PG8_LDA(dst, b, h) do { _Pragma("unroll") for (int m = 0; m < 4; ++m) _Pragma("unroll") for (int k = 0; k < 2; ++k) dst[m][k] = *(const LAS bf16x8*)(pA + PG8_SA(b, h) + m * 2048 + k * 1024); } while (0)
; #define PG8_LDB(dst, b, h) do { _Pragma("unroll") for (int n = 0; n < 2; ++n) _Pragma("unroll") for (int k = 0; k < 2; ++k) dst[n][k] = *(const LAS bf16x8*)(pB + (PG8_SB(b, h) - 4 * HTB) + n * 2048 + k * 1024); } while (0)
; #define PG8_MMA(ai, bj, At, Bt) do { __builtin_amdgcn_s_setprio(1); _Pragma("unroll") for (int m = 0; m < 4; ++m) _Pragma("unroll") for (int n = 0; n < 2; ++n) _Pragma("unroll") for (int k = 0; k < 2; ++k) \
;         acc[ai][bj][m][n] = __builtin_amdgcn_mfma_f32_16x16x32_bf16(Bt[n][k], At[m][k], acc[ai][bj][m][n], 0, 0, 0); __builtin_amdgcn_s_setprio(0); } while (0)
; #define PG8_WAIT_V(n) asm volatile("s_waitcnt vmcnt(" #n ")" ::: "memory")
; #define PG8_BAR __builtin_amdgcn_s_barrier()
; template <class Desc, class Epi, bool ALIGN_EPI>
; __device__ __forceinline__ void gemm_phase(LAS unsigned char* lds, const Desc& D, const Epi& E, int G, int c) {
;     ...
;             PG8_LDB(B0, 0, 0); PG8_LDB(B1, 0, 1); PG8_SCHED; PG8_LDA(At, 0, 0); PG8_STAGE(PG8_SA(1, 1), a1 + hstepA, voffA);
;             PG8_WAIT_V(8); PG8_WAIT_L(0); PG8_BAR; PG8_MMA(0, 0, At, B0); PG8_MMA(0, 1, At, B1); PG8_BAR; PG8_SCHED;
;             PG8_LDA(At, 0, 1); PG8_STAGE(PG8_SB(0, 0), b2, voffB); PG8_STAGE(PG8_SB(0, 1), b2 + hstepB, voffB); PG8_STAGE(PG8_SA(0, 0), a2, voffA);
;             PG8_WAIT_V(8); PG8_WAIT_L(0); PG8_BAR; PG8_MMA(1, 0, At, B0); PG8_MMA(1, 1, At, B1); PG8_BAR; PG8_SCHED;
;             PG8_LDB(B0, 1, 0); PG8_LDB(B1, 1, 1); PG8_SCHED; PG8_LDA(At, 1, 0); PG8_STAGE(PG8_SA(0, 1), a2 + hstepA, voffA);
;             PG8_WAIT_V(8); PG8_WAIT_L(0); PG8_BAR; PG8_MMA(0, 0, At, B0); PG8_MMA(0, 1, At, B1); PG8_BAR; PG8_SCHED;
;             PG8_LDA(At, 1, 1); PG8_STAGE(PG8_SB(1, 0), b3, voffB); PG8_STAGE(PG8_SB(1, 1), b3 + hstepB, voffB); PG8_STAGE(PG8_SA(1, 0), a3, voffA);
;             PG8_WAIT_V(8); PG8_WAIT_L(0); PG8_BAR; PG8_MMA(1, 0, At, B0); PG8_MMA(1, 1, At, B1); PG8_BAR; PG8_SCHED;
	v_mfma_f32_16x16x32_bf16 v[64:67], v[134:137], v[182:185], v[64:67]
	v_mfma_f32_16x16x32_bf16 v[52:55], v[142:145], v[182:185], v[52:55]
	v_mfma_f32_16x16x32_bf16 v[32:35], v[134:137], v[190:193], v[32:35]
	v_mfma_f32_16x16x32_bf16 v[20:23], v[142:145], v[190:193], v[20:23]
	v_mfma_f32_16x16x32_bf16 v[16:19], v[134:137], v[198:201], v[16:19]
	v_mfma_f32_16x16x32_bf16 v[12:15], v[142:145], v[198:201], v[12:15]
	v_mfma_f32_16x16x32_bf16 v[8:11], v[134:137], v[206:209], v[8:11]
	v_mfma_f32_16x16x32_bf16 v[4:7], v[142:145], v[206:209], v[4:7]
	v_mfma_f32_16x16x32_bf16 v[64:67], v[138:141], v[186:189], v[64:67]
	v_mfma_f32_16x16x32_bf16 v[52:55], v[146:149], v[186:189], v[52:55]
	v_mfma_f32_16x16x32_bf16 v[32:35], v[138:141], v[194:197], v[32:35]
	v_mfma_f32_16x16x32_bf16 v[20:23], v[146:149], v[194:197], v[20:23]
	v_mfma_f32_16x16x32_bf16 v[16:19], v[138:141], v[202:205], v[16:19]
	v_mfma_f32_16x16x32_bf16 v[12:15], v[146:149], v[202:205], v[12:15]
	v_mfma_f32_16x16x32_bf16 v[8:11], v[138:141], v[210:213], v[8:11]
	v_mfma_f32_16x16x32_bf16 v[4:7], v[146:149], v[210:213], v[4:7]
	v_mfma_f32_16x16x32_bf16 v[60:63], v[160:163], v[182:185], v[60:63]
	v_mfma_f32_16x16x32_bf16 v[56:59], v[174:177], v[182:185], v[56:59]
	v_mfma_f32_16x16x32_bf16 v[48:51], v[160:163], v[190:193], v[48:51]
	v_mfma_f32_16x16x32_bf16 v[44:47], v[174:177], v[190:193], v[44:47]
	v_mfma_f32_16x16x32_bf16 v[40:43], v[160:163], v[198:201], v[40:43]
	v_mfma_f32_16x16x32_bf16 v[36:39], v[174:177], v[198:201], v[36:39]
	v_mfma_f32_16x16x32_bf16 v[28:31], v[160:163], v[206:209], v[28:31]
	v_mfma_f32_16x16x32_bf16 v[24:27], v[174:177], v[206:209], v[24:27]
	v_mfma_f32_16x16x32_bf16 v[60:63], v[164:167], v[186:189], v[60:63]
	v_mfma_f32_16x16x32_bf16 v[56:59], v[178:181], v[186:189], v[56:59]
	v_mfma_f32_16x16x32_bf16 v[48:51], v[164:167], v[194:197], v[48:51]
	v_mfma_f32_16x16x32_bf16 v[44:47], v[178:181], v[194:197], v[44:47]
	v_mfma_f32_16x16x32_bf16 v[40:43], v[164:167], v[202:205], v[40:43]
	v_mfma_f32_16x16x32_bf16 v[36:39], v[178:181], v[202:205], v[36:39]
	v_mfma_f32_16x16x32_bf16 v[28:31], v[164:167], v[210:213], v[28:31]
	v_mfma_f32_16x16x32_bf16 v[24:27], v[178:181], v[210:213], v[24:27]
	s_barrier
	s_setprio 1
	ds_read_b128 v[134:137], v169 offset:32768
	ds_read_b128 v[138:141], v169 offset:33792
	ds_read_b128 v[142:145], v169 offset:34816
	ds_read_b128 v[146:149], v169 offset:35840
	ds_read_b128 v[160:163], v169 offset:49152
	ds_read_b128 v[164:167], v169 offset:50176
	ds_read_b128 v[174:177], v169 offset:51200
	ds_read_b128 v[178:181], v169 offset:52224
	s_add_u32 s26, s38, 0x100000
	s_addc_u32 s27, s39, 0
	s_mov_b32 m0, s89
	v_lshl_add_u64 v[220:221], s[26:27], 0, v[152:153]
	ds_read_b128 v[182:185], v168 offset:32768
	ds_read_b128 v[186:189], v168 offset:33792
	ds_read_b128 v[190:193], v168 offset:34816
	ds_read_b128 v[194:197], v168 offset:35840
	ds_read_b128 v[198:201], v168 offset:36864
	ds_read_b128 v[202:205], v168 offset:37888
	ds_read_b128 v[206:209], v168 offset:38912
	ds_read_b128 v[210:213], v168 offset:39936
	global_load_lds_dwordx4 v[220:221], off
	v_lshl_add_u64 v[220:221], s[26:27], 0, v[156:157]
	s_mov_b32 m0, s90
	s_nop 0
	global_load_lds_dwordx4 v[220:221], off
	s_waitcnt vmcnt(8)
	s_waitcnt lgkmcnt(0)
	s_setprio 0
	s_barrier
	v_mfma_f32_16x16x32_bf16 v[128:131], v[134:137], v[182:185], v[128:131]
	v_mfma_f32_16x16x32_bf16 v[124:127], v[142:145], v[182:185], v[124:127]
	v_mfma_f32_16x16x32_bf16 v[120:123], v[134:137], v[190:193], v[120:123]
	v_mfma_f32_16x16x32_bf16 v[116:119], v[142:145], v[190:193], v[116:119]
	v_mfma_f32_16x16x32_bf16 v[112:115], v[134:137], v[198:201], v[112:115]
	v_mfma_f32_16x16x32_bf16 v[108:111], v[142:145], v[198:201], v[108:111]
	v_mfma_f32_16x16x32_bf16 v[104:107], v[134:137], v[206:209], v[104:107]
	v_mfma_f32_16x16x32_bf16 v[100:103], v[142:145], v[206:209], v[100:103]
	v_mfma_f32_16x16x32_bf16 v[128:131], v[138:141], v[186:189], v[128:131]
	v_mfma_f32_16x16x32_bf16 v[124:127], v[146:149], v[186:189], v[124:127]
	v_mfma_f32_16x16x32_bf16 v[120:123], v[138:141], v[194:197], v[120:123]
	v_mfma_f32_16x16x32_bf16 v[116:119], v[146:149], v[194:197], v[116:119]
	v_mfma_f32_16x16x32_bf16 v[112:115], v[138:141], v[202:205], v[112:115]
	v_mfma_f32_16x16x32_bf16 v[108:111], v[146:149], v[202:205], v[108:111]
	v_mfma_f32_16x16x32_bf16 v[104:107], v[138:141], v[210:213], v[104:107]
	v_mfma_f32_16x16x32_bf16 v[100:103], v[146:149], v[210:213], v[100:103]
	v_mfma_f32_16x16x32_bf16 v[96:99], v[160:163], v[182:185], v[96:99]
	v_mfma_f32_16x16x32_bf16 v[92:95], v[174:177], v[182:185], v[92:95]
	v_mfma_f32_16x16x32_bf16 v[88:91], v[160:163], v[190:193], v[88:91]
	v_mfma_f32_16x16x32_bf16 v[84:87], v[174:177], v[190:193], v[84:87]
	v_mfma_f32_16x16x32_bf16 v[80:83], v[160:163], v[198:201], v[80:83]
	v_mfma_f32_16x16x32_bf16 v[76:79], v[174:177], v[198:201], v[76:79]
	v_mfma_f32_16x16x32_bf16 v[72:75], v[160:163], v[206:209], v[72:75]
	v_mfma_f32_16x16x32_bf16 v[68:71], v[174:177], v[206:209], v[68:71]
	v_mfma_f32_16x16x32_bf16 v[96:99], v[164:167], v[186:189], v[96:99]
	v_mfma_f32_16x16x32_bf16 v[92:95], v[178:181], v[186:189], v[92:95]
	v_mfma_f32_16x16x32_bf16 v[88:91], v[164:167], v[194:197], v[88:91]
	v_mfma_f32_16x16x32_bf16 v[84:87], v[178:181], v[194:197], v[84:87]
	v_mfma_f32_16x16x32_bf16 v[80:83], v[164:167], v[202:205], v[80:83]
	v_mfma_f32_16x16x32_bf16 v[76:79], v[178:181], v[202:205], v[76:79]
	v_mfma_f32_16x16x32_bf16 v[72:75], v[164:167], v[210:213], v[72:75]
	v_mfma_f32_16x16x32_bf16 v[68:71], v[178:181], v[210:213], v[68:71]
	s_barrier
; #define PG8_STAGE(bufoff, gbase, voff) do { _Pragma("unroll") for (int _i = 0; _i < 2; ++_i) \
;         __builtin_amdgcn_global_load_lds((const unsigned*)((const char*)(gbase) + (voff)[_i]), (LAS unsigned*)(lds + (bufoff) + ldsw + _i * 8192), 16, 0, 0); } while (0)
; #define PG8_LDA(dst, b, h) do { _Pragma("unroll") for (int m = 0; m < 4; ++m) _Pragma("unroll") for (int k = 0; k < 2; ++k) dst[m][k] = *(const LAS bf16x8*)(pA + PG8_SA(b, h) + m * 2048 + k * 1024); } while (0)
; #define PG8_LDB(dst, b, h) do { _Pragma("unroll") for (int n = 0; n < 2; ++n) _Pragma("unroll") for (int k = 0; k < 2; ++k) dst[n][k] = *(const LAS bf16x8*)(pB + (PG8_SB(b, h) - 4 * HTB) + n * 2048 + k * 1024); } while (0)
; #define PG8_MMA(ai, bj, At, Bt) do { __builtin_amdgcn_s_setprio(1); _Pragma("unroll") for (int m = 0; m < 4; ++m) _Pragma("unroll") for (int n = 0; n < 2; ++n) _Pragma("unroll") for (int k = 0; k < 2; ++k) \
;         acc[ai][bj][m][n] = __builtin_amdgcn_mfma_f32_16x16x32_bf16(Bt[n][k], At[m][k], acc[ai][bj][m][n], 0, 0, 0); __builtin_amdgcn_s_setprio(0); } while (0)
; #define PG8_WAIT_V(n) asm volatile("s_waitcnt vmcnt(" #n ")" ::: "memory")
; #define PG8_WAIT_L(n) asm volatile("s_waitcnt lgkmcnt(" #n ")" ::: "memory")
; #define PG8_BAR __builtin_amdgcn_s_barrier()
; #define PG8_SCHED __builtin_amdgcn_sched_barrier(0)
; template <class Desc, class Epi, bool ALIGN_EPI>
; __device__ __forceinline__ void gemm_phase(LAS unsigned char* lds, const Desc& D, const Epi& E, int G, int c) {
;     ...
;             PG8_LDB(B0, 1, 0); PG8_LDB(B1, 1, 1); PG8_SCHED; PG8_LDA(At, 1, 0); PG8_STAGE(PG8_SA(0, 1), a2 + hstepA, voffA);
;             PG8_WAIT_V(8); PG8_WAIT_L(0); PG8_BAR; PG8_MMA(0, 0, At, B0); PG8_MMA(0, 1, At, B1); PG8_BAR; PG8_SCHED;
;             PG8_LDA(At, 1, 1); PG8_STAGE(PG8_SB(1, 0), b3, voffB); PG8_STAGE(PG8_SB(1, 1), b3 + hstepB, voffB); PG8_STAGE(PG8_SA(1, 0), a3, voffA);
;             PG8_WAIT_V(8); PG8_WAIT_L(0); PG8_BAR; PG8_MMA(1, 0, At, B0); PG8_MMA(1, 1, At, B1); PG8_BAR; PG8_SCHED;
;         }
	s_setprio 1
	s_mov_b32 m0, s92
	v_lshl_add_u64 v[150:151], v[150:151], 0, s[76:77]
	s_add_u32 s26, s30, 0x100080
	ds_read_b128 v[182:185], v168 offset:49152
	ds_read_b128 v[186:189], v168 offset:50176
	ds_read_b128 v[190:193], v168 offset:51200
	ds_read_b128 v[194:197], v168 offset:52224
	ds_read_b128 v[198:201], v168 offset:53248
	ds_read_b128 v[202:205], v168 offset:54272
	ds_read_b128 v[206:209], v168 offset:55296
	ds_read_b128 v[210:213], v168 offset:56320
	global_load_lds_dwordx4 v[150:151], off
	v_lshl_add_u64 v[150:151], v[214:215], 0, s[76:77]
	s_mov_b32 m0, s93
	s_addc_u32 s27, s31, 0
	global_load_lds_dwordx4 v[150:151], off
	v_lshl_add_u64 v[150:151], s[26:27], 0, v[154:155]
	s_mov_b32 m0, s97
	s_nop 0
	global_load_lds_dwordx4 v[150:151], off
	v_lshl_add_u64 v[150:151], s[26:27], 0, v[158:159]
	s_mov_b32 m0, s82
	s_nop 0
	global_load_lds_dwordx4 v[150:151], off
	v_lshl_add_u64 v[150:151], v[216:217], 0, s[76:77]
	s_mov_b32 m0, s94
	s_nop 0
	global_load_lds_dwordx4 v[150:151], off
	v_lshl_add_u64 v[150:151], v[218:219], 0, s[76:77]
	s_mov_b32 m0, s95
	s_nop 0
	global_load_lds_dwordx4 v[150:151], off
	s_waitcnt vmcnt(8)
	s_waitcnt lgkmcnt(0)
	s_setprio 0
	s_barrier
	v_mfma_f32_16x16x32_bf16 v[64:67], v[134:137], v[182:185], v[64:67]
	v_mfma_f32_16x16x32_bf16 v[52:55], v[142:145], v[182:185], v[52:55]
	v_mfma_f32_16x16x32_bf16 v[32:35], v[134:137], v[190:193], v[32:35]
	v_mfma_f32_16x16x32_bf16 v[20:23], v[142:145], v[190:193], v[20:23]
	v_mfma_f32_16x16x32_bf16 v[16:19], v[134:137], v[198:201], v[16:19]
	v_mfma_f32_16x16x32_bf16 v[12:15], v[142:145], v[198:201], v[12:15]
	v_mfma_f32_16x16x32_bf16 v[8:11], v[134:137], v[206:209], v[8:11]
	v_mfma_f32_16x16x32_bf16 v[4:7], v[142:145], v[206:209], v[4:7]
	v_mfma_f32_16x16x32_bf16 v[64:67], v[138:141], v[186:189], v[64:67]
	v_mfma_f32_16x16x32_bf16 v[52:55], v[146:149], v[186:189], v[52:55]
	v_mfma_f32_16x16x32_bf16 v[32:35], v[138:141], v[194:197], v[32:35]
	v_mfma_f32_16x16x32_bf16 v[20:23], v[146:149], v[194:197], v[20:23]
	v_mfma_f32_16x16x32_bf16 v[16:19], v[138:141], v[202:205], v[16:19]
	v_mfma_f32_16x16x32_bf16 v[12:15], v[146:149], v[202:205], v[12:15]
	v_mfma_f32_16x16x32_bf16 v[8:11], v[138:141], v[210:213], v[8:11]
	v_mfma_f32_16x16x32_bf16 v[4:7], v[146:149], v[210:213], v[4:7]
	v_mfma_f32_16x16x32_bf16 v[60:63], v[160:163], v[182:185], v[60:63]
	v_mfma_f32_16x16x32_bf16 v[56:59], v[174:177], v[182:185], v[56:59]
	v_mfma_f32_16x16x32_bf16 v[48:51], v[160:163], v[190:193], v[48:51]
	v_mfma_f32_16x16x32_bf16 v[44:47], v[174:177], v[190:193], v[44:47]
	v_mfma_f32_16x16x32_bf16 v[40:43], v[160:163], v[198:201], v[40:43]
	v_mfma_f32_16x16x32_bf16 v[36:39], v[174:177], v[198:201], v[36:39]
	v_mfma_f32_16x16x32_bf16 v[28:31], v[160:163], v[206:209], v[28:31]
	v_mfma_f32_16x16x32_bf16 v[24:27], v[174:177], v[206:209], v[24:27]
	v_mfma_f32_16x16x32_bf16 v[60:63], v[164:167], v[186:189], v[60:63]
	v_mfma_f32_16x16x32_bf16 v[56:59], v[178:181], v[186:189], v[56:59]
	v_mfma_f32_16x16x32_bf16 v[48:51], v[164:167], v[194:197], v[48:51]
	v_mfma_f32_16x16x32_bf16 v[44:47], v[178:181], v[194:197], v[44:47]
	v_mfma_f32_16x16x32_bf16 v[40:43], v[164:167], v[202:205], v[40:43]
	v_mfma_f32_16x16x32_bf16 v[36:39], v[178:181], v[202:205], v[36:39]
	v_mfma_f32_16x16x32_bf16 v[28:31], v[164:167], v[210:213], v[28:31]
	v_mfma_f32_16x16x32_bf16 v[24:27], v[178:181], v[210:213], v[24:27]
	s_barrier
	s_setprio 1
	s_cmp_ge_u32 s14, s3
	s_mov_b32 s17, s14
	s_cbranch_scc1 .LBB0_183

; #define PG8_STAGE(bufoff, gbase, voff) do { _Pragma("unroll") for (int _i = 0; _i < 2; ++_i) \
;         __builtin_amdgcn_global_load_lds((const unsigned*)((const char*)(gbase) + (voff)[_i]), (LAS unsigned*)(lds + (bufoff) + ldsw + _i * 8192), 16, 0, 0); } while (0)
; #define PG8_LDA(dst, b, h) do { _Pragma("unroll") for (int m = 0; m < 4; ++m) _Pragma("unroll") for (int k = 0; k < 2; ++k) dst[m][k] = *(const LAS bf16x8*)(pA + PG8_SA(b, h) + m * 2048 + k * 1024); } while (0)
; #define PG8_LDB(dst, b, h) do { _Pragma("unroll") for (int n = 0; n < 2; ++n) _Pragma("unroll") for (int k = 0; k < 2; ++k) dst[n][k] = *(const LAS bf16x8*)(pB + (PG8_SB(b, h) - 4 * HTB) + n * 2048 + k * 1024); } while (0)
; #define PG8_MMA(ai, bj, At, Bt) do { __builtin_amdgcn_s_setprio(1); _Pragma("unroll") for (int m = 0; m < 4; ++m) _Pragma("unroll") for (int n = 0; n < 2; ++n) _Pragma("unroll") for (int k = 0; k < 2; ++k) \
;         acc[ai][bj][m][n] = __builtin_amdgcn_mfma_f32_16x16x32_bf16(Bt[n][k], At[m][k], acc[ai][bj][m][n], 0, 0, 0); __builtin_amdgcn_s_setprio(0); } while (0)
; #define PG8_WAIT_V(n) asm volatile("s_waitcnt vmcnt(" #n ")" ::: "memory")
; #define PG8_BAR __builtin_amdgcn_s_barrier()
; template <class Desc, class Epi, bool ALIGN_EPI>
; __device__ __forceinline__ void gemm_phase(LAS unsigned char* lds, const Desc& D, const Epi& E, int G, int c) {
;     ...
;             PG8_LDB(B0, 0, 0); PG8_LDB(B1, 0, 1); PG8_SCHED; PG8_LDA(At, 0, 0); PG8_STAGE(PG8_SA(1, 1), a1 + hstepA, voffA);
;             PG8_WAIT_V(8); PG8_WAIT_L(0); PG8_BAR; PG8_MMA(0, 0, At, B0); PG8_MMA(0, 1, At, B1); PG8_BAR; PG8_SCHED;
;             PG8_LDA(At, 0, 1); PG8_STAGE(PG8_SB(0, 0), b2, voffB); PG8_STAGE(PG8_SB(0, 1), b2 + hstepB, voffB); PG8_STAGE(PG8_SA(0, 0), a2, voffA);
;             PG8_WAIT_V(8); PG8_WAIT_L(0); PG8_BAR; PG8_MMA(1, 0, At, B0); PG8_MMA(1, 1, At, B1); PG8_BAR; PG8_SCHED;
;             PG8_LDB(B0, 1, 0); PG8_LDB(B1, 1, 1); PG8_SCHED; PG8_LDA(At, 1, 0); PG8_STAGE(PG8_SA(0, 1), a2 + hstepA, voffA);
;             PG8_WAIT_V(8); PG8_WAIT_L(0); PG8_BAR; PG8_MMA(0, 0, At, B0); PG8_MMA(0, 1, At, B1); PG8_BAR; PG8_SCHED;
;             PG8_LDA(At, 1, 1); PG8_STAGE(PG8_SB(1, 0), b3, voffB); PG8_STAGE(PG8_SB(1, 1), b3 + hstepB, voffB); PG8_STAGE(PG8_SA(1, 0), a3, voffA);
;             PG8_WAIT_V(8); PG8_WAIT_L(0); PG8_BAR; PG8_MMA(1, 0, At, B0); PG8_MMA(1, 1, At, B1); PG8_BAR; PG8_SCHED;
.LBB0_603:
	ds_read_b128 v[144:147], v149
	ds_read_b128 v[152:155], v149 offset:1024
	ds_read_b128 v[156:159], v149 offset:2048
	ds_read_b128 v[160:163], v149 offset:3072
	ds_read_b128 v[164:167], v149 offset:16384
	ds_read_b128 v[168:171], v149 offset:17408
	ds_read_b128 v[172:175], v149 offset:18432
	ds_read_b128 v[176:179], v149 offset:19456
	s_add_u32 s16, s12, 0xfff80080
	s_addc_u32 s17, s13, -1
	s_cmp_eq_u32 s46, 4
	s_cselect_b32 s19, s9, s17
	s_cselect_b32 s18, s8, s16
	s_cselect_b32 s17, s11, s45
	s_cselect_b32 s16, s10, s7
	v_lshl_add_u64 v[212:213], s[12:13], 0, v[140:141]
	s_add_i32 m0, s20, 0xc000
	ds_read_b128 v[180:183], v148
	ds_read_b128 v[184:187], v148 offset:1024
	ds_read_b128 v[188:191], v148 offset:2048
	ds_read_b128 v[192:195], v148 offset:3072
	ds_read_b128 v[196:199], v148 offset:4096
	ds_read_b128 v[200:203], v148 offset:5120
	ds_read_b128 v[204:207], v148 offset:6144
	ds_read_b128 v[208:211], v148 offset:7168
	global_load_lds_dwordx4 v[212:213], off
	v_lshl_add_u64 v[212:213], s[12:13], 0, v[142:143]
	s_add_i32 m0, s20, 0xe000
	s_nop 0
	global_load_lds_dwordx4 v[212:213], off
	s_waitcnt vmcnt(8)
	s_waitcnt lgkmcnt(0)
	s_setprio 0
	s_barrier
	v_mfma_f32_16x16x32_bf16 v[128:131], v[144:147], v[180:183], v[128:131]
	v_mfma_f32_16x16x32_bf16 v[124:127], v[156:159], v[180:183], v[124:127]
	v_mfma_f32_16x16x32_bf16 v[116:119], v[144:147], v[188:191], v[116:119]
	v_mfma_f32_16x16x32_bf16 v[108:111], v[156:159], v[188:191], v[108:111]
	v_mfma_f32_16x16x32_bf16 v[100:103], v[144:147], v[196:199], v[100:103]
	v_mfma_f32_16x16x32_bf16 v[92:95], v[156:159], v[196:199], v[92:95]
	v_mfma_f32_16x16x32_bf16 v[84:87], v[144:147], v[204:207], v[84:87]
	v_mfma_f32_16x16x32_bf16 v[76:79], v[156:159], v[204:207], v[76:79]
	v_mfma_f32_16x16x32_bf16 v[128:131], v[152:155], v[184:187], v[128:131]
	v_mfma_f32_16x16x32_bf16 v[124:127], v[160:163], v[184:187], v[124:127]
	v_mfma_f32_16x16x32_bf16 v[116:119], v[152:155], v[192:195], v[116:119]
	v_mfma_f32_16x16x32_bf16 v[108:111], v[160:163], v[192:195], v[108:111]
	v_mfma_f32_16x16x32_bf16 v[100:103], v[152:155], v[200:203], v[100:103]
	v_mfma_f32_16x16x32_bf16 v[92:95], v[160:163], v[200:203], v[92:95]
	v_mfma_f32_16x16x32_bf16 v[84:87], v[152:155], v[208:211], v[84:87]
	v_mfma_f32_16x16x32_bf16 v[76:79], v[160:163], v[208:211], v[76:79]
	v_mfma_f32_16x16x32_bf16 v[120:123], v[164:167], v[180:183], v[120:123]
	v_mfma_f32_16x16x32_bf16 v[112:115], v[172:175], v[180:183], v[112:115]
	v_mfma_f32_16x16x32_bf16 v[104:107], v[164:167], v[188:191], v[104:107]
	v_mfma_f32_16x16x32_bf16 v[96:99], v[172:175], v[188:191], v[96:99]
	v_mfma_f32_16x16x32_bf16 v[88:91], v[164:167], v[196:199], v[88:91]
	v_mfma_f32_16x16x32_bf16 v[80:83], v[172:175], v[196:199], v[80:83]
	v_mfma_f32_16x16x32_bf16 v[72:75], v[164:167], v[204:207], v[72:75]
	v_mfma_f32_16x16x32_bf16 v[68:71], v[172:175], v[204:207], v[68:71]
	v_mfma_f32_16x16x32_bf16 v[120:123], v[168:171], v[184:187], v[120:123]
	v_mfma_f32_16x16x32_bf16 v[112:115], v[176:179], v[184:187], v[112:115]
	v_mfma_f32_16x16x32_bf16 v[104:107], v[168:171], v[192:195], v[104:107]
	v_mfma_f32_16x16x32_bf16 v[96:99], v[176:179], v[192:195], v[96:99]
	v_mfma_f32_16x16x32_bf16 v[88:91], v[168:171], v[200:203], v[88:91]
	v_mfma_f32_16x16x32_bf16 v[80:83], v[176:179], v[200:203], v[80:83]
	v_mfma_f32_16x16x32_bf16 v[72:75], v[168:171], v[208:211], v[72:75]
	v_mfma_f32_16x16x32_bf16 v[68:71], v[176:179], v[208:211], v[68:71]
	s_barrier
	s_setprio 1
	s_mov_b32 m0, s21
	v_lshl_add_u64 v[212:213], s[16:17], 0, v[136:137]
	s_add_u32 s48, s16, 0x20000
	ds_read_b128 v[180:183], v148 offset:16384
	ds_read_b128 v[184:187], v148 offset:17408
	ds_read_b128 v[188:191], v148 offset:18432
	ds_read_b128 v[192:195], v148 offset:19456
	ds_read_b128 v[196:199], v148 offset:20480
	ds_read_b128 v[200:203], v148 offset:21504
	ds_read_b128 v[204:207], v148 offset:22528
	ds_read_b128 v[208:211], v148 offset:23552
	global_load_lds_dwordx4 v[212:213], off
	v_lshl_add_u64 v[214:215], s[16:17], 0, v[132:133]
	s_mov_b32 m0, s23
	s_addc_u32 s49, s17, 0
	global_load_lds_dwordx4 v[214:215], off
	v_lshl_add_u64 v[216:217], s[48:49], 0, v[136:137]
	s_mov_b32 m0, s24
	v_lshl_add_u64 v[218:219], s[18:19], 0, v[134:135]
	global_load_lds_dwordx4 v[216:217], off
	v_lshl_add_u64 v[216:217], s[48:49], 0, v[132:133]
	s_mov_b32 m0, s25
	s_nop 0
	global_load_lds_dwordx4 v[216:217], off
	v_lshl_add_u64 v[216:217], s[18:19], 0, v[138:139]
	s_mov_b32 m0, s20
	s_nop 0
	global_load_lds_dwordx4 v[216:217], off
	s_mov_b32 m0, s26
	s_nop 0
	global_load_lds_dwordx4 v[218:219], off
	s_waitcnt vmcnt(8)
	s_waitcnt lgkmcnt(0)
	s_setprio 0
	s_barrier
; #define PG8_STAGE(bufoff, gbase, voff) do { _Pragma("unroll") for (int _i = 0; _i < 2; ++_i) \
;         __builtin_amdgcn_global_load_lds((const unsigned*)((const char*)(gbase) + (voff)[_i]), (LAS unsigned*)(lds + (bufoff) + ldsw + _i * 8192), 16, 0, 0); } while (0)
; #define PG8_LDA(dst, b, h) do { _Pragma("unroll") for (int m = 0; m < 4; ++m) _Pragma("unroll") for (int k = 0; k < 2; ++k) dst[m][k] = *(const LAS bf16x8*)(pA + PG8_SA(b, h) + m * 2048 + k * 1024); } while (0)
; #define PG8_LDB(dst, b, h) do { _Pragma("unroll") for (int n = 0; n < 2; ++n) _Pragma("unroll") for (int k = 0; k < 2; ++k) dst[n][k] = *(const LAS bf16x8*)(pB + (PG8_SB(b, h) - 4 * HTB) + n * 2048 + k * 1024); } while (0)
; #define PG8_MMA(ai, bj, At, Bt) do { __builtin_amdgcn_s_setprio(1); _Pragma("unroll") for (int m = 0; m < 4; ++m) _Pragma("unroll") for (int n = 0; n < 2; ++n) _Pragma("unroll") for (int k = 0; k < 2; ++k) \
;         acc[ai][bj][m][n] = __builtin_amdgcn_mfma_f32_16x16x32_bf16(Bt[n][k], At[m][k], acc[ai][bj][m][n], 0, 0, 0); __builtin_amdgcn_s_setprio(0); } while (0)
; #define PG8_WAIT_V(n) asm volatile("s_waitcnt vmcnt(" #n ")" ::: "memory")
; #define PG8_WAIT_L(n) asm volatile("s_waitcnt lgkmcnt(" #n ")" ::: "memory")
; #define PG8_BAR __builtin_amdgcn_s_barrier()
; #define PG8_SCHED __builtin_amdgcn_sched_barrier(0)
; template <class Desc, class Epi, bool ALIGN_EPI>
; __device__ __forceinline__ void gemm_phase(LAS unsigned char* lds, const Desc& D, const Epi& E, int G, int c) {
;     ...
;             PG8_LDA(At, 0, 1); PG8_STAGE(PG8_SB(0, 0), b2, voffB); PG8_STAGE(PG8_SB(0, 1), b2 + hstepB, voffB); PG8_STAGE(PG8_SA(0, 0), a2, voffA);
;             PG8_WAIT_V(8); PG8_WAIT_L(0); PG8_BAR; PG8_MMA(1, 0, At, B0); PG8_MMA(1, 1, At, B1); PG8_BAR; PG8_SCHED;
;             PG8_LDB(B0, 1, 0); PG8_LDB(B1, 1, 1); PG8_SCHED; PG8_LDA(At, 1, 0); PG8_STAGE(PG8_SA(0, 1), a2 + hstepA, voffA);
;             PG8_WAIT_V(8); PG8_WAIT_L(0); PG8_BAR; PG8_MMA(0, 0, At, B0); PG8_MMA(0, 1, At, B1); PG8_BAR; PG8_SCHED;
	v_mfma_f32_16x16x32_bf16 v[64:67], v[144:147], v[180:183], v[64:67]
	v_mfma_f32_16x16x32_bf16 v[60:63], v[156:159], v[180:183], v[60:63]
	v_mfma_f32_16x16x32_bf16 v[52:55], v[144:147], v[188:191], v[52:55]
	v_mfma_f32_16x16x32_bf16 v[44:47], v[156:159], v[188:191], v[44:47]
	v_mfma_f32_16x16x32_bf16 v[36:39], v[144:147], v[196:199], v[36:39]
	v_mfma_f32_16x16x32_bf16 v[28:31], v[156:159], v[196:199], v[28:31]
	v_mfma_f32_16x16x32_bf16 v[20:23], v[144:147], v[204:207], v[20:23]
	v_mfma_f32_16x16x32_bf16 v[12:15], v[156:159], v[204:207], v[12:15]
	v_mfma_f32_16x16x32_bf16 v[64:67], v[152:155], v[184:187], v[64:67]
	v_mfma_f32_16x16x32_bf16 v[60:63], v[160:163], v[184:187], v[60:63]
	v_mfma_f32_16x16x32_bf16 v[52:55], v[152:155], v[192:195], v[52:55]
	v_mfma_f32_16x16x32_bf16 v[44:47], v[160:163], v[192:195], v[44:47]
	v_mfma_f32_16x16x32_bf16 v[36:39], v[152:155], v[200:203], v[36:39]
	v_mfma_f32_16x16x32_bf16 v[28:31], v[160:163], v[200:203], v[28:31]
	v_mfma_f32_16x16x32_bf16 v[20:23], v[152:155], v[208:211], v[20:23]
	v_mfma_f32_16x16x32_bf16 v[12:15], v[160:163], v[208:211], v[12:15]
	v_mfma_f32_16x16x32_bf16 v[56:59], v[164:167], v[180:183], v[56:59]
	v_mfma_f32_16x16x32_bf16 v[48:51], v[172:175], v[180:183], v[48:51]
	v_mfma_f32_16x16x32_bf16 v[40:43], v[164:167], v[188:191], v[40:43]
	v_mfma_f32_16x16x32_bf16 v[32:35], v[172:175], v[188:191], v[32:35]
	v_mfma_f32_16x16x32_bf16 v[24:27], v[164:167], v[196:199], v[24:27]
	v_mfma_f32_16x16x32_bf16 v[16:19], v[172:175], v[196:199], v[16:19]
	v_mfma_f32_16x16x32_bf16 v[8:11], v[164:167], v[204:207], v[8:11]
	v_mfma_f32_16x16x32_bf16 v[4:7], v[172:175], v[204:207], v[4:7]
	v_mfma_f32_16x16x32_bf16 v[56:59], v[168:171], v[184:187], v[56:59]
	v_mfma_f32_16x16x32_bf16 v[48:51], v[176:179], v[184:187], v[48:51]
	v_mfma_f32_16x16x32_bf16 v[40:43], v[168:171], v[192:195], v[40:43]
	v_mfma_f32_16x16x32_bf16 v[32:35], v[176:179], v[192:195], v[32:35]
	v_mfma_f32_16x16x32_bf16 v[24:27], v[168:171], v[200:203], v[24:27]
	v_mfma_f32_16x16x32_bf16 v[16:19], v[176:179], v[200:203], v[16:19]
	v_mfma_f32_16x16x32_bf16 v[8:11], v[168:171], v[208:211], v[8:11]
	v_mfma_f32_16x16x32_bf16 v[4:7], v[176:179], v[208:211], v[4:7]
	s_barrier
	s_setprio 1
	ds_read_b128 v[144:147], v149 offset:32768
	ds_read_b128 v[152:155], v149 offset:33792
	ds_read_b128 v[156:159], v149 offset:34816
	ds_read_b128 v[160:163], v149 offset:35840
	ds_read_b128 v[164:167], v149 offset:49152
	ds_read_b128 v[168:171], v149 offset:50176
	ds_read_b128 v[172:175], v149 offset:51200
	ds_read_b128 v[176:179], v149 offset:52224
	s_add_u32 s18, s18, 0x80000
	s_addc_u32 s19, s19, 0
	s_mov_b32 m0, s27
	v_lshl_add_u64 v[220:221], s[18:19], 0, v[138:139]
	ds_read_b128 v[180:183], v148 offset:32768
	ds_read_b128 v[184:187], v148 offset:33792
	ds_read_b128 v[188:191], v148 offset:34816
	ds_read_b128 v[192:195], v148 offset:35840
	ds_read_b128 v[196:199], v148 offset:36864
	ds_read_b128 v[200:203], v148 offset:37888
	ds_read_b128 v[204:207], v148 offset:38912
	ds_read_b128 v[208:211], v148 offset:39936
	global_load_lds_dwordx4 v[220:221], off
	v_lshl_add_u64 v[220:221], s[18:19], 0, v[134:135]
	s_mov_b32 m0, s30
	s_nop 0
	global_load_lds_dwordx4 v[220:221], off
	s_waitcnt vmcnt(8)
	s_waitcnt lgkmcnt(0)
	s_setprio 0
	s_barrier
	v_mfma_f32_16x16x32_bf16 v[128:131], v[144:147], v[180:183], v[128:131]
	v_mfma_f32_16x16x32_bf16 v[124:127], v[156:159], v[180:183], v[124:127]
	v_mfma_f32_16x16x32_bf16 v[116:119], v[144:147], v[188:191], v[116:119]
	v_mfma_f32_16x16x32_bf16 v[108:111], v[156:159], v[188:191], v[108:111]
	v_mfma_f32_16x16x32_bf16 v[100:103], v[144:147], v[196:199], v[100:103]
	v_mfma_f32_16x16x32_bf16 v[92:95], v[156:159], v[196:199], v[92:95]
	v_mfma_f32_16x16x32_bf16 v[84:87], v[144:147], v[204:207], v[84:87]
	v_mfma_f32_16x16x32_bf16 v[76:79], v[156:159], v[204:207], v[76:79]
	v_mfma_f32_16x16x32_bf16 v[128:131], v[152:155], v[184:187], v[128:131]
	v_mfma_f32_16x16x32_bf16 v[124:127], v[160:163], v[184:187], v[124:127]
	v_mfma_f32_16x16x32_bf16 v[116:119], v[152:155], v[192:195], v[116:119]
	v_mfma_f32_16x16x32_bf16 v[108:111], v[160:163], v[192:195], v[108:111]
	v_mfma_f32_16x16x32_bf16 v[100:103], v[152:155], v[200:203], v[100:103]
	v_mfma_f32_16x16x32_bf16 v[92:95], v[160:163], v[200:203], v[92:95]
	v_mfma_f32_16x16x32_bf16 v[84:87], v[152:155], v[208:211], v[84:87]
	v_mfma_f32_16x16x32_bf16 v[76:79], v[160:163], v[208:211], v[76:79]
	v_mfma_f32_16x16x32_bf16 v[120:123], v[164:167], v[180:183], v[120:123]
	v_mfma_f32_16x16x32_bf16 v[112:115], v[172:175], v[180:183], v[112:115]
	v_mfma_f32_16x16x32_bf16 v[104:107], v[164:167], v[188:191], v[104:107]
	v_mfma_f32_16x16x32_bf16 v[96:99], v[172:175], v[188:191], v[96:99]
	v_mfma_f32_16x16x32_bf16 v[88:91], v[164:167], v[196:199], v[88:91]
	v_mfma_f32_16x16x32_bf16 v[80:83], v[172:175], v[196:199], v[80:83]
	v_mfma_f32_16x16x32_bf16 v[72:75], v[164:167], v[204:207], v[72:75]
	v_mfma_f32_16x16x32_bf16 v[68:71], v[172:175], v[204:207], v[68:71]
	v_mfma_f32_16x16x32_bf16 v[120:123], v[168:171], v[184:187], v[120:123]
	v_mfma_f32_16x16x32_bf16 v[112:115], v[176:179], v[184:187], v[112:115]
	v_mfma_f32_16x16x32_bf16 v[104:107], v[168:171], v[192:195], v[104:107]
	v_mfma_f32_16x16x32_bf16 v[96:99], v[176:179], v[192:195], v[96:99]
	v_mfma_f32_16x16x32_bf16 v[88:91], v[168:171], v[200:203], v[88:91]
	v_mfma_f32_16x16x32_bf16 v[80:83], v[176:179], v[200:203], v[80:83]
	v_mfma_f32_16x16x32_bf16 v[72:75], v[168:171], v[208:211], v[72:75]
	v_mfma_f32_16x16x32_bf16 v[68:71], v[176:179], v[208:211], v[68:71]
	s_barrier
; #define PG8_STAGE(bufoff, gbase, voff) do { _Pragma("unroll") for (int _i = 0; _i < 2; ++_i) \
;         __builtin_amdgcn_global_load_lds((const unsigned*)((const char*)(gbase) + (voff)[_i]), (LAS unsigned*)(lds + (bufoff) + ldsw + _i * 8192), 16, 0, 0); } while (0)
; #define PG8_LDA(dst, b, h) do { _Pragma("unroll") for (int m = 0; m < 4; ++m) _Pragma("unroll") for (int k = 0; k < 2; ++k) dst[m][k] = *(const LAS bf16x8*)(pA + PG8_SA(b, h) + m * 2048 + k * 1024); } while (0)
; #define PG8_MMA(ai, bj, At, Bt) do { __builtin_amdgcn_s_setprio(1); _Pragma("unroll") for (int m = 0; m < 4; ++m) _Pragma("unroll") for (int n = 0; n < 2; ++n) _Pragma("unroll") for (int k = 0; k < 2; ++k) \
;         acc[ai][bj][m][n] = __builtin_amdgcn_mfma_f32_16x16x32_bf16(Bt[n][k], At[m][k], acc[ai][bj][m][n], 0, 0, 0); __builtin_amdgcn_s_setprio(0); } while (0)
; #define PG8_WAIT_V(n) asm volatile("s_waitcnt vmcnt(" #n ")" ::: "memory")
; #define PG8_WAIT_L(n) asm volatile("s_waitcnt lgkmcnt(" #n ")" ::: "memory")
; #define PG8_BAR __builtin_amdgcn_s_barrier()
; #define PG8_SCHED __builtin_amdgcn_sched_barrier(0)
; template <class Desc, class Epi, bool ALIGN_EPI>
; __device__ __forceinline__ void gemm_phase(LAS unsigned char* lds, const Desc& D, const Epi& E, int G, int c) {
;     ...
;             PG8_LDA(At, 1, 1); PG8_STAGE(PG8_SB(1, 0), b3, voffB); PG8_STAGE(PG8_SB(1, 1), b3 + hstepB, voffB); PG8_STAGE(PG8_SA(1, 0), a3, voffA);
;             PG8_WAIT_V(8); PG8_WAIT_L(0); PG8_BAR; PG8_MMA(1, 0, At, B0); PG8_MMA(1, 1, At, B1); PG8_BAR; PG8_SCHED;
;         }
	s_setprio 1
	s_mov_b32 m0, s31
	v_lshl_add_u64 v[212:213], v[212:213], 0, s[76:77]
	s_add_u32 s16, s16, 0x20080
	ds_read_b128 v[180:183], v148 offset:49152
	ds_read_b128 v[184:187], v148 offset:50176
	ds_read_b128 v[188:191], v148 offset:51200
	ds_read_b128 v[192:195], v148 offset:52224
	ds_read_b128 v[196:199], v148 offset:53248
	ds_read_b128 v[200:203], v148 offset:54272
	ds_read_b128 v[204:207], v148 offset:55296
	ds_read_b128 v[208:211], v148 offset:56320
	global_load_lds_dwordx4 v[212:213], off
	v_lshl_add_u64 v[212:213], v[214:215], 0, s[76:77]
	s_mov_b32 m0, s33
	s_addc_u32 s17, s17, 0
	global_load_lds_dwordx4 v[212:213], off
	v_lshl_add_u64 v[212:213], s[16:17], 0, v[136:137]
	s_mov_b32 m0, s38
	s_nop 0
	global_load_lds_dwordx4 v[212:213], off
	v_lshl_add_u64 v[212:213], s[16:17], 0, v[132:133]
	s_mov_b32 m0, s39
	s_nop 0
	global_load_lds_dwordx4 v[212:213], off
	v_lshl_add_u64 v[212:213], v[216:217], 0, s[76:77]
	s_mov_b32 m0, s34
	s_nop 0
	global_load_lds_dwordx4 v[212:213], off
	v_lshl_add_u64 v[212:213], v[218:219], 0, s[76:77]
	s_mov_b32 m0, s35
	s_nop 0
	global_load_lds_dwordx4 v[212:213], off
	s_waitcnt vmcnt(8)
	s_waitcnt lgkmcnt(0)
	s_setprio 0
	s_barrier
	v_mfma_f32_16x16x32_bf16 v[64:67], v[144:147], v[180:183], v[64:67]
	v_mfma_f32_16x16x32_bf16 v[60:63], v[156:159], v[180:183], v[60:63]
	v_mfma_f32_16x16x32_bf16 v[52:55], v[144:147], v[188:191], v[52:55]
	v_mfma_f32_16x16x32_bf16 v[44:47], v[156:159], v[188:191], v[44:47]
	v_mfma_f32_16x16x32_bf16 v[36:39], v[144:147], v[196:199], v[36:39]
	v_mfma_f32_16x16x32_bf16 v[28:31], v[156:159], v[196:199], v[28:31]
	v_mfma_f32_16x16x32_bf16 v[20:23], v[144:147], v[204:207], v[20:23]
	v_mfma_f32_16x16x32_bf16 v[12:15], v[156:159], v[204:207], v[12:15]
	v_mfma_f32_16x16x32_bf16 v[64:67], v[152:155], v[184:187], v[64:67]
	v_mfma_f32_16x16x32_bf16 v[60:63], v[160:163], v[184:187], v[60:63]
	v_mfma_f32_16x16x32_bf16 v[52:55], v[152:155], v[192:195], v[52:55]
	v_mfma_f32_16x16x32_bf16 v[44:47], v[160:163], v[192:195], v[44:47]
	v_mfma_f32_16x16x32_bf16 v[36:39], v[152:155], v[200:203], v[36:39]
	v_mfma_f32_16x16x32_bf16 v[28:31], v[160:163], v[200:203], v[28:31]
	v_mfma_f32_16x16x32_bf16 v[20:23], v[152:155], v[208:211], v[20:23]
	v_mfma_f32_16x16x32_bf16 v[12:15], v[160:163], v[208:211], v[12:15]
	v_mfma_f32_16x16x32_bf16 v[56:59], v[164:167], v[180:183], v[56:59]
	v_mfma_f32_16x16x32_bf16 v[48:51], v[172:175], v[180:183], v[48:51]
	v_mfma_f32_16x16x32_bf16 v[40:43], v[164:167], v[188:191], v[40:43]
	v_mfma_f32_16x16x32_bf16 v[32:35], v[172:175], v[188:191], v[32:35]
	v_mfma_f32_16x16x32_bf16 v[24:27], v[164:167], v[196:199], v[24:27]
	v_mfma_f32_16x16x32_bf16 v[16:19], v[172:175], v[196:199], v[16:19]
	v_mfma_f32_16x16x32_bf16 v[8:11], v[164:167], v[204:207], v[8:11]
	v_mfma_f32_16x16x32_bf16 v[4:7], v[172:175], v[204:207], v[4:7]
	v_mfma_f32_16x16x32_bf16 v[56:59], v[168:171], v[184:187], v[56:59]
	v_mfma_f32_16x16x32_bf16 v[48:51], v[176:179], v[184:187], v[48:51]
	v_mfma_f32_16x16x32_bf16 v[40:43], v[168:171], v[192:195], v[40:43]
	v_mfma_f32_16x16x32_bf16 v[32:35], v[176:179], v[192:195], v[32:35]
	v_mfma_f32_16x16x32_bf16 v[24:27], v[168:171], v[200:203], v[24:27]
	v_mfma_f32_16x16x32_bf16 v[16:19], v[176:179], v[200:203], v[16:19]
	v_mfma_f32_16x16x32_bf16 v[8:11], v[168:171], v[208:211], v[8:11]
	v_mfma_f32_16x16x32_bf16 v[4:7], v[176:179], v[208:211], v[4:7]
	s_barrier
	s_setprio 1
	s_add_i32 s46, s46, 2
	s_add_u32 s12, s12, 0x100
	s_addc_u32 s13, s13, 0
	s_add_u32 s7, s7, 0x100
	s_addc_u32 s45, s45, 0
	s_cmp_gt_u32 s46, 5
	s_cbranch_scc0 .LBB0_603
	v_readlane_b32 s46, v255, 36
	s_and_b64 vcc, exec, s[4:5]
	v_readlane_b32 s47, v255, 37
	s_cbranch_vccz .LBB0_606
	s_barrier

; #define PG8_STAGE(bufoff, gbase, voff) do { _Pragma("unroll") for (int _i = 0; _i < 2; ++_i) \
;         __builtin_amdgcn_global_load_lds((const unsigned*)((const char*)(gbase) + (voff)[_i]), (LAS unsigned*)(lds + (bufoff) + ldsw + _i * 8192), 16, 0, 0); } while (0)
; #define PG8_LDA(dst, b, h) do { _Pragma("unroll") for (int m = 0; m < 4; ++m) _Pragma("unroll") for (int k = 0; k < 2; ++k) dst[m][k] = *(const LAS bf16x8*)(pA + PG8_SA(b, h) + m * 2048 + k * 1024); } while (0)
; #define PG8_LDB(dst, b, h) do { _Pragma("unroll") for (int n = 0; n < 2; ++n) _Pragma("unroll") for (int k = 0; k < 2; ++k) dst[n][k] = *(const LAS bf16x8*)(pB + (PG8_SB(b, h) - 4 * HTB) + n * 2048 + k * 1024); } while (0)
; #define PG8_MMA(ai, bj, At, Bt) do { __builtin_amdgcn_s_setprio(1); _Pragma("unroll") for (int m = 0; m < 4; ++m) _Pragma("unroll") for (int n = 0; n < 2; ++n) _Pragma("unroll") for (int k = 0; k < 2; ++k) \
;         acc[ai][bj][m][n] = __builtin_amdgcn_mfma_f32_16x16x32_bf16(Bt[n][k], At[m][k], acc[ai][bj][m][n], 0, 0, 0); __builtin_amdgcn_s_setprio(0); } while (0)
; #define PG8_WAIT_V(n) asm volatile("s_waitcnt vmcnt(" #n ")" ::: "memory")
; #define PG8_BAR __builtin_amdgcn_s_barrier()
; template <class Desc, class Epi, bool ALIGN_EPI>
; __device__ __forceinline__ void gemm_phase(LAS unsigned char* lds, const Desc& D, const Epi& E, int G, int c) {
;     ...
;             PG8_LDB(B0, 0, 0); PG8_LDB(B1, 0, 1); PG8_SCHED; PG8_LDA(At, 0, 0); PG8_STAGE(PG8_SA(1, 1), a1 + hstepA, voffA);
;             PG8_WAIT_V(8); PG8_WAIT_L(0); PG8_BAR; PG8_MMA(0, 0, At, B0); PG8_MMA(0, 1, At, B1); PG8_BAR; PG8_SCHED;
;             PG8_LDA(At, 0, 1); PG8_STAGE(PG8_SB(0, 0), b2, voffB); PG8_STAGE(PG8_SB(0, 1), b2 + hstepB, voffB); PG8_STAGE(PG8_SA(0, 0), a2, voffA);
;             PG8_WAIT_V(8); PG8_WAIT_L(0); PG8_BAR; PG8_MMA(1, 0, At, B0); PG8_MMA(1, 1, At, B1); PG8_BAR; PG8_SCHED;
;             PG8_LDB(B0, 1, 0); PG8_LDB(B1, 1, 1); PG8_SCHED; PG8_LDA(At, 1, 0); PG8_STAGE(PG8_SA(0, 1), a2 + hstepA, voffA);
;             PG8_WAIT_V(8); PG8_WAIT_L(0); PG8_BAR; PG8_MMA(0, 0, At, B0); PG8_MMA(0, 1, At, B1); PG8_BAR; PG8_SCHED;
;             PG8_LDA(At, 1, 1); PG8_STAGE(PG8_SB(1, 0), b3, voffB); PG8_STAGE(PG8_SB(1, 1), b3 + hstepB, voffB); PG8_STAGE(PG8_SA(1, 0), a3, voffA);
;             PG8_WAIT_V(8); PG8_WAIT_L(0); PG8_BAR; PG8_MMA(1, 0, At, B0); PG8_MMA(1, 1, At, B1); PG8_BAR; PG8_SCHED;
.LBB0_1164:
	s_waitcnt lgkmcnt(0)
	ds_read_b128 v[132:135], v229
	ds_read_b128 v[136:139], v229 offset:1024
	ds_read_b128 v[140:143], v229 offset:2048
	ds_read_b128 v[144:147], v229 offset:3072
	ds_read_b128 v[148:151], v229 offset:16384
	ds_read_b128 v[152:155], v229 offset:17408
	ds_read_b128 v[156:159], v229 offset:18432
	ds_read_b128 v[160:163], v229 offset:19456
	s_add_i32 s20, s14, 2
	s_add_u32 s16, s12, 0xfff00080
	s_addc_u32 s17, s13, -1
	s_cmp_eq_u32 s1, s14
	s_cselect_b32 s19, s39, s17
	s_cselect_b32 s18, s38, s16
	s_cselect_b32 s17, s41, s11
	s_cselect_b32 s16, s40, s3
	v_lshl_add_u64 v[208:209], s[12:13], 0, v[204:205]
	s_add_i32 m0, s35, 0xc000
	ds_read_b128 v[164:167], v228
	ds_read_b128 v[168:171], v228 offset:1024
	ds_read_b128 v[172:175], v228 offset:2048
	ds_read_b128 v[176:179], v228 offset:3072
	ds_read_b128 v[180:183], v228 offset:4096
	ds_read_b128 v[184:187], v228 offset:5120
	ds_read_b128 v[188:191], v228 offset:6144
	ds_read_b128 v[192:195], v228 offset:7168
	global_load_lds_dwordx4 v[208:209], off
	v_lshl_add_u64 v[208:209], s[12:13], 0, v[206:207]
	s_add_i32 m0, s35, 0xe000
	s_nop 0
	global_load_lds_dwordx4 v[208:209], off
	s_waitcnt vmcnt(8)
	s_waitcnt lgkmcnt(0)
	s_setprio 0
	s_barrier
	v_mfma_f32_16x16x32_bf16 v[128:131], v[132:135], v[164:167], v[128:131]
	v_mfma_f32_16x16x32_bf16 v[124:127], v[140:143], v[164:167], v[124:127]
	v_mfma_f32_16x16x32_bf16 v[120:123], v[132:135], v[172:175], v[120:123]
	v_mfma_f32_16x16x32_bf16 v[116:119], v[140:143], v[172:175], v[116:119]
	v_mfma_f32_16x16x32_bf16 v[112:115], v[132:135], v[180:183], v[112:115]
	v_mfma_f32_16x16x32_bf16 v[108:111], v[140:143], v[180:183], v[108:111]
	v_mfma_f32_16x16x32_bf16 v[104:107], v[132:135], v[188:191], v[104:107]
	v_mfma_f32_16x16x32_bf16 v[100:103], v[140:143], v[188:191], v[100:103]
	v_mfma_f32_16x16x32_bf16 v[128:131], v[136:139], v[168:171], v[128:131]
	v_mfma_f32_16x16x32_bf16 v[124:127], v[144:147], v[168:171], v[124:127]
	v_mfma_f32_16x16x32_bf16 v[120:123], v[136:139], v[176:179], v[120:123]
	v_mfma_f32_16x16x32_bf16 v[116:119], v[144:147], v[176:179], v[116:119]
	v_mfma_f32_16x16x32_bf16 v[112:115], v[136:139], v[184:187], v[112:115]
	v_mfma_f32_16x16x32_bf16 v[108:111], v[144:147], v[184:187], v[108:111]
	v_mfma_f32_16x16x32_bf16 v[104:107], v[136:139], v[192:195], v[104:107]
	v_mfma_f32_16x16x32_bf16 v[100:103], v[144:147], v[192:195], v[100:103]
	v_mfma_f32_16x16x32_bf16 v[96:99], v[148:151], v[164:167], v[96:99]
	v_mfma_f32_16x16x32_bf16 v[92:95], v[156:159], v[164:167], v[92:95]
	v_mfma_f32_16x16x32_bf16 v[88:91], v[148:151], v[172:175], v[88:91]
	v_mfma_f32_16x16x32_bf16 v[80:83], v[156:159], v[172:175], v[80:83]
	v_mfma_f32_16x16x32_bf16 v[64:67], v[148:151], v[180:183], v[64:67]
	v_mfma_f32_16x16x32_bf16 v[52:55], v[156:159], v[180:183], v[52:55]
	v_mfma_f32_16x16x32_bf16 v[32:35], v[148:151], v[188:191], v[32:35]
	v_mfma_f32_16x16x32_bf16 v[20:23], v[156:159], v[188:191], v[20:23]
	v_mfma_f32_16x16x32_bf16 v[96:99], v[152:155], v[168:171], v[96:99]
	v_mfma_f32_16x16x32_bf16 v[92:95], v[160:163], v[168:171], v[92:95]
	v_mfma_f32_16x16x32_bf16 v[88:91], v[152:155], v[176:179], v[88:91]
	v_mfma_f32_16x16x32_bf16 v[80:83], v[160:163], v[176:179], v[80:83]
	v_mfma_f32_16x16x32_bf16 v[64:67], v[152:155], v[184:187], v[64:67]
	v_mfma_f32_16x16x32_bf16 v[52:55], v[160:163], v[184:187], v[52:55]
	v_mfma_f32_16x16x32_bf16 v[32:35], v[152:155], v[192:195], v[32:35]
	v_mfma_f32_16x16x32_bf16 v[20:23], v[160:163], v[192:195], v[20:23]
	s_barrier
	s_setprio 1
	s_mov_b32 m0, s44
	v_lshl_add_u64 v[208:209], s[16:17], 0, v[198:199]
	s_add_u32 s62, s16, 0x100000
	ds_read_b128 v[164:167], v228 offset:16384
	ds_read_b128 v[168:171], v228 offset:17408
	ds_read_b128 v[172:175], v228 offset:18432
	ds_read_b128 v[176:179], v228 offset:19456
	ds_read_b128 v[180:183], v228 offset:20480
	ds_read_b128 v[184:187], v228 offset:21504
	ds_read_b128 v[188:191], v228 offset:22528
	ds_read_b128 v[192:195], v228 offset:23552
	global_load_lds_dwordx4 v[208:209], off
	v_lshl_add_u64 v[210:211], s[16:17], 0, v[202:203]
	s_mov_b32 m0, s45
	s_addc_u32 s63, s17, 0
	global_load_lds_dwordx4 v[210:211], off
	v_lshl_add_u64 v[212:213], s[62:63], 0, v[198:199]
	s_mov_b32 m0, s46
	v_lshl_add_u64 v[214:215], s[18:19], 0, v[200:201]
	global_load_lds_dwordx4 v[212:213], off
	v_lshl_add_u64 v[212:213], s[62:63], 0, v[202:203]
	s_mov_b32 m0, s47
	s_nop 0
	global_load_lds_dwordx4 v[212:213], off
	v_lshl_add_u64 v[212:213], s[18:19], 0, v[196:197]
	s_mov_b32 m0, s35
	s_nop 0
	global_load_lds_dwordx4 v[212:213], off
	s_mov_b32 m0, s48
	s_nop 0
	global_load_lds_dwordx4 v[214:215], off
	s_waitcnt vmcnt(8)
	s_waitcnt lgkmcnt(0)
	s_setprio 0
	s_barrier
; #define PG8_STAGE(bufoff, gbase, voff) do { _Pragma("unroll") for (int _i = 0; _i < 2; ++_i) \
;         __builtin_amdgcn_global_load_lds((const unsigned*)((const char*)(gbase) + (voff)[_i]), (LAS unsigned*)(lds + (bufoff) + ldsw + _i * 8192), 16, 0, 0); } while (0)
; #define PG8_LDA(dst, b, h) do { _Pragma("unroll") for (int m = 0; m < 4; ++m) _Pragma("unroll") for (int k = 0; k < 2; ++k) dst[m][k] = *(const LAS bf16x8*)(pA + PG8_SA(b, h) + m * 2048 + k * 1024); } while (0)
; #define PG8_LDB(dst, b, h) do { _Pragma("unroll") for (int n = 0; n < 2; ++n) _Pragma("unroll") for (int k = 0; k < 2; ++k) dst[n][k] = *(const LAS bf16x8*)(pB + (PG8_SB(b, h) - 4 * HTB) + n * 2048 + k * 1024); } while (0)
; #define PG8_MMA(ai, bj, At, Bt) do { __builtin_amdgcn_s_setprio(1); _Pragma("unroll") for (int m = 0; m < 4; ++m) _Pragma("unroll") for (int n = 0; n < 2; ++n) _Pragma("unroll") for (int k = 0; k < 2; ++k) \
;         acc[ai][bj][m][n] = __builtin_amdgcn_mfma_f32_16x16x32_bf16(Bt[n][k], At[m][k], acc[ai][bj][m][n], 0, 0, 0); __builtin_amdgcn_s_setprio(0); } while (0)
; #define PG8_WAIT_V(n) asm volatile("s_waitcnt vmcnt(" #n ")" ::: "memory")
; #define PG8_WAIT_L(n) asm volatile("s_waitcnt lgkmcnt(" #n ")" ::: "memory")
; #define PG8_BAR __builtin_amdgcn_s_barrier()
; #define PG8_SCHED __builtin_amdgcn_sched_barrier(0)
; template <class Desc, class Epi, bool ALIGN_EPI>
; __device__ __forceinline__ void gemm_phase(LAS unsigned char* lds, const Desc& D, const Epi& E, int G, int c) {
;     ...
;             PG8_LDA(At, 0, 1); PG8_STAGE(PG8_SB(0, 0), b2, voffB); PG8_STAGE(PG8_SB(0, 1), b2 + hstepB, voffB); PG8_STAGE(PG8_SA(0, 0), a2, voffA);
;             PG8_WAIT_V(8); PG8_WAIT_L(0); PG8_BAR; PG8_MMA(1, 0, At, B0); PG8_MMA(1, 1, At, B1); PG8_BAR; PG8_SCHED;
;             PG8_LDB(B0, 1, 0); PG8_LDB(B1, 1, 1); PG8_SCHED; PG8_LDA(At, 1, 0); PG8_STAGE(PG8_SA(0, 1), a2 + hstepA, voffA);
;             PG8_WAIT_V(8); PG8_WAIT_L(0); PG8_BAR; PG8_MMA(0, 0, At, B0); PG8_MMA(0, 1, At, B1); PG8_BAR; PG8_SCHED;
	v_mfma_f32_16x16x32_bf16 v[84:87], v[132:135], v[164:167], v[84:87]
	v_mfma_f32_16x16x32_bf16 v[76:79], v[140:143], v[164:167], v[76:79]
	v_mfma_f32_16x16x32_bf16 v[72:75], v[132:135], v[172:175], v[72:75]
	v_mfma_f32_16x16x32_bf16 v[68:71], v[140:143], v[172:175], v[68:71]
	v_mfma_f32_16x16x32_bf16 v[60:63], v[132:135], v[180:183], v[60:63]
	v_mfma_f32_16x16x32_bf16 v[56:59], v[140:143], v[180:183], v[56:59]
	v_mfma_f32_16x16x32_bf16 v[48:51], v[132:135], v[188:191], v[48:51]
	v_mfma_f32_16x16x32_bf16 v[44:47], v[140:143], v[188:191], v[44:47]
	v_mfma_f32_16x16x32_bf16 v[84:87], v[136:139], v[168:171], v[84:87]
	v_mfma_f32_16x16x32_bf16 v[76:79], v[144:147], v[168:171], v[76:79]
	v_mfma_f32_16x16x32_bf16 v[72:75], v[136:139], v[176:179], v[72:75]
	v_mfma_f32_16x16x32_bf16 v[68:71], v[144:147], v[176:179], v[68:71]
	v_mfma_f32_16x16x32_bf16 v[60:63], v[136:139], v[184:187], v[60:63]
	v_mfma_f32_16x16x32_bf16 v[56:59], v[144:147], v[184:187], v[56:59]
	v_mfma_f32_16x16x32_bf16 v[48:51], v[136:139], v[192:195], v[48:51]
	v_mfma_f32_16x16x32_bf16 v[44:47], v[144:147], v[192:195], v[44:47]
	v_mfma_f32_16x16x32_bf16 v[40:43], v[148:151], v[164:167], v[40:43]
	v_mfma_f32_16x16x32_bf16 v[36:39], v[156:159], v[164:167], v[36:39]
	v_mfma_f32_16x16x32_bf16 v[28:31], v[148:151], v[172:175], v[28:31]
	v_mfma_f32_16x16x32_bf16 v[24:27], v[156:159], v[172:175], v[24:27]
	v_mfma_f32_16x16x32_bf16 v[16:19], v[148:151], v[180:183], v[16:19]
	v_mfma_f32_16x16x32_bf16 v[12:15], v[156:159], v[180:183], v[12:15]
	v_mfma_f32_16x16x32_bf16 v[8:11], v[148:151], v[188:191], v[8:11]
	v_mfma_f32_16x16x32_bf16 v[4:7], v[156:159], v[188:191], v[4:7]
	v_mfma_f32_16x16x32_bf16 v[40:43], v[152:155], v[168:171], v[40:43]
	v_mfma_f32_16x16x32_bf16 v[36:39], v[160:163], v[168:171], v[36:39]
	v_mfma_f32_16x16x32_bf16 v[28:31], v[152:155], v[176:179], v[28:31]
	v_mfma_f32_16x16x32_bf16 v[24:27], v[160:163], v[176:179], v[24:27]
	v_mfma_f32_16x16x32_bf16 v[16:19], v[152:155], v[184:187], v[16:19]
	v_mfma_f32_16x16x32_bf16 v[12:15], v[160:163], v[184:187], v[12:15]
	v_mfma_f32_16x16x32_bf16 v[8:11], v[152:155], v[192:195], v[8:11]
	v_mfma_f32_16x16x32_bf16 v[4:7], v[160:163], v[192:195], v[4:7]
	s_barrier
	s_setprio 1
	ds_read_b128 v[132:135], v229 offset:32768
	ds_read_b128 v[136:139], v229 offset:33792
	ds_read_b128 v[140:143], v229 offset:34816
	ds_read_b128 v[144:147], v229 offset:35840
	ds_read_b128 v[148:151], v229 offset:49152
	ds_read_b128 v[152:155], v229 offset:50176
	ds_read_b128 v[156:159], v229 offset:51200
	ds_read_b128 v[160:163], v229 offset:52224
	s_add_u32 s18, s18, 0x100000
	s_addc_u32 s19, s19, 0
	s_mov_b32 m0, s49
	v_lshl_add_u64 v[216:217], s[18:19], 0, v[196:197]
	ds_read_b128 v[164:167], v228 offset:32768
	ds_read_b128 v[168:171], v228 offset:33792
	ds_read_b128 v[172:175], v228 offset:34816
	ds_read_b128 v[176:179], v228 offset:35840
	ds_read_b128 v[180:183], v228 offset:36864
	ds_read_b128 v[184:187], v228 offset:37888
	ds_read_b128 v[188:191], v228 offset:38912
	ds_read_b128 v[192:195], v228 offset:39936
	global_load_lds_dwordx4 v[216:217], off
	v_lshl_add_u64 v[216:217], s[18:19], 0, v[200:201]
	s_mov_b32 m0, s50
	s_nop 0
	global_load_lds_dwordx4 v[216:217], off
	s_waitcnt vmcnt(8)
	s_waitcnt lgkmcnt(0)
	s_setprio 0
	s_barrier
	v_mfma_f32_16x16x32_bf16 v[128:131], v[132:135], v[164:167], v[128:131]
	v_mfma_f32_16x16x32_bf16 v[124:127], v[140:143], v[164:167], v[124:127]
	v_mfma_f32_16x16x32_bf16 v[120:123], v[132:135], v[172:175], v[120:123]
	v_mfma_f32_16x16x32_bf16 v[116:119], v[140:143], v[172:175], v[116:119]
	v_mfma_f32_16x16x32_bf16 v[112:115], v[132:135], v[180:183], v[112:115]
	v_mfma_f32_16x16x32_bf16 v[108:111], v[140:143], v[180:183], v[108:111]
	v_mfma_f32_16x16x32_bf16 v[104:107], v[132:135], v[188:191], v[104:107]
	v_mfma_f32_16x16x32_bf16 v[100:103], v[140:143], v[188:191], v[100:103]
	v_mfma_f32_16x16x32_bf16 v[128:131], v[136:139], v[168:171], v[128:131]
	v_mfma_f32_16x16x32_bf16 v[124:127], v[144:147], v[168:171], v[124:127]
	v_mfma_f32_16x16x32_bf16 v[120:123], v[136:139], v[176:179], v[120:123]
	v_mfma_f32_16x16x32_bf16 v[116:119], v[144:147], v[176:179], v[116:119]
	v_mfma_f32_16x16x32_bf16 v[112:115], v[136:139], v[184:187], v[112:115]
	v_mfma_f32_16x16x32_bf16 v[108:111], v[144:147], v[184:187], v[108:111]
	v_mfma_f32_16x16x32_bf16 v[104:107], v[136:139], v[192:195], v[104:107]
	v_mfma_f32_16x16x32_bf16 v[100:103], v[144:147], v[192:195], v[100:103]
	v_mfma_f32_16x16x32_bf16 v[96:99], v[148:151], v[164:167], v[96:99]
	v_mfma_f32_16x16x32_bf16 v[92:95], v[156:159], v[164:167], v[92:95]
	v_mfma_f32_16x16x32_bf16 v[88:91], v[148:151], v[172:175], v[88:91]
	v_mfma_f32_16x16x32_bf16 v[80:83], v[156:159], v[172:175], v[80:83]
	v_mfma_f32_16x16x32_bf16 v[64:67], v[148:151], v[180:183], v[64:67]
	v_mfma_f32_16x16x32_bf16 v[52:55], v[156:159], v[180:183], v[52:55]
	v_mfma_f32_16x16x32_bf16 v[32:35], v[148:151], v[188:191], v[32:35]
	v_mfma_f32_16x16x32_bf16 v[20:23], v[156:159], v[188:191], v[20:23]
	v_mfma_f32_16x16x32_bf16 v[96:99], v[152:155], v[168:171], v[96:99]
	v_mfma_f32_16x16x32_bf16 v[92:95], v[160:163], v[168:171], v[92:95]
	v_mfma_f32_16x16x32_bf16 v[88:91], v[152:155], v[176:179], v[88:91]
	v_mfma_f32_16x16x32_bf16 v[80:83], v[160:163], v[176:179], v[80:83]
	v_mfma_f32_16x16x32_bf16 v[64:67], v[152:155], v[184:187], v[64:67]
	v_mfma_f32_16x16x32_bf16 v[52:55], v[160:163], v[184:187], v[52:55]
	v_mfma_f32_16x16x32_bf16 v[32:35], v[152:155], v[192:195], v[32:35]
	v_mfma_f32_16x16x32_bf16 v[20:23], v[160:163], v[192:195], v[20:23]
	s_barrier
; #define PG8_STAGE(bufoff, gbase, voff) do { _Pragma("unroll") for (int _i = 0; _i < 2; ++_i) \
;         __builtin_amdgcn_global_load_lds((const unsigned*)((const char*)(gbase) + (voff)[_i]), (LAS unsigned*)(lds + (bufoff) + ldsw + _i * 8192), 16, 0, 0); } while (0)
; #define PG8_LDA(dst, b, h) do { _Pragma("unroll") for (int m = 0; m < 4; ++m) _Pragma("unroll") for (int k = 0; k < 2; ++k) dst[m][k] = *(const LAS bf16x8*)(pA + PG8_SA(b, h) + m * 2048 + k * 1024); } while (0)
; #define PG8_MMA(ai, bj, At, Bt) do { __builtin_amdgcn_s_setprio(1); _Pragma("unroll") for (int m = 0; m < 4; ++m) _Pragma("unroll") for (int n = 0; n < 2; ++n) _Pragma("unroll") for (int k = 0; k < 2; ++k) \
;         acc[ai][bj][m][n] = __builtin_amdgcn_mfma_f32_16x16x32_bf16(Bt[n][k], At[m][k], acc[ai][bj][m][n], 0, 0, 0); __builtin_amdgcn_s_setprio(0); } while (0)
; #define PG8_WAIT_V(n) asm volatile("s_waitcnt vmcnt(" #n ")" ::: "memory")
; #define PG8_WAIT_L(n) asm volatile("s_waitcnt lgkmcnt(" #n ")" ::: "memory")
; #define PG8_BAR __builtin_amdgcn_s_barrier()
; #define PG8_SCHED __builtin_amdgcn_sched_barrier(0)
; template <class Desc, class Epi, bool ALIGN_EPI>
; __device__ __forceinline__ void gemm_phase(LAS unsigned char* lds, const Desc& D, const Epi& E, int G, int c) {
;     ...
;             PG8_LDA(At, 1, 1); PG8_STAGE(PG8_SB(1, 0), b3, voffB); PG8_STAGE(PG8_SB(1, 1), b3 + hstepB, voffB); PG8_STAGE(PG8_SA(1, 0), a3, voffA);
;             PG8_WAIT_V(8); PG8_WAIT_L(0); PG8_BAR; PG8_MMA(1, 0, At, B0); PG8_MMA(1, 1, At, B1); PG8_BAR; PG8_SCHED;
;         }
	s_setprio 1
	s_mov_b32 m0, s52
	v_lshl_add_u64 v[208:209], v[208:209], 0, s[76:77]
	s_add_u32 s16, s16, 0x100080
	ds_read_b128 v[164:167], v228 offset:49152
	ds_read_b128 v[168:171], v228 offset:50176
	ds_read_b128 v[172:175], v228 offset:51200
	ds_read_b128 v[176:179], v228 offset:52224
	ds_read_b128 v[180:183], v228 offset:53248
	ds_read_b128 v[184:187], v228 offset:54272
	ds_read_b128 v[188:191], v228 offset:55296
	ds_read_b128 v[192:195], v228 offset:56320
	global_load_lds_dwordx4 v[208:209], off
	v_lshl_add_u64 v[208:209], v[210:211], 0, s[76:77]
	s_mov_b32 m0, s53
	s_addc_u32 s17, s17, 0
	global_load_lds_dwordx4 v[208:209], off
	v_lshl_add_u64 v[208:209], s[16:17], 0, v[198:199]
	s_mov_b32 m0, s56
	s_nop 0
	global_load_lds_dwordx4 v[208:209], off
	v_lshl_add_u64 v[208:209], s[16:17], 0, v[202:203]
	s_mov_b32 m0, s57
	s_nop 0
	global_load_lds_dwordx4 v[208:209], off
	v_lshl_add_u64 v[208:209], v[212:213], 0, s[76:77]
	s_mov_b32 m0, s54
	s_nop 0
	global_load_lds_dwordx4 v[208:209], off
	v_lshl_add_u64 v[208:209], v[214:215], 0, s[76:77]
	s_mov_b32 m0, s55
	s_nop 0
	global_load_lds_dwordx4 v[208:209], off
	s_waitcnt vmcnt(8)
	s_waitcnt lgkmcnt(0)
	s_setprio 0
	s_barrier
	v_mfma_f32_16x16x32_bf16 v[84:87], v[132:135], v[164:167], v[84:87]
	v_mfma_f32_16x16x32_bf16 v[76:79], v[140:143], v[164:167], v[76:79]
	v_mfma_f32_16x16x32_bf16 v[72:75], v[132:135], v[172:175], v[72:75]
	v_mfma_f32_16x16x32_bf16 v[68:71], v[140:143], v[172:175], v[68:71]
	v_mfma_f32_16x16x32_bf16 v[60:63], v[132:135], v[180:183], v[60:63]
	v_mfma_f32_16x16x32_bf16 v[56:59], v[140:143], v[180:183], v[56:59]
	v_mfma_f32_16x16x32_bf16 v[48:51], v[132:135], v[188:191], v[48:51]
	v_mfma_f32_16x16x32_bf16 v[44:47], v[140:143], v[188:191], v[44:47]
	v_mfma_f32_16x16x32_bf16 v[84:87], v[136:139], v[168:171], v[84:87]
	v_mfma_f32_16x16x32_bf16 v[76:79], v[144:147], v[168:171], v[76:79]
	v_mfma_f32_16x16x32_bf16 v[72:75], v[136:139], v[176:179], v[72:75]
	v_mfma_f32_16x16x32_bf16 v[68:71], v[144:147], v[176:179], v[68:71]
	v_mfma_f32_16x16x32_bf16 v[60:63], v[136:139], v[184:187], v[60:63]
	v_mfma_f32_16x16x32_bf16 v[56:59], v[144:147], v[184:187], v[56:59]
	v_mfma_f32_16x16x32_bf16 v[48:51], v[136:139], v[192:195], v[48:51]
	v_mfma_f32_16x16x32_bf16 v[44:47], v[144:147], v[192:195], v[44:47]
	v_mfma_f32_16x16x32_bf16 v[40:43], v[148:151], v[164:167], v[40:43]
	v_mfma_f32_16x16x32_bf16 v[36:39], v[156:159], v[164:167], v[36:39]
	v_mfma_f32_16x16x32_bf16 v[28:31], v[148:151], v[172:175], v[28:31]
	v_mfma_f32_16x16x32_bf16 v[24:27], v[156:159], v[172:175], v[24:27]
	v_mfma_f32_16x16x32_bf16 v[16:19], v[148:151], v[180:183], v[16:19]
	v_mfma_f32_16x16x32_bf16 v[12:15], v[156:159], v[180:183], v[12:15]
	v_mfma_f32_16x16x32_bf16 v[8:11], v[148:151], v[188:191], v[8:11]
	v_mfma_f32_16x16x32_bf16 v[4:7], v[156:159], v[188:191], v[4:7]
	v_mfma_f32_16x16x32_bf16 v[40:43], v[152:155], v[168:171], v[40:43]
	v_mfma_f32_16x16x32_bf16 v[36:39], v[160:163], v[168:171], v[36:39]
	v_mfma_f32_16x16x32_bf16 v[28:31], v[152:155], v[176:179], v[28:31]
	v_mfma_f32_16x16x32_bf16 v[24:27], v[160:163], v[176:179], v[24:27]
	v_mfma_f32_16x16x32_bf16 v[16:19], v[152:155], v[184:187], v[16:19]
	v_mfma_f32_16x16x32_bf16 v[12:15], v[160:163], v[184:187], v[12:15]
	v_mfma_f32_16x16x32_bf16 v[8:11], v[152:155], v[192:195], v[8:11]
	v_mfma_f32_16x16x32_bf16 v[4:7], v[160:163], v[192:195], v[4:7]
	s_barrier
	s_setprio 1
	s_add_u32 s12, s12, 0x100
	s_addc_u32 s13, s13, 0
	s_add_u32 s3, s3, 0x100
	s_addc_u32 s11, s11, 0
	s_cmp_ge_u32 s20, s2
	s_mov_b32 s14, s20
	s_cbranch_scc0 .LBB0_1164
	s_and_b64 vcc, exec, s[8:9]
	s_cbranch_vccz .LBB0_1167
	s_barrier

; #define PG8_STAGE(bufoff, gbase, voff) do { _Pragma("unroll") for (int _i = 0; _i < 2; ++_i) \
;         __builtin_amdgcn_global_load_lds((const unsigned*)((const char*)(gbase) + (voff)[_i]), (LAS unsigned*)(lds + (bufoff) + ldsw + _i * 8192), 16, 0, 0); } while (0)
; #define PG8_LDA(dst, b, h) do { _Pragma("unroll") for (int m = 0; m < 4; ++m) _Pragma("unroll") for (int k = 0; k < 2; ++k) dst[m][k] = *(const LAS bf16x8*)(pA + PG8_SA(b, h) + m * 2048 + k * 1024); } while (0)
; #define PG8_LDB(dst, b, h) do { _Pragma("unroll") for (int n = 0; n < 2; ++n) _Pragma("unroll") for (int k = 0; k < 2; ++k) dst[n][k] = *(const LAS bf16x8*)(pB + (PG8_SB(b, h) - 4 * HTB) + n * 2048 + k * 1024); } while (0)
; #define PG8_MMA(ai, bj, At, Bt) do { __builtin_amdgcn_s_setprio(1); _Pragma("unroll") for (int m = 0; m < 4; ++m) _Pragma("unroll") for (int n = 0; n < 2; ++n) _Pragma("unroll") for (int k = 0; k < 2; ++k) \
;         acc[ai][bj][m][n] = __builtin_amdgcn_mfma_f32_16x16x32_bf16(Bt[n][k], At[m][k], acc[ai][bj][m][n], 0, 0, 0); __builtin_amdgcn_s_setprio(0); } while (0)
; #define PG8_WAIT_V(n) asm volatile("s_waitcnt vmcnt(" #n ")" ::: "memory")
; #define PG8_BAR __builtin_amdgcn_s_barrier()
; template <class Desc, class Epi, bool ALIGN_EPI>
; __device__ __forceinline__ void gemm_phase(LAS unsigned char* lds, const Desc& D, const Epi& E, int G, int c) {
;     ...
;             PG8_LDB(B0, 0, 0); PG8_LDB(B1, 0, 1); PG8_SCHED; PG8_LDA(At, 0, 0); PG8_STAGE(PG8_SA(1, 1), a1 + hstepA, voffA);
;             PG8_WAIT_V(8); PG8_WAIT_L(0); PG8_BAR; PG8_MMA(0, 0, At, B0); PG8_MMA(0, 1, At, B1); PG8_BAR; PG8_SCHED;
;             PG8_LDA(At, 0, 1); PG8_STAGE(PG8_SB(0, 0), b2, voffB); PG8_STAGE(PG8_SB(0, 1), b2 + hstepB, voffB); PG8_STAGE(PG8_SA(0, 0), a2, voffA);
;             PG8_WAIT_V(8); PG8_WAIT_L(0); PG8_BAR; PG8_MMA(1, 0, At, B0); PG8_MMA(1, 1, At, B1); PG8_BAR; PG8_SCHED;
;             PG8_LDB(B0, 1, 0); PG8_LDB(B1, 1, 1); PG8_SCHED; PG8_LDA(At, 1, 0); PG8_STAGE(PG8_SA(0, 1), a2 + hstepA, voffA);
;             PG8_WAIT_V(8); PG8_WAIT_L(0); PG8_BAR; PG8_MMA(0, 0, At, B0); PG8_MMA(0, 1, At, B1); PG8_BAR; PG8_SCHED;
;             PG8_LDA(At, 1, 1); PG8_STAGE(PG8_SB(1, 0), b3, voffB); PG8_STAGE(PG8_SB(1, 1), b3 + hstepB, voffB); PG8_STAGE(PG8_SA(1, 0), a3, voffA);
;             PG8_WAIT_V(8); PG8_WAIT_L(0); PG8_BAR; PG8_MMA(1, 0, At, B0); PG8_MMA(1, 1, At, B1); PG8_BAR; PG8_SCHED;
.LBB0_1324:
	ds_read_b128 v[144:147], v149
	ds_read_b128 v[152:155], v149 offset:1024
	ds_read_b128 v[156:159], v149 offset:2048
	ds_read_b128 v[160:163], v149 offset:3072
	ds_read_b128 v[164:167], v149 offset:16384
	ds_read_b128 v[168:171], v149 offset:17408
	ds_read_b128 v[172:175], v149 offset:18432
	ds_read_b128 v[176:179], v149 offset:19456
	s_add_i32 s50, s18, 2
	s_add_u32 s19, s16, 0xfff00080
	s_addc_u32 s20, s17, -1
	s_cmp_eq_u32 s9, s18
	s_cselect_b32 s18, s12, s48
	s_cselect_b32 s21, s11, s20
	s_cselect_b32 s20, s10, s19
	s_cselect_b32 s19, s13, s49
	v_lshl_add_u64 v[212:213], s[16:17], 0, v[140:141]
	s_add_i32 m0, s24, 0xc000
	ds_read_b128 v[180:183], v148
	ds_read_b128 v[184:187], v148 offset:1024
	ds_read_b128 v[188:191], v148 offset:2048
	ds_read_b128 v[192:195], v148 offset:3072
	ds_read_b128 v[196:199], v148 offset:4096
	ds_read_b128 v[200:203], v148 offset:5120
	ds_read_b128 v[204:207], v148 offset:6144
	ds_read_b128 v[208:211], v148 offset:7168
	global_load_lds_dwordx4 v[212:213], off
	v_lshl_add_u64 v[212:213], s[16:17], 0, v[142:143]
	s_add_i32 m0, s24, 0xe000
	s_nop 0
	global_load_lds_dwordx4 v[212:213], off
	s_waitcnt vmcnt(8)
	s_waitcnt lgkmcnt(0)
	s_setprio 0
	s_barrier
	v_mfma_f32_16x16x32_bf16 v[128:131], v[144:147], v[180:183], v[128:131]
	v_mfma_f32_16x16x32_bf16 v[124:127], v[156:159], v[180:183], v[124:127]
	v_mfma_f32_16x16x32_bf16 v[120:123], v[144:147], v[188:191], v[120:123]
	v_mfma_f32_16x16x32_bf16 v[112:115], v[156:159], v[188:191], v[112:115]
	v_mfma_f32_16x16x32_bf16 v[104:107], v[144:147], v[196:199], v[104:107]
	v_mfma_f32_16x16x32_bf16 v[96:99], v[156:159], v[196:199], v[96:99]
	v_mfma_f32_16x16x32_bf16 v[88:91], v[144:147], v[204:207], v[88:91]
	v_mfma_f32_16x16x32_bf16 v[80:83], v[156:159], v[204:207], v[80:83]
	v_mfma_f32_16x16x32_bf16 v[128:131], v[152:155], v[184:187], v[128:131]
	v_mfma_f32_16x16x32_bf16 v[124:127], v[160:163], v[184:187], v[124:127]
	v_mfma_f32_16x16x32_bf16 v[120:123], v[152:155], v[192:195], v[120:123]
	v_mfma_f32_16x16x32_bf16 v[112:115], v[160:163], v[192:195], v[112:115]
	v_mfma_f32_16x16x32_bf16 v[104:107], v[152:155], v[200:203], v[104:107]
	v_mfma_f32_16x16x32_bf16 v[96:99], v[160:163], v[200:203], v[96:99]
	v_mfma_f32_16x16x32_bf16 v[88:91], v[152:155], v[208:211], v[88:91]
	v_mfma_f32_16x16x32_bf16 v[80:83], v[160:163], v[208:211], v[80:83]
	v_mfma_f32_16x16x32_bf16 v[116:119], v[164:167], v[180:183], v[116:119]
	v_mfma_f32_16x16x32_bf16 v[108:111], v[172:175], v[180:183], v[108:111]
	v_mfma_f32_16x16x32_bf16 v[100:103], v[164:167], v[188:191], v[100:103]
	v_mfma_f32_16x16x32_bf16 v[92:95], v[172:175], v[188:191], v[92:95]
	v_mfma_f32_16x16x32_bf16 v[84:87], v[164:167], v[196:199], v[84:87]
	v_mfma_f32_16x16x32_bf16 v[76:79], v[172:175], v[196:199], v[76:79]
	v_mfma_f32_16x16x32_bf16 v[72:75], v[164:167], v[204:207], v[72:75]
	v_mfma_f32_16x16x32_bf16 v[68:71], v[172:175], v[204:207], v[68:71]
	v_mfma_f32_16x16x32_bf16 v[116:119], v[168:171], v[184:187], v[116:119]
	v_mfma_f32_16x16x32_bf16 v[108:111], v[176:179], v[184:187], v[108:111]
	v_mfma_f32_16x16x32_bf16 v[100:103], v[168:171], v[192:195], v[100:103]
	v_mfma_f32_16x16x32_bf16 v[92:95], v[176:179], v[192:195], v[92:95]
	v_mfma_f32_16x16x32_bf16 v[84:87], v[168:171], v[200:203], v[84:87]
	v_mfma_f32_16x16x32_bf16 v[76:79], v[176:179], v[200:203], v[76:79]
	v_mfma_f32_16x16x32_bf16 v[72:75], v[168:171], v[208:211], v[72:75]
	v_mfma_f32_16x16x32_bf16 v[68:71], v[176:179], v[208:211], v[68:71]
	s_barrier
	s_setprio 1
	s_mov_b32 m0, s25
	v_lshl_add_u64 v[212:213], s[18:19], 0, v[136:137]
	s_add_u32 s52, s18, 0x100000
	ds_read_b128 v[180:183], v148 offset:16384
	ds_read_b128 v[184:187], v148 offset:17408
	ds_read_b128 v[188:191], v148 offset:18432
	ds_read_b128 v[192:195], v148 offset:19456
	ds_read_b128 v[196:199], v148 offset:20480
	ds_read_b128 v[200:203], v148 offset:21504
	ds_read_b128 v[204:207], v148 offset:22528
	ds_read_b128 v[208:211], v148 offset:23552
	global_load_lds_dwordx4 v[212:213], off
	v_lshl_add_u64 v[214:215], s[18:19], 0, v[132:133]
	s_mov_b32 m0, s26
	s_addc_u32 s53, s19, 0
	global_load_lds_dwordx4 v[214:215], off
	v_lshl_add_u64 v[216:217], s[52:53], 0, v[136:137]
	s_mov_b32 m0, s27
	v_lshl_add_u64 v[218:219], s[20:21], 0, v[134:135]
	global_load_lds_dwordx4 v[216:217], off
	v_lshl_add_u64 v[216:217], s[52:53], 0, v[132:133]
	s_mov_b32 m0, s30
	s_nop 0
	global_load_lds_dwordx4 v[216:217], off
	v_lshl_add_u64 v[216:217], s[20:21], 0, v[138:139]
	s_mov_b32 m0, s24
	s_nop 0
	global_load_lds_dwordx4 v[216:217], off
	s_mov_b32 m0, s31
	s_nop 0
	global_load_lds_dwordx4 v[218:219], off
	s_waitcnt vmcnt(8)
	s_waitcnt lgkmcnt(0)
	s_setprio 0
	s_barrier
; #define PG8_STAGE(bufoff, gbase, voff) do { _Pragma("unroll") for (int _i = 0; _i < 2; ++_i) \
;         __builtin_amdgcn_global_load_lds((const unsigned*)((const char*)(gbase) + (voff)[_i]), (LAS unsigned*)(lds + (bufoff) + ldsw + _i * 8192), 16, 0, 0); } while (0)
; #define PG8_LDA(dst, b, h) do { _Pragma("unroll") for (int m = 0; m < 4; ++m) _Pragma("unroll") for (int k = 0; k < 2; ++k) dst[m][k] = *(const LAS bf16x8*)(pA + PG8_SA(b, h) + m * 2048 + k * 1024); } while (0)
; #define PG8_LDB(dst, b, h) do { _Pragma("unroll") for (int n = 0; n < 2; ++n) _Pragma("unroll") for (int k = 0; k < 2; ++k) dst[n][k] = *(const LAS bf16x8*)(pB + (PG8_SB(b, h) - 4 * HTB) + n * 2048 + k * 1024); } while (0)
; #define PG8_MMA(ai, bj, At, Bt) do { __builtin_amdgcn_s_setprio(1); _Pragma("unroll") for (int m = 0; m < 4; ++m) _Pragma("unroll") for (int n = 0; n < 2; ++n) _Pragma("unroll") for (int k = 0; k < 2; ++k) \
;         acc[ai][bj][m][n] = __builtin_amdgcn_mfma_f32_16x16x32_bf16(Bt[n][k], At[m][k], acc[ai][bj][m][n], 0, 0, 0); __builtin_amdgcn_s_setprio(0); } while (0)
; #define PG8_WAIT_V(n) asm volatile("s_waitcnt vmcnt(" #n ")" ::: "memory")
; #define PG8_WAIT_L(n) asm volatile("s_waitcnt lgkmcnt(" #n ")" ::: "memory")
; #define PG8_BAR __builtin_amdgcn_s_barrier()
; #define PG8_SCHED __builtin_amdgcn_sched_barrier(0)
; template <class Desc, class Epi, bool ALIGN_EPI>
; __device__ __forceinline__ void gemm_phase(LAS unsigned char* lds, const Desc& D, const Epi& E, int G, int c) {
;     ...
;             PG8_LDA(At, 0, 1); PG8_STAGE(PG8_SB(0, 0), b2, voffB); PG8_STAGE(PG8_SB(0, 1), b2 + hstepB, voffB); PG8_STAGE(PG8_SA(0, 0), a2, voffA);
;             PG8_WAIT_V(8); PG8_WAIT_L(0); PG8_BAR; PG8_MMA(1, 0, At, B0); PG8_MMA(1, 1, At, B1); PG8_BAR; PG8_SCHED;
;             PG8_LDB(B0, 1, 0); PG8_LDB(B1, 1, 1); PG8_SCHED; PG8_LDA(At, 1, 0); PG8_STAGE(PG8_SA(0, 1), a2 + hstepA, voffA);
;             PG8_WAIT_V(8); PG8_WAIT_L(0); PG8_BAR; PG8_MMA(0, 0, At, B0); PG8_MMA(0, 1, At, B1); PG8_BAR; PG8_SCHED;
	v_mfma_f32_16x16x32_bf16 v[64:67], v[144:147], v[180:183], v[64:67]
	v_mfma_f32_16x16x32_bf16 v[60:63], v[156:159], v[180:183], v[60:63]
	v_mfma_f32_16x16x32_bf16 v[56:59], v[144:147], v[188:191], v[56:59]
	v_mfma_f32_16x16x32_bf16 v[48:51], v[156:159], v[188:191], v[48:51]
	v_mfma_f32_16x16x32_bf16 v[40:43], v[144:147], v[196:199], v[40:43]
	v_mfma_f32_16x16x32_bf16 v[32:35], v[156:159], v[196:199], v[32:35]
	v_mfma_f32_16x16x32_bf16 v[24:27], v[144:147], v[204:207], v[24:27]
	v_mfma_f32_16x16x32_bf16 v[16:19], v[156:159], v[204:207], v[16:19]
	v_mfma_f32_16x16x32_bf16 v[64:67], v[152:155], v[184:187], v[64:67]
	v_mfma_f32_16x16x32_bf16 v[60:63], v[160:163], v[184:187], v[60:63]
	v_mfma_f32_16x16x32_bf16 v[56:59], v[152:155], v[192:195], v[56:59]
	v_mfma_f32_16x16x32_bf16 v[48:51], v[160:163], v[192:195], v[48:51]
	v_mfma_f32_16x16x32_bf16 v[40:43], v[152:155], v[200:203], v[40:43]
	v_mfma_f32_16x16x32_bf16 v[32:35], v[160:163], v[200:203], v[32:35]
	v_mfma_f32_16x16x32_bf16 v[24:27], v[152:155], v[208:211], v[24:27]
	v_mfma_f32_16x16x32_bf16 v[16:19], v[160:163], v[208:211], v[16:19]
	v_mfma_f32_16x16x32_bf16 v[52:55], v[164:167], v[180:183], v[52:55]
	v_mfma_f32_16x16x32_bf16 v[44:47], v[172:175], v[180:183], v[44:47]
	v_mfma_f32_16x16x32_bf16 v[36:39], v[164:167], v[188:191], v[36:39]
	v_mfma_f32_16x16x32_bf16 v[28:31], v[172:175], v[188:191], v[28:31]
	v_mfma_f32_16x16x32_bf16 v[20:23], v[164:167], v[196:199], v[20:23]
	v_mfma_f32_16x16x32_bf16 v[12:15], v[172:175], v[196:199], v[12:15]
	v_mfma_f32_16x16x32_bf16 v[8:11], v[164:167], v[204:207], v[8:11]
	v_mfma_f32_16x16x32_bf16 v[4:7], v[172:175], v[204:207], v[4:7]
	v_mfma_f32_16x16x32_bf16 v[52:55], v[168:171], v[184:187], v[52:55]
	v_mfma_f32_16x16x32_bf16 v[44:47], v[176:179], v[184:187], v[44:47]
	v_mfma_f32_16x16x32_bf16 v[36:39], v[168:171], v[192:195], v[36:39]
	v_mfma_f32_16x16x32_bf16 v[28:31], v[176:179], v[192:195], v[28:31]
	v_mfma_f32_16x16x32_bf16 v[20:23], v[168:171], v[200:203], v[20:23]
	v_mfma_f32_16x16x32_bf16 v[12:15], v[176:179], v[200:203], v[12:15]
	v_mfma_f32_16x16x32_bf16 v[8:11], v[168:171], v[208:211], v[8:11]
	v_mfma_f32_16x16x32_bf16 v[4:7], v[176:179], v[208:211], v[4:7]
	s_barrier
	s_setprio 1
	ds_read_b128 v[144:147], v149 offset:32768
	ds_read_b128 v[152:155], v149 offset:33792
	ds_read_b128 v[156:159], v149 offset:34816
	ds_read_b128 v[160:163], v149 offset:35840
	ds_read_b128 v[164:167], v149 offset:49152
	ds_read_b128 v[168:171], v149 offset:50176
	ds_read_b128 v[172:175], v149 offset:51200
	ds_read_b128 v[176:179], v149 offset:52224
	s_add_u32 s20, s20, 0x100000
	s_addc_u32 s21, s21, 0
	s_mov_b32 m0, s33
	v_lshl_add_u64 v[220:221], s[20:21], 0, v[138:139]
	ds_read_b128 v[180:183], v148 offset:32768
	ds_read_b128 v[184:187], v148 offset:33792
	ds_read_b128 v[188:191], v148 offset:34816
	ds_read_b128 v[192:195], v148 offset:35840
	ds_read_b128 v[196:199], v148 offset:36864
	ds_read_b128 v[200:203], v148 offset:37888
	ds_read_b128 v[204:207], v148 offset:38912
	ds_read_b128 v[208:211], v148 offset:39936
	global_load_lds_dwordx4 v[220:221], off
	v_lshl_add_u64 v[220:221], s[20:21], 0, v[134:135]
	s_mov_b32 m0, s34
	s_nop 0
	global_load_lds_dwordx4 v[220:221], off
	s_waitcnt vmcnt(8)
	s_waitcnt lgkmcnt(0)
	s_setprio 0
	s_barrier
	v_mfma_f32_16x16x32_bf16 v[128:131], v[144:147], v[180:183], v[128:131]
	v_mfma_f32_16x16x32_bf16 v[124:127], v[156:159], v[180:183], v[124:127]
	v_mfma_f32_16x16x32_bf16 v[120:123], v[144:147], v[188:191], v[120:123]
	v_mfma_f32_16x16x32_bf16 v[112:115], v[156:159], v[188:191], v[112:115]
	v_mfma_f32_16x16x32_bf16 v[104:107], v[144:147], v[196:199], v[104:107]
	v_mfma_f32_16x16x32_bf16 v[96:99], v[156:159], v[196:199], v[96:99]
	v_mfma_f32_16x16x32_bf16 v[88:91], v[144:147], v[204:207], v[88:91]
	v_mfma_f32_16x16x32_bf16 v[80:83], v[156:159], v[204:207], v[80:83]
	v_mfma_f32_16x16x32_bf16 v[128:131], v[152:155], v[184:187], v[128:131]
	v_mfma_f32_16x16x32_bf16 v[124:127], v[160:163], v[184:187], v[124:127]
	v_mfma_f32_16x16x32_bf16 v[120:123], v[152:155], v[192:195], v[120:123]
	v_mfma_f32_16x16x32_bf16 v[112:115], v[160:163], v[192:195], v[112:115]
	v_mfma_f32_16x16x32_bf16 v[104:107], v[152:155], v[200:203], v[104:107]
	v_mfma_f32_16x16x32_bf16 v[96:99], v[160:163], v[200:203], v[96:99]
	v_mfma_f32_16x16x32_bf16 v[88:91], v[152:155], v[208:211], v[88:91]
	v_mfma_f32_16x16x32_bf16 v[80:83], v[160:163], v[208:211], v[80:83]
	v_mfma_f32_16x16x32_bf16 v[116:119], v[164:167], v[180:183], v[116:119]
	v_mfma_f32_16x16x32_bf16 v[108:111], v[172:175], v[180:183], v[108:111]
	v_mfma_f32_16x16x32_bf16 v[100:103], v[164:167], v[188:191], v[100:103]
	v_mfma_f32_16x16x32_bf16 v[92:95], v[172:175], v[188:191], v[92:95]
	v_mfma_f32_16x16x32_bf16 v[84:87], v[164:167], v[196:199], v[84:87]
	v_mfma_f32_16x16x32_bf16 v[76:79], v[172:175], v[196:199], v[76:79]
	v_mfma_f32_16x16x32_bf16 v[72:75], v[164:167], v[204:207], v[72:75]
	v_mfma_f32_16x16x32_bf16 v[68:71], v[172:175], v[204:207], v[68:71]
	v_mfma_f32_16x16x32_bf16 v[116:119], v[168:171], v[184:187], v[116:119]
	v_mfma_f32_16x16x32_bf16 v[108:111], v[176:179], v[184:187], v[108:111]
	v_mfma_f32_16x16x32_bf16 v[100:103], v[168:171], v[192:195], v[100:103]
	v_mfma_f32_16x16x32_bf16 v[92:95], v[176:179], v[192:195], v[92:95]
	v_mfma_f32_16x16x32_bf16 v[84:87], v[168:171], v[200:203], v[84:87]
	v_mfma_f32_16x16x32_bf16 v[76:79], v[176:179], v[200:203], v[76:79]
	v_mfma_f32_16x16x32_bf16 v[72:75], v[168:171], v[208:211], v[72:75]
	v_mfma_f32_16x16x32_bf16 v[68:71], v[176:179], v[208:211], v[68:71]
	s_barrier
; #define PG8_STAGE(bufoff, gbase, voff) do { _Pragma("unroll") for (int _i = 0; _i < 2; ++_i) \
;         __builtin_amdgcn_global_load_lds((const unsigned*)((const char*)(gbase) + (voff)[_i]), (LAS unsigned*)(lds + (bufoff) + ldsw + _i * 8192), 16, 0, 0); } while (0)
; #define PG8_LDA(dst, b, h) do { _Pragma("unroll") for (int m = 0; m < 4; ++m) _Pragma("unroll") for (int k = 0; k < 2; ++k) dst[m][k] = *(const LAS bf16x8*)(pA + PG8_SA(b, h) + m * 2048 + k * 1024); } while (0)
; #define PG8_MMA(ai, bj, At, Bt) do { __builtin_amdgcn_s_setprio(1); _Pragma("unroll") for (int m = 0; m < 4; ++m) _Pragma("unroll") for (int n = 0; n < 2; ++n) _Pragma("unroll") for (int k = 0; k < 2; ++k) \
;         acc[ai][bj][m][n] = __builtin_amdgcn_mfma_f32_16x16x32_bf16(Bt[n][k], At[m][k], acc[ai][bj][m][n], 0, 0, 0); __builtin_amdgcn_s_setprio(0); } while (0)
; #define PG8_WAIT_V(n) asm volatile("s_waitcnt vmcnt(" #n ")" ::: "memory")
; #define PG8_WAIT_L(n) asm volatile("s_waitcnt lgkmcnt(" #n ")" ::: "memory")
; #define PG8_BAR __builtin_amdgcn_s_barrier()
; #define PG8_SCHED __builtin_amdgcn_sched_barrier(0)
; template <class Desc, class Epi, bool ALIGN_EPI>
; __device__ __forceinline__ void gemm_phase(LAS unsigned char* lds, const Desc& D, const Epi& E, int G, int c) {
;     ...
;             PG8_LDA(At, 1, 1); PG8_STAGE(PG8_SB(1, 0), b3, voffB); PG8_STAGE(PG8_SB(1, 1), b3 + hstepB, voffB); PG8_STAGE(PG8_SA(1, 0), a3, voffA);
;             PG8_WAIT_V(8); PG8_WAIT_L(0); PG8_BAR; PG8_MMA(1, 0, At, B0); PG8_MMA(1, 1, At, B1); PG8_BAR; PG8_SCHED;
;         }
	s_setprio 1
	s_mov_b32 m0, s35
	v_lshl_add_u64 v[212:213], v[212:213], 0, s[76:77]
	s_add_u32 s18, s18, 0x100080
	ds_read_b128 v[180:183], v148 offset:49152
	ds_read_b128 v[184:187], v148 offset:50176
	ds_read_b128 v[188:191], v148 offset:51200
	ds_read_b128 v[192:195], v148 offset:52224
	ds_read_b128 v[196:199], v148 offset:53248
	ds_read_b128 v[200:203], v148 offset:54272
	ds_read_b128 v[204:207], v148 offset:55296
	ds_read_b128 v[208:211], v148 offset:56320
	global_load_lds_dwordx4 v[212:213], off
	v_lshl_add_u64 v[212:213], v[214:215], 0, s[76:77]
	s_mov_b32 m0, s38
	s_addc_u32 s19, s19, 0
	global_load_lds_dwordx4 v[212:213], off
	v_lshl_add_u64 v[212:213], s[18:19], 0, v[136:137]
	s_mov_b32 m0, s41
	s_nop 0
	global_load_lds_dwordx4 v[212:213], off
	v_lshl_add_u64 v[212:213], s[18:19], 0, v[132:133]
	s_mov_b32 m0, s42
	s_nop 0
	global_load_lds_dwordx4 v[212:213], off
	v_lshl_add_u64 v[212:213], v[216:217], 0, s[76:77]
	s_mov_b32 m0, s39
	s_nop 0
	global_load_lds_dwordx4 v[212:213], off
	v_lshl_add_u64 v[212:213], v[218:219], 0, s[76:77]
	s_mov_b32 m0, s40
	s_nop 0
	global_load_lds_dwordx4 v[212:213], off
	s_waitcnt vmcnt(8)
	s_waitcnt lgkmcnt(0)
	s_setprio 0
	s_barrier
	v_mfma_f32_16x16x32_bf16 v[64:67], v[144:147], v[180:183], v[64:67]
	v_mfma_f32_16x16x32_bf16 v[60:63], v[156:159], v[180:183], v[60:63]
	v_mfma_f32_16x16x32_bf16 v[56:59], v[144:147], v[188:191], v[56:59]
	v_mfma_f32_16x16x32_bf16 v[48:51], v[156:159], v[188:191], v[48:51]
	v_mfma_f32_16x16x32_bf16 v[40:43], v[144:147], v[196:199], v[40:43]
	v_mfma_f32_16x16x32_bf16 v[32:35], v[156:159], v[196:199], v[32:35]
	v_mfma_f32_16x16x32_bf16 v[24:27], v[144:147], v[204:207], v[24:27]
	v_mfma_f32_16x16x32_bf16 v[16:19], v[156:159], v[204:207], v[16:19]
	v_mfma_f32_16x16x32_bf16 v[64:67], v[152:155], v[184:187], v[64:67]
	v_mfma_f32_16x16x32_bf16 v[60:63], v[160:163], v[184:187], v[60:63]
	v_mfma_f32_16x16x32_bf16 v[56:59], v[152:155], v[192:195], v[56:59]
	v_mfma_f32_16x16x32_bf16 v[48:51], v[160:163], v[192:195], v[48:51]
	v_mfma_f32_16x16x32_bf16 v[40:43], v[152:155], v[200:203], v[40:43]
	v_mfma_f32_16x16x32_bf16 v[32:35], v[160:163], v[200:203], v[32:35]
	v_mfma_f32_16x16x32_bf16 v[24:27], v[152:155], v[208:211], v[24:27]
	v_mfma_f32_16x16x32_bf16 v[16:19], v[160:163], v[208:211], v[16:19]
	v_mfma_f32_16x16x32_bf16 v[52:55], v[164:167], v[180:183], v[52:55]
	v_mfma_f32_16x16x32_bf16 v[44:47], v[172:175], v[180:183], v[44:47]
	v_mfma_f32_16x16x32_bf16 v[36:39], v[164:167], v[188:191], v[36:39]
	v_mfma_f32_16x16x32_bf16 v[28:31], v[172:175], v[188:191], v[28:31]
	v_mfma_f32_16x16x32_bf16 v[20:23], v[164:167], v[196:199], v[20:23]
	v_mfma_f32_16x16x32_bf16 v[12:15], v[172:175], v[196:199], v[12:15]
	v_mfma_f32_16x16x32_bf16 v[8:11], v[164:167], v[204:207], v[8:11]
	v_mfma_f32_16x16x32_bf16 v[4:7], v[172:175], v[204:207], v[4:7]
	v_mfma_f32_16x16x32_bf16 v[52:55], v[168:171], v[184:187], v[52:55]
	v_mfma_f32_16x16x32_bf16 v[44:47], v[176:179], v[184:187], v[44:47]
	v_mfma_f32_16x16x32_bf16 v[36:39], v[168:171], v[192:195], v[36:39]
	v_mfma_f32_16x16x32_bf16 v[28:31], v[176:179], v[192:195], v[28:31]
	v_mfma_f32_16x16x32_bf16 v[20:23], v[168:171], v[200:203], v[20:23]
	v_mfma_f32_16x16x32_bf16 v[12:15], v[176:179], v[200:203], v[12:15]
	v_mfma_f32_16x16x32_bf16 v[8:11], v[168:171], v[208:211], v[8:11]
	v_mfma_f32_16x16x32_bf16 v[4:7], v[176:179], v[208:211], v[4:7]
	s_barrier
	s_setprio 1
	s_add_u32 s16, s16, 0x100
	s_addc_u32 s17, s17, 0
	s_add_u32 s48, s48, 0x100
	s_addc_u32 s49, s49, 0
	s_cmp_ge_u32 s50, s46
	s_mov_b32 s18, s50
	s_cbranch_scc0 .LBB0_1324
	s_and_b64 vcc, exec, s[6:7]
	s_cbranch_vccz .LBB0_1327
	s_barrier

; #define PG8_STAGE(bufoff, gbase, voff) do { _Pragma("unroll") for (int _i = 0; _i < 2; ++_i) \
;         __builtin_amdgcn_global_load_lds((const unsigned*)((const char*)(gbase) + (voff)[_i]), (LAS unsigned*)(lds + (bufoff) + ldsw + _i * 8192), 16, 0, 0); } while (0)
; #define PG8_LDA(dst, b, h) do { _Pragma("unroll") for (int m = 0; m < 4; ++m) _Pragma("unroll") for (int k = 0; k < 2; ++k) dst[m][k] = *(const LAS bf16x8*)(pA + PG8_SA(b, h) + m * 2048 + k * 1024); } while (0)
; #define PG8_LDB(dst, b, h) do { _Pragma("unroll") for (int n = 0; n < 2; ++n) _Pragma("unroll") for (int k = 0; k < 2; ++k) dst[n][k] = *(const LAS bf16x8*)(pB + (PG8_SB(b, h) - 4 * HTB) + n * 2048 + k * 1024); } while (0)
; #define PG8_MMA(ai, bj, At, Bt) do { __builtin_amdgcn_s_setprio(1); _Pragma("unroll") for (int m = 0; m < 4; ++m) _Pragma("unroll") for (int n = 0; n < 2; ++n) _Pragma("unroll") for (int k = 0; k < 2; ++k) \
;         acc[ai][bj][m][n] = __builtin_amdgcn_mfma_f32_16x16x32_bf16(Bt[n][k], At[m][k], acc[ai][bj][m][n], 0, 0, 0); __builtin_amdgcn_s_setprio(0); } while (0)
; #define PG8_WAIT_V(n) asm volatile("s_waitcnt vmcnt(" #n ")" ::: "memory")
; #define PG8_BAR __builtin_amdgcn_s_barrier()
; template <class Desc, class Epi, bool ALIGN_EPI>
; __device__ __forceinline__ void gemm_phase(LAS unsigned char* lds, const Desc& D, const Epi& E, int G, int c) {
;     ...
;             PG8_LDB(B0, 0, 0); PG8_LDB(B1, 0, 1); PG8_SCHED; PG8_LDA(At, 0, 0); PG8_STAGE(PG8_SA(1, 1), a1 + hstepA, voffA);
;             PG8_WAIT_V(8); PG8_WAIT_L(0); PG8_BAR; PG8_MMA(0, 0, At, B0); PG8_MMA(0, 1, At, B1); PG8_BAR; PG8_SCHED;
;             PG8_LDA(At, 0, 1); PG8_STAGE(PG8_SB(0, 0), b2, voffB); PG8_STAGE(PG8_SB(0, 1), b2 + hstepB, voffB); PG8_STAGE(PG8_SA(0, 0), a2, voffA);
;             PG8_WAIT_V(8); PG8_WAIT_L(0); PG8_BAR; PG8_MMA(1, 0, At, B0); PG8_MMA(1, 1, At, B1); PG8_BAR; PG8_SCHED;
;             PG8_LDB(B0, 1, 0); PG8_LDB(B1, 1, 1); PG8_SCHED; PG8_LDA(At, 1, 0); PG8_STAGE(PG8_SA(0, 1), a2 + hstepA, voffA);
;             PG8_WAIT_V(8); PG8_WAIT_L(0); PG8_BAR; PG8_MMA(0, 0, At, B0); PG8_MMA(0, 1, At, B1); PG8_BAR; PG8_SCHED;
;             PG8_LDA(At, 1, 1); PG8_STAGE(PG8_SB(1, 0), b3, voffB); PG8_STAGE(PG8_SB(1, 1), b3 + hstepB, voffB); PG8_STAGE(PG8_SA(1, 0), a3, voffA);
;             PG8_WAIT_V(8); PG8_WAIT_L(0); PG8_BAR; PG8_MMA(1, 0, At, B0); PG8_MMA(1, 1, At, B1); PG8_BAR; PG8_SCHED;
.LBB0_1479:
	ds_read_b128 v[116:119], v225
	ds_read_b128 v[128:131], v225 offset:1024
	ds_read_b128 v[132:135], v225 offset:2048
	ds_read_b128 v[136:139], v225 offset:3072
	ds_read_b128 v[140:143], v225 offset:16384
	ds_read_b128 v[144:147], v225 offset:17408
	ds_read_b128 v[148:151], v225 offset:18432
	ds_read_b128 v[152:155], v225 offset:19456
	s_add_u32 s12, s0, 0xfffe0080
	s_addc_u32 s13, s1, -1
	s_cmp_eq_u32 s52, 4
	s_cselect_b32 s17, s37, s13
	s_cselect_b32 s16, s36, s12
	s_cselect_b32 s13, s21, s33
	s_cselect_b32 s12, s24, s27
	v_lshl_add_u64 v[208:209], s[0:1], 0, v[200:201]
	s_add_i32 m0, s31, 0xc000
	ds_read_b128 v[164:167], v224
	ds_read_b128 v[168:171], v224 offset:1024
	ds_read_b128 v[172:175], v224 offset:2048
	ds_read_b128 v[176:179], v224 offset:3072
	ds_read_b128 v[180:183], v224 offset:4096
	ds_read_b128 v[184:187], v224 offset:5120
	ds_read_b128 v[188:191], v224 offset:6144
	ds_read_b128 v[204:207], v224 offset:7168
	global_load_lds_dwordx4 v[208:209], off
	v_lshl_add_u64 v[208:209], s[0:1], 0, v[202:203]
	s_add_i32 m0, s31, 0xe000
	s_nop 0
	global_load_lds_dwordx4 v[208:209], off
	s_waitcnt vmcnt(8)
	s_waitcnt lgkmcnt(0)
	s_setprio 0
	s_barrier
	v_mfma_f32_16x16x32_bf16 v[160:163], v[116:119], v[164:167], v[160:163]
	v_mfma_f32_16x16x32_bf16 v[156:159], v[132:135], v[164:167], v[156:159]
	v_mfma_f32_16x16x32_bf16 v[112:115], v[116:119], v[172:175], v[112:115]
	v_mfma_f32_16x16x32_bf16 v[108:111], v[132:135], v[172:175], v[108:111]
	v_mfma_f32_16x16x32_bf16 v[96:99], v[116:119], v[180:183], v[96:99]
	v_mfma_f32_16x16x32_bf16 v[92:95], v[132:135], v[180:183], v[92:95]
	v_mfma_f32_16x16x32_bf16 v[80:83], v[116:119], v[188:191], v[80:83]
	v_mfma_f32_16x16x32_bf16 v[76:79], v[132:135], v[188:191], v[76:79]
	v_mfma_f32_16x16x32_bf16 v[160:163], v[128:131], v[168:171], v[160:163]
	v_mfma_f32_16x16x32_bf16 v[156:159], v[136:139], v[168:171], v[156:159]
	v_mfma_f32_16x16x32_bf16 v[112:115], v[128:131], v[176:179], v[112:115]
	v_mfma_f32_16x16x32_bf16 v[108:111], v[136:139], v[176:179], v[108:111]
	v_mfma_f32_16x16x32_bf16 v[96:99], v[128:131], v[184:187], v[96:99]
	v_mfma_f32_16x16x32_bf16 v[92:95], v[136:139], v[184:187], v[92:95]
	v_mfma_f32_16x16x32_bf16 v[80:83], v[128:131], v[204:207], v[80:83]
	v_mfma_f32_16x16x32_bf16 v[76:79], v[136:139], v[204:207], v[76:79]
	v_mfma_f32_16x16x32_bf16 v[124:127], v[140:143], v[164:167], v[124:127]
	v_mfma_f32_16x16x32_bf16 v[120:123], v[148:151], v[164:167], v[120:123]
	v_mfma_f32_16x16x32_bf16 v[104:107], v[140:143], v[172:175], v[104:107]
	v_mfma_f32_16x16x32_bf16 v[100:103], v[148:151], v[172:175], v[100:103]
	v_mfma_f32_16x16x32_bf16 v[88:91], v[140:143], v[180:183], v[88:91]
	v_mfma_f32_16x16x32_bf16 v[84:87], v[148:151], v[180:183], v[84:87]
	v_mfma_f32_16x16x32_bf16 v[72:75], v[140:143], v[188:191], v[72:75]
	v_mfma_f32_16x16x32_bf16 v[68:71], v[148:151], v[188:191], v[68:71]
	v_mfma_f32_16x16x32_bf16 v[124:127], v[144:147], v[168:171], v[124:127]
	v_mfma_f32_16x16x32_bf16 v[120:123], v[152:155], v[168:171], v[120:123]
	v_mfma_f32_16x16x32_bf16 v[104:107], v[144:147], v[176:179], v[104:107]
	v_mfma_f32_16x16x32_bf16 v[100:103], v[152:155], v[176:179], v[100:103]
	v_mfma_f32_16x16x32_bf16 v[88:91], v[144:147], v[184:187], v[88:91]
	v_mfma_f32_16x16x32_bf16 v[84:87], v[152:155], v[184:187], v[84:87]
	v_mfma_f32_16x16x32_bf16 v[72:75], v[144:147], v[204:207], v[72:75]
	v_mfma_f32_16x16x32_bf16 v[68:71], v[152:155], v[204:207], v[68:71]
	s_barrier
	s_setprio 1
	s_mov_b32 m0, s34
	v_lshl_add_u64 v[208:209], s[12:13], 0, v[196:197]
	s_add_u32 s54, s12, 0x20000
	ds_read_b128 v[164:167], v224 offset:16384
	ds_read_b128 v[168:171], v224 offset:17408
	ds_read_b128 v[172:175], v224 offset:18432
	ds_read_b128 v[176:179], v224 offset:19456
	ds_read_b128 v[180:183], v224 offset:20480
	ds_read_b128 v[184:187], v224 offset:21504
	ds_read_b128 v[188:191], v224 offset:22528
	ds_read_b128 v[204:207], v224 offset:23552
	global_load_lds_dwordx4 v[208:209], off
	v_lshl_add_u64 v[210:211], s[12:13], 0, v[192:193]
	s_mov_b32 m0, s35
	s_addc_u32 s55, s13, 0
	global_load_lds_dwordx4 v[210:211], off
	v_lshl_add_u64 v[212:213], s[54:55], 0, v[196:197]
	s_mov_b32 m0, s40
	v_lshl_add_u64 v[214:215], s[16:17], 0, v[194:195]
	global_load_lds_dwordx4 v[212:213], off
	v_lshl_add_u64 v[212:213], s[54:55], 0, v[192:193]
	s_mov_b32 m0, s41
	s_nop 0
	global_load_lds_dwordx4 v[212:213], off
	v_lshl_add_u64 v[212:213], s[16:17], 0, v[198:199]
	s_mov_b32 m0, s31
	s_nop 0
	global_load_lds_dwordx4 v[212:213], off
	s_mov_b32 m0, s42
	s_nop 0
	global_load_lds_dwordx4 v[214:215], off
	s_waitcnt vmcnt(8)
	s_waitcnt lgkmcnt(0)
	s_setprio 0
	s_barrier
; #define PG8_STAGE(bufoff, gbase, voff) do { _Pragma("unroll") for (int _i = 0; _i < 2; ++_i) \
;         __builtin_amdgcn_global_load_lds((const unsigned*)((const char*)(gbase) + (voff)[_i]), (LAS unsigned*)(lds + (bufoff) + ldsw + _i * 8192), 16, 0, 0); } while (0)
; #define PG8_LDA(dst, b, h) do { _Pragma("unroll") for (int m = 0; m < 4; ++m) _Pragma("unroll") for (int k = 0; k < 2; ++k) dst[m][k] = *(const LAS bf16x8*)(pA + PG8_SA(b, h) + m * 2048 + k * 1024); } while (0)
; #define PG8_LDB(dst, b, h) do { _Pragma("unroll") for (int n = 0; n < 2; ++n) _Pragma("unroll") for (int k = 0; k < 2; ++k) dst[n][k] = *(const LAS bf16x8*)(pB + (PG8_SB(b, h) - 4 * HTB) + n * 2048 + k * 1024); } while (0)
; #define PG8_MMA(ai, bj, At, Bt) do { __builtin_amdgcn_s_setprio(1); _Pragma("unroll") for (int m = 0; m < 4; ++m) _Pragma("unroll") for (int n = 0; n < 2; ++n) _Pragma("unroll") for (int k = 0; k < 2; ++k) \
;         acc[ai][bj][m][n] = __builtin_amdgcn_mfma_f32_16x16x32_bf16(Bt[n][k], At[m][k], acc[ai][bj][m][n], 0, 0, 0); __builtin_amdgcn_s_setprio(0); } while (0)
; #define PG8_WAIT_V(n) asm volatile("s_waitcnt vmcnt(" #n ")" ::: "memory")
; #define PG8_WAIT_L(n) asm volatile("s_waitcnt lgkmcnt(" #n ")" ::: "memory")
; #define PG8_BAR __builtin_amdgcn_s_barrier()
; #define PG8_SCHED __builtin_amdgcn_sched_barrier(0)
; template <class Desc, class Epi, bool ALIGN_EPI>
; __device__ __forceinline__ void gemm_phase(LAS unsigned char* lds, const Desc& D, const Epi& E, int G, int c) {
;     ...
;             PG8_LDA(At, 0, 1); PG8_STAGE(PG8_SB(0, 0), b2, voffB); PG8_STAGE(PG8_SB(0, 1), b2 + hstepB, voffB); PG8_STAGE(PG8_SA(0, 0), a2, voffA);
;             PG8_WAIT_V(8); PG8_WAIT_L(0); PG8_BAR; PG8_MMA(1, 0, At, B0); PG8_MMA(1, 1, At, B1); PG8_BAR; PG8_SCHED;
;             PG8_LDB(B0, 1, 0); PG8_LDB(B1, 1, 1); PG8_SCHED; PG8_LDA(At, 1, 0); PG8_STAGE(PG8_SA(0, 1), a2 + hstepA, voffA);
;             PG8_WAIT_V(8); PG8_WAIT_L(0); PG8_BAR; PG8_MMA(0, 0, At, B0); PG8_MMA(0, 1, At, B1); PG8_BAR; PG8_SCHED;
	v_mfma_f32_16x16x32_bf16 v[64:67], v[116:119], v[164:167], v[64:67]
	v_mfma_f32_16x16x32_bf16 v[60:63], v[132:135], v[164:167], v[60:63]
	v_mfma_f32_16x16x32_bf16 v[48:51], v[116:119], v[172:175], v[48:51]
	v_mfma_f32_16x16x32_bf16 v[44:47], v[132:135], v[172:175], v[44:47]
	v_mfma_f32_16x16x32_bf16 v[32:35], v[116:119], v[180:183], v[32:35]
	v_mfma_f32_16x16x32_bf16 v[28:31], v[132:135], v[180:183], v[28:31]
	v_mfma_f32_16x16x32_bf16 v[16:19], v[116:119], v[188:191], v[16:19]
	v_mfma_f32_16x16x32_bf16 v[12:15], v[132:135], v[188:191], v[12:15]
	v_mfma_f32_16x16x32_bf16 v[64:67], v[128:131], v[168:171], v[64:67]
	v_mfma_f32_16x16x32_bf16 v[60:63], v[136:139], v[168:171], v[60:63]
	v_mfma_f32_16x16x32_bf16 v[48:51], v[128:131], v[176:179], v[48:51]
	v_mfma_f32_16x16x32_bf16 v[44:47], v[136:139], v[176:179], v[44:47]
	v_mfma_f32_16x16x32_bf16 v[32:35], v[128:131], v[184:187], v[32:35]
	v_mfma_f32_16x16x32_bf16 v[28:31], v[136:139], v[184:187], v[28:31]
	v_mfma_f32_16x16x32_bf16 v[16:19], v[128:131], v[204:207], v[16:19]
	v_mfma_f32_16x16x32_bf16 v[12:15], v[136:139], v[204:207], v[12:15]
	v_mfma_f32_16x16x32_bf16 v[56:59], v[140:143], v[164:167], v[56:59]
	v_mfma_f32_16x16x32_bf16 v[52:55], v[148:151], v[164:167], v[52:55]
	v_mfma_f32_16x16x32_bf16 v[40:43], v[140:143], v[172:175], v[40:43]
	v_mfma_f32_16x16x32_bf16 v[36:39], v[148:151], v[172:175], v[36:39]
	v_mfma_f32_16x16x32_bf16 v[24:27], v[140:143], v[180:183], v[24:27]
	v_mfma_f32_16x16x32_bf16 v[20:23], v[148:151], v[180:183], v[20:23]
	v_mfma_f32_16x16x32_bf16 v[8:11], v[140:143], v[188:191], v[8:11]
	v_mfma_f32_16x16x32_bf16 v[4:7], v[148:151], v[188:191], v[4:7]
	v_mfma_f32_16x16x32_bf16 v[56:59], v[144:147], v[168:171], v[56:59]
	v_mfma_f32_16x16x32_bf16 v[52:55], v[152:155], v[168:171], v[52:55]
	v_mfma_f32_16x16x32_bf16 v[40:43], v[144:147], v[176:179], v[40:43]
	v_mfma_f32_16x16x32_bf16 v[36:39], v[152:155], v[176:179], v[36:39]
	v_mfma_f32_16x16x32_bf16 v[24:27], v[144:147], v[184:187], v[24:27]
	v_mfma_f32_16x16x32_bf16 v[20:23], v[152:155], v[184:187], v[20:23]
	v_mfma_f32_16x16x32_bf16 v[8:11], v[144:147], v[204:207], v[8:11]
	v_mfma_f32_16x16x32_bf16 v[4:7], v[152:155], v[204:207], v[4:7]
	s_barrier
	s_setprio 1
	ds_read_b128 v[116:119], v225 offset:32768
	ds_read_b128 v[128:131], v225 offset:33792
	ds_read_b128 v[132:135], v225 offset:34816
	ds_read_b128 v[136:139], v225 offset:35840
	ds_read_b128 v[140:143], v225 offset:49152
	ds_read_b128 v[144:147], v225 offset:50176
	ds_read_b128 v[148:151], v225 offset:51200
	ds_read_b128 v[152:155], v225 offset:52224
	s_add_u32 s16, s16, 0x20000
	s_addc_u32 s17, s17, 0
	s_mov_b32 m0, s43
	v_lshl_add_u64 v[216:217], s[16:17], 0, v[198:199]
	ds_read_b128 v[164:167], v224 offset:32768
	ds_read_b128 v[168:171], v224 offset:33792
	ds_read_b128 v[172:175], v224 offset:34816
	ds_read_b128 v[176:179], v224 offset:35840
	ds_read_b128 v[180:183], v224 offset:36864
	ds_read_b128 v[184:187], v224 offset:37888
	ds_read_b128 v[188:191], v224 offset:38912
	ds_read_b128 v[204:207], v224 offset:39936
	global_load_lds_dwordx4 v[216:217], off
	v_lshl_add_u64 v[216:217], s[16:17], 0, v[194:195]
	s_mov_b32 m0, s44
	s_nop 0
	global_load_lds_dwordx4 v[216:217], off
	s_waitcnt vmcnt(8)
	s_waitcnt lgkmcnt(0)
	s_setprio 0
	s_barrier
	v_mfma_f32_16x16x32_bf16 v[160:163], v[116:119], v[164:167], v[160:163]
	v_mfma_f32_16x16x32_bf16 v[156:159], v[132:135], v[164:167], v[156:159]
	v_mfma_f32_16x16x32_bf16 v[112:115], v[116:119], v[172:175], v[112:115]
	v_mfma_f32_16x16x32_bf16 v[108:111], v[132:135], v[172:175], v[108:111]
	v_mfma_f32_16x16x32_bf16 v[96:99], v[116:119], v[180:183], v[96:99]
	v_mfma_f32_16x16x32_bf16 v[92:95], v[132:135], v[180:183], v[92:95]
	v_mfma_f32_16x16x32_bf16 v[80:83], v[116:119], v[188:191], v[80:83]
	v_mfma_f32_16x16x32_bf16 v[76:79], v[132:135], v[188:191], v[76:79]
	v_mfma_f32_16x16x32_bf16 v[160:163], v[128:131], v[168:171], v[160:163]
	v_mfma_f32_16x16x32_bf16 v[156:159], v[136:139], v[168:171], v[156:159]
	v_mfma_f32_16x16x32_bf16 v[112:115], v[128:131], v[176:179], v[112:115]
	v_mfma_f32_16x16x32_bf16 v[108:111], v[136:139], v[176:179], v[108:111]
	v_mfma_f32_16x16x32_bf16 v[96:99], v[128:131], v[184:187], v[96:99]
	v_mfma_f32_16x16x32_bf16 v[92:95], v[136:139], v[184:187], v[92:95]
	v_mfma_f32_16x16x32_bf16 v[80:83], v[128:131], v[204:207], v[80:83]
	v_mfma_f32_16x16x32_bf16 v[76:79], v[136:139], v[204:207], v[76:79]
	v_mfma_f32_16x16x32_bf16 v[124:127], v[140:143], v[164:167], v[124:127]
	v_mfma_f32_16x16x32_bf16 v[120:123], v[148:151], v[164:167], v[120:123]
	v_mfma_f32_16x16x32_bf16 v[104:107], v[140:143], v[172:175], v[104:107]
	v_mfma_f32_16x16x32_bf16 v[100:103], v[148:151], v[172:175], v[100:103]
	v_mfma_f32_16x16x32_bf16 v[88:91], v[140:143], v[180:183], v[88:91]
	v_mfma_f32_16x16x32_bf16 v[84:87], v[148:151], v[180:183], v[84:87]
	v_mfma_f32_16x16x32_bf16 v[72:75], v[140:143], v[188:191], v[72:75]
	v_mfma_f32_16x16x32_bf16 v[68:71], v[148:151], v[188:191], v[68:71]
	v_mfma_f32_16x16x32_bf16 v[124:127], v[144:147], v[168:171], v[124:127]
	v_mfma_f32_16x16x32_bf16 v[120:123], v[152:155], v[168:171], v[120:123]
	v_mfma_f32_16x16x32_bf16 v[104:107], v[144:147], v[176:179], v[104:107]
	v_mfma_f32_16x16x32_bf16 v[100:103], v[152:155], v[176:179], v[100:103]
	v_mfma_f32_16x16x32_bf16 v[88:91], v[144:147], v[184:187], v[88:91]
	v_mfma_f32_16x16x32_bf16 v[84:87], v[152:155], v[184:187], v[84:87]
	v_mfma_f32_16x16x32_bf16 v[72:75], v[144:147], v[204:207], v[72:75]
	v_mfma_f32_16x16x32_bf16 v[68:71], v[152:155], v[204:207], v[68:71]
	s_barrier
; #define PG8_STAGE(bufoff, gbase, voff) do { _Pragma("unroll") for (int _i = 0; _i < 2; ++_i) \
;         __builtin_amdgcn_global_load_lds((const unsigned*)((const char*)(gbase) + (voff)[_i]), (LAS unsigned*)(lds + (bufoff) + ldsw + _i * 8192), 16, 0, 0); } while (0)
; #define PG8_LDA(dst, b, h) do { _Pragma("unroll") for (int m = 0; m < 4; ++m) _Pragma("unroll") for (int k = 0; k < 2; ++k) dst[m][k] = *(const LAS bf16x8*)(pA + PG8_SA(b, h) + m * 2048 + k * 1024); } while (0)
; #define PG8_MMA(ai, bj, At, Bt) do { __builtin_amdgcn_s_setprio(1); _Pragma("unroll") for (int m = 0; m < 4; ++m) _Pragma("unroll") for (int n = 0; n < 2; ++n) _Pragma("unroll") for (int k = 0; k < 2; ++k) \
;         acc[ai][bj][m][n] = __builtin_amdgcn_mfma_f32_16x16x32_bf16(Bt[n][k], At[m][k], acc[ai][bj][m][n], 0, 0, 0); __builtin_amdgcn_s_setprio(0); } while (0)
; #define PG8_WAIT_V(n) asm volatile("s_waitcnt vmcnt(" #n ")" ::: "memory")
; #define PG8_WAIT_L(n) asm volatile("s_waitcnt lgkmcnt(" #n ")" ::: "memory")
; #define PG8_BAR __builtin_amdgcn_s_barrier()
; #define PG8_SCHED __builtin_amdgcn_sched_barrier(0)
; template <class Desc, class Epi, bool ALIGN_EPI>
; __device__ __forceinline__ void gemm_phase(LAS unsigned char* lds, const Desc& D, const Epi& E, int G, int c) {
;     ...
;             PG8_LDA(At, 1, 1); PG8_STAGE(PG8_SB(1, 0), b3, voffB); PG8_STAGE(PG8_SB(1, 1), b3 + hstepB, voffB); PG8_STAGE(PG8_SA(1, 0), a3, voffA);
;             PG8_WAIT_V(8); PG8_WAIT_L(0); PG8_BAR; PG8_MMA(1, 0, At, B0); PG8_MMA(1, 1, At, B1); PG8_BAR; PG8_SCHED;
;         }
	s_setprio 1
	s_mov_b32 m0, s45
	v_lshl_add_u64 v[208:209], v[208:209], 0, s[76:77]
	s_add_u32 s12, s12, 0x20080
	ds_read_b128 v[164:167], v224 offset:49152
	ds_read_b128 v[168:171], v224 offset:50176
	ds_read_b128 v[172:175], v224 offset:51200
	ds_read_b128 v[176:179], v224 offset:52224
	ds_read_b128 v[180:183], v224 offset:53248
	ds_read_b128 v[184:187], v224 offset:54272
	ds_read_b128 v[188:191], v224 offset:55296
	ds_read_b128 v[204:207], v224 offset:56320
	global_load_lds_dwordx4 v[208:209], off
	v_lshl_add_u64 v[208:209], v[210:211], 0, s[76:77]
	s_mov_b32 m0, s46
	s_addc_u32 s13, s13, 0
	global_load_lds_dwordx4 v[208:209], off
	v_lshl_add_u64 v[208:209], s[12:13], 0, v[196:197]
	s_mov_b32 m0, s49
	s_nop 0
	global_load_lds_dwordx4 v[208:209], off
	v_lshl_add_u64 v[208:209], s[12:13], 0, v[192:193]
	s_mov_b32 m0, s50
	s_nop 0
	global_load_lds_dwordx4 v[208:209], off
	v_lshl_add_u64 v[208:209], v[212:213], 0, s[76:77]
	s_mov_b32 m0, s47
	s_nop 0
	global_load_lds_dwordx4 v[208:209], off
	v_lshl_add_u64 v[208:209], v[214:215], 0, s[76:77]
	s_mov_b32 m0, s48
	s_nop 0
	global_load_lds_dwordx4 v[208:209], off
	s_waitcnt vmcnt(8)
	s_waitcnt lgkmcnt(0)
	s_setprio 0
	s_barrier
	v_mfma_f32_16x16x32_bf16 v[64:67], v[116:119], v[164:167], v[64:67]
	v_mfma_f32_16x16x32_bf16 v[60:63], v[132:135], v[164:167], v[60:63]
	v_mfma_f32_16x16x32_bf16 v[48:51], v[116:119], v[172:175], v[48:51]
	v_mfma_f32_16x16x32_bf16 v[44:47], v[132:135], v[172:175], v[44:47]
	v_mfma_f32_16x16x32_bf16 v[32:35], v[116:119], v[180:183], v[32:35]
	v_mfma_f32_16x16x32_bf16 v[28:31], v[132:135], v[180:183], v[28:31]
	v_mfma_f32_16x16x32_bf16 v[16:19], v[116:119], v[188:191], v[16:19]
	v_mfma_f32_16x16x32_bf16 v[12:15], v[132:135], v[188:191], v[12:15]
	v_mfma_f32_16x16x32_bf16 v[64:67], v[128:131], v[168:171], v[64:67]
	v_mfma_f32_16x16x32_bf16 v[60:63], v[136:139], v[168:171], v[60:63]
	v_mfma_f32_16x16x32_bf16 v[48:51], v[128:131], v[176:179], v[48:51]
	v_mfma_f32_16x16x32_bf16 v[44:47], v[136:139], v[176:179], v[44:47]
	v_mfma_f32_16x16x32_bf16 v[32:35], v[128:131], v[184:187], v[32:35]
	v_mfma_f32_16x16x32_bf16 v[28:31], v[136:139], v[184:187], v[28:31]
	v_mfma_f32_16x16x32_bf16 v[16:19], v[128:131], v[204:207], v[16:19]
	v_mfma_f32_16x16x32_bf16 v[12:15], v[136:139], v[204:207], v[12:15]
	v_mfma_f32_16x16x32_bf16 v[56:59], v[140:143], v[164:167], v[56:59]
	v_mfma_f32_16x16x32_bf16 v[52:55], v[148:151], v[164:167], v[52:55]
	v_mfma_f32_16x16x32_bf16 v[40:43], v[140:143], v[172:175], v[40:43]
	v_mfma_f32_16x16x32_bf16 v[36:39], v[148:151], v[172:175], v[36:39]
	v_mfma_f32_16x16x32_bf16 v[24:27], v[140:143], v[180:183], v[24:27]
	v_mfma_f32_16x16x32_bf16 v[20:23], v[148:151], v[180:183], v[20:23]
	v_mfma_f32_16x16x32_bf16 v[8:11], v[140:143], v[188:191], v[8:11]
	v_mfma_f32_16x16x32_bf16 v[4:7], v[148:151], v[188:191], v[4:7]
	v_mfma_f32_16x16x32_bf16 v[56:59], v[144:147], v[168:171], v[56:59]
	v_mfma_f32_16x16x32_bf16 v[52:55], v[152:155], v[168:171], v[52:55]
	v_mfma_f32_16x16x32_bf16 v[40:43], v[144:147], v[176:179], v[40:43]
	v_mfma_f32_16x16x32_bf16 v[36:39], v[152:155], v[176:179], v[36:39]
	v_mfma_f32_16x16x32_bf16 v[24:27], v[144:147], v[184:187], v[24:27]
	v_mfma_f32_16x16x32_bf16 v[20:23], v[152:155], v[184:187], v[20:23]
	v_mfma_f32_16x16x32_bf16 v[8:11], v[144:147], v[204:207], v[8:11]
	v_mfma_f32_16x16x32_bf16 v[4:7], v[152:155], v[204:207], v[4:7]
	s_barrier
	s_setprio 1
	s_add_i32 s52, s52, 2
	s_add_u32 s0, s0, 0x100
	s_addc_u32 s1, s1, 0
	s_add_u32 s27, s27, 0x100
	s_addc_u32 s33, s33, 0
	s_cmp_gt_u32 s52, 5
	s_cbranch_scc0 .LBB0_1479
	s_and_b64 vcc, exec, s[8:9]
	s_cbranch_vccz .LBB0_1482
	s_barrier

; #define PG8_STAGE(bufoff, gbase, voff) do { _Pragma("unroll") for (int _i = 0; _i < 2; ++_i) \
;         __builtin_amdgcn_global_load_lds((const unsigned*)((const char*)(gbase) + (voff)[_i]), (LAS unsigned*)(lds + (bufoff) + ldsw + _i * 8192), 16, 0, 0); } while (0)
; #define PG8_LDA(dst, b, h) do { _Pragma("unroll") for (int m = 0; m < 4; ++m) _Pragma("unroll") for (int k = 0; k < 2; ++k) dst[m][k] = *(const LAS bf16x8*)(pA + PG8_SA(b, h) + m * 2048 + k * 1024); } while (0)
; #define PG8_LDB(dst, b, h) do { _Pragma("unroll") for (int n = 0; n < 2; ++n) _Pragma("unroll") for (int k = 0; k < 2; ++k) dst[n][k] = *(const LAS bf16x8*)(pB + (PG8_SB(b, h) - 4 * HTB) + n * 2048 + k * 1024); } while (0)
; #define PG8_MMA(ai, bj, At, Bt) do { __builtin_amdgcn_s_setprio(1); _Pragma("unroll") for (int m = 0; m < 4; ++m) _Pragma("unroll") for (int n = 0; n < 2; ++n) _Pragma("unroll") for (int k = 0; k < 2; ++k) \
;         acc[ai][bj][m][n] = __builtin_amdgcn_mfma_f32_16x16x32_bf16(Bt[n][k], At[m][k], acc[ai][bj][m][n], 0, 0, 0); __builtin_amdgcn_s_setprio(0); } while (0)
; #define PG8_WAIT_V(n) asm volatile("s_waitcnt vmcnt(" #n ")" ::: "memory")
; #define PG8_BAR __builtin_amdgcn_s_barrier()
; template <class Desc, class Epi, bool ALIGN_EPI>
; __device__ __forceinline__ void gemm_phase(LAS unsigned char* lds, const Desc& D, const Epi& E, int G, int c) {
;     ...
;             PG8_LDB(B0, 0, 0); PG8_LDB(B1, 0, 1); PG8_SCHED; PG8_LDA(At, 0, 0); PG8_STAGE(PG8_SA(1, 1), a1 + hstepA, voffA);
;             PG8_WAIT_V(8); PG8_WAIT_L(0); PG8_BAR; PG8_MMA(0, 0, At, B0); PG8_MMA(0, 1, At, B1); PG8_BAR; PG8_SCHED;
;             PG8_LDA(At, 0, 1); PG8_STAGE(PG8_SB(0, 0), b2, voffB); PG8_STAGE(PG8_SB(0, 1), b2 + hstepB, voffB); PG8_STAGE(PG8_SA(0, 0), a2, voffA);
;             PG8_WAIT_V(8); PG8_WAIT_L(0); PG8_BAR; PG8_MMA(1, 0, At, B0); PG8_MMA(1, 1, At, B1); PG8_BAR; PG8_SCHED;
;             PG8_LDB(B0, 1, 0); PG8_LDB(B1, 1, 1); PG8_SCHED; PG8_LDA(At, 1, 0); PG8_STAGE(PG8_SA(0, 1), a2 + hstepA, voffA);
;             PG8_WAIT_V(8); PG8_WAIT_L(0); PG8_BAR; PG8_MMA(0, 0, At, B0); PG8_MMA(0, 1, At, B1); PG8_BAR; PG8_SCHED;
;             PG8_LDA(At, 1, 1); PG8_STAGE(PG8_SB(1, 0), b3, voffB); PG8_STAGE(PG8_SB(1, 1), b3 + hstepB, voffB); PG8_STAGE(PG8_SA(1, 0), a3, voffA);
;             PG8_WAIT_V(8); PG8_WAIT_L(0); PG8_BAR; PG8_MMA(1, 0, At, B0); PG8_MMA(1, 1, At, B1); PG8_BAR; PG8_SCHED;
.LBB0_1517:
	ds_read_b128 v[116:119], v225
	ds_read_b128 v[128:131], v225 offset:1024
	ds_read_b128 v[132:135], v225 offset:2048
	ds_read_b128 v[136:139], v225 offset:3072
	ds_read_b128 v[140:143], v225 offset:16384
	ds_read_b128 v[144:147], v225 offset:17408
	ds_read_b128 v[148:151], v225 offset:18432
	ds_read_b128 v[152:155], v225 offset:19456
	s_add_u32 s12, s0, 0xfffe0080
	s_addc_u32 s13, s1, -1
	s_cmp_eq_u32 s54, 4
	s_cselect_b32 s17, s37, s13
	s_cselect_b32 s16, s36, s12
	s_cselect_b32 s13, s21, s33
	s_cselect_b32 s12, s24, s27
	v_lshl_add_u64 v[208:209], s[0:1], 0, v[200:201]
	s_add_i32 m0, s31, 0xc000
	ds_read_b128 v[164:167], v224
	ds_read_b128 v[168:171], v224 offset:1024
	ds_read_b128 v[172:175], v224 offset:2048
	ds_read_b128 v[176:179], v224 offset:3072
	ds_read_b128 v[180:183], v224 offset:4096
	ds_read_b128 v[184:187], v224 offset:5120
	ds_read_b128 v[188:191], v224 offset:6144
	ds_read_b128 v[204:207], v224 offset:7168
	global_load_lds_dwordx4 v[208:209], off
	v_lshl_add_u64 v[208:209], s[0:1], 0, v[202:203]
	s_add_i32 m0, s31, 0xe000
	s_nop 0
	global_load_lds_dwordx4 v[208:209], off
	s_waitcnt vmcnt(8)
	s_waitcnt lgkmcnt(0)
	s_setprio 0
	s_barrier
	v_mfma_f32_16x16x32_bf16 v[160:163], v[116:119], v[164:167], v[160:163]
	v_mfma_f32_16x16x32_bf16 v[156:159], v[132:135], v[164:167], v[156:159]
	v_mfma_f32_16x16x32_bf16 v[112:115], v[116:119], v[172:175], v[112:115]
	v_mfma_f32_16x16x32_bf16 v[108:111], v[132:135], v[172:175], v[108:111]
	v_mfma_f32_16x16x32_bf16 v[96:99], v[116:119], v[180:183], v[96:99]
	v_mfma_f32_16x16x32_bf16 v[92:95], v[132:135], v[180:183], v[92:95]
	v_mfma_f32_16x16x32_bf16 v[80:83], v[116:119], v[188:191], v[80:83]
	v_mfma_f32_16x16x32_bf16 v[76:79], v[132:135], v[188:191], v[76:79]
	v_mfma_f32_16x16x32_bf16 v[160:163], v[128:131], v[168:171], v[160:163]
	v_mfma_f32_16x16x32_bf16 v[156:159], v[136:139], v[168:171], v[156:159]
	v_mfma_f32_16x16x32_bf16 v[112:115], v[128:131], v[176:179], v[112:115]
	v_mfma_f32_16x16x32_bf16 v[108:111], v[136:139], v[176:179], v[108:111]
	v_mfma_f32_16x16x32_bf16 v[96:99], v[128:131], v[184:187], v[96:99]
	v_mfma_f32_16x16x32_bf16 v[92:95], v[136:139], v[184:187], v[92:95]
	v_mfma_f32_16x16x32_bf16 v[80:83], v[128:131], v[204:207], v[80:83]
	v_mfma_f32_16x16x32_bf16 v[76:79], v[136:139], v[204:207], v[76:79]
	v_mfma_f32_16x16x32_bf16 v[124:127], v[140:143], v[164:167], v[124:127]
	v_mfma_f32_16x16x32_bf16 v[120:123], v[148:151], v[164:167], v[120:123]
	v_mfma_f32_16x16x32_bf16 v[104:107], v[140:143], v[172:175], v[104:107]
	v_mfma_f32_16x16x32_bf16 v[100:103], v[148:151], v[172:175], v[100:103]
	v_mfma_f32_16x16x32_bf16 v[88:91], v[140:143], v[180:183], v[88:91]
	v_mfma_f32_16x16x32_bf16 v[84:87], v[148:151], v[180:183], v[84:87]
	v_mfma_f32_16x16x32_bf16 v[72:75], v[140:143], v[188:191], v[72:75]
	v_mfma_f32_16x16x32_bf16 v[68:71], v[148:151], v[188:191], v[68:71]
	v_mfma_f32_16x16x32_bf16 v[124:127], v[144:147], v[168:171], v[124:127]
	v_mfma_f32_16x16x32_bf16 v[120:123], v[152:155], v[168:171], v[120:123]
	v_mfma_f32_16x16x32_bf16 v[104:107], v[144:147], v[176:179], v[104:107]
	v_mfma_f32_16x16x32_bf16 v[100:103], v[152:155], v[176:179], v[100:103]
	v_mfma_f32_16x16x32_bf16 v[88:91], v[144:147], v[184:187], v[88:91]
	v_mfma_f32_16x16x32_bf16 v[84:87], v[152:155], v[184:187], v[84:87]
	v_mfma_f32_16x16x32_bf16 v[72:75], v[144:147], v[204:207], v[72:75]
	v_mfma_f32_16x16x32_bf16 v[68:71], v[152:155], v[204:207], v[68:71]
	s_barrier
	s_setprio 1
	s_mov_b32 m0, s34
	v_lshl_add_u64 v[208:209], s[12:13], 0, v[196:197]
	s_add_u32 s56, s12, 0x20000
	ds_read_b128 v[164:167], v224 offset:16384
	ds_read_b128 v[168:171], v224 offset:17408
	ds_read_b128 v[172:175], v224 offset:18432
	ds_read_b128 v[176:179], v224 offset:19456
	ds_read_b128 v[180:183], v224 offset:20480
	ds_read_b128 v[184:187], v224 offset:21504
	ds_read_b128 v[188:191], v224 offset:22528
	ds_read_b128 v[204:207], v224 offset:23552
	global_load_lds_dwordx4 v[208:209], off
	v_lshl_add_u64 v[210:211], s[12:13], 0, v[192:193]
	s_mov_b32 m0, s35
	s_addc_u32 s57, s13, 0
	global_load_lds_dwordx4 v[210:211], off
	v_lshl_add_u64 v[212:213], s[56:57], 0, v[196:197]
	s_mov_b32 m0, s42
	v_lshl_add_u64 v[214:215], s[16:17], 0, v[194:195]
	global_load_lds_dwordx4 v[212:213], off
	v_lshl_add_u64 v[212:213], s[56:57], 0, v[192:193]
	s_mov_b32 m0, s43
	s_nop 0
	global_load_lds_dwordx4 v[212:213], off
	v_lshl_add_u64 v[212:213], s[16:17], 0, v[198:199]
	s_mov_b32 m0, s31
	s_nop 0
	global_load_lds_dwordx4 v[212:213], off
	s_mov_b32 m0, s44
	s_nop 0
	global_load_lds_dwordx4 v[214:215], off
	s_waitcnt vmcnt(8)
	s_waitcnt lgkmcnt(0)
	s_setprio 0
	s_barrier
; #define PG8_STAGE(bufoff, gbase, voff) do { _Pragma("unroll") for (int _i = 0; _i < 2; ++_i) \
;         __builtin_amdgcn_global_load_lds((const unsigned*)((const char*)(gbase) + (voff)[_i]), (LAS unsigned*)(lds + (bufoff) + ldsw + _i * 8192), 16, 0, 0); } while (0)
; #define PG8_LDA(dst, b, h) do { _Pragma("unroll") for (int m = 0; m < 4; ++m) _Pragma("unroll") for (int k = 0; k < 2; ++k) dst[m][k] = *(const LAS bf16x8*)(pA + PG8_SA(b, h) + m * 2048 + k * 1024); } while (0)
; #define PG8_LDB(dst, b, h) do { _Pragma("unroll") for (int n = 0; n < 2; ++n) _Pragma("unroll") for (int k = 0; k < 2; ++k) dst[n][k] = *(const LAS bf16x8*)(pB + (PG8_SB(b, h) - 4 * HTB) + n * 2048 + k * 1024); } while (0)
; #define PG8_MMA(ai, bj, At, Bt) do { __builtin_amdgcn_s_setprio(1); _Pragma("unroll") for (int m = 0; m < 4; ++m) _Pragma("unroll") for (int n = 0; n < 2; ++n) _Pragma("unroll") for (int k = 0; k < 2; ++k) \
;         acc[ai][bj][m][n] = __builtin_amdgcn_mfma_f32_16x16x32_bf16(Bt[n][k], At[m][k], acc[ai][bj][m][n], 0, 0, 0); __builtin_amdgcn_s_setprio(0); } while (0)
; #define PG8_WAIT_V(n) asm volatile("s_waitcnt vmcnt(" #n ")" ::: "memory")
; #define PG8_WAIT_L(n) asm volatile("s_waitcnt lgkmcnt(" #n ")" ::: "memory")
; #define PG8_BAR __builtin_amdgcn_s_barrier()
; #define PG8_SCHED __builtin_amdgcn_sched_barrier(0)
; template <class Desc, class Epi, bool ALIGN_EPI>
; __device__ __forceinline__ void gemm_phase(LAS unsigned char* lds, const Desc& D, const Epi& E, int G, int c) {
;     ...
;             PG8_LDA(At, 0, 1); PG8_STAGE(PG8_SB(0, 0), b2, voffB); PG8_STAGE(PG8_SB(0, 1), b2 + hstepB, voffB); PG8_STAGE(PG8_SA(0, 0), a2, voffA);
;             PG8_WAIT_V(8); PG8_WAIT_L(0); PG8_BAR; PG8_MMA(1, 0, At, B0); PG8_MMA(1, 1, At, B1); PG8_BAR; PG8_SCHED;
;             PG8_LDB(B0, 1, 0); PG8_LDB(B1, 1, 1); PG8_SCHED; PG8_LDA(At, 1, 0); PG8_STAGE(PG8_SA(0, 1), a2 + hstepA, voffA);
;             PG8_WAIT_V(8); PG8_WAIT_L(0); PG8_BAR; PG8_MMA(0, 0, At, B0); PG8_MMA(0, 1, At, B1); PG8_BAR; PG8_SCHED;
	v_mfma_f32_16x16x32_bf16 v[64:67], v[116:119], v[164:167], v[64:67]
	v_mfma_f32_16x16x32_bf16 v[60:63], v[132:135], v[164:167], v[60:63]
	v_mfma_f32_16x16x32_bf16 v[48:51], v[116:119], v[172:175], v[48:51]
	v_mfma_f32_16x16x32_bf16 v[44:47], v[132:135], v[172:175], v[44:47]
	v_mfma_f32_16x16x32_bf16 v[32:35], v[116:119], v[180:183], v[32:35]
	v_mfma_f32_16x16x32_bf16 v[28:31], v[132:135], v[180:183], v[28:31]
	v_mfma_f32_16x16x32_bf16 v[16:19], v[116:119], v[188:191], v[16:19]
	v_mfma_f32_16x16x32_bf16 v[12:15], v[132:135], v[188:191], v[12:15]
	v_mfma_f32_16x16x32_bf16 v[64:67], v[128:131], v[168:171], v[64:67]
	v_mfma_f32_16x16x32_bf16 v[60:63], v[136:139], v[168:171], v[60:63]
	v_mfma_f32_16x16x32_bf16 v[48:51], v[128:131], v[176:179], v[48:51]
	v_mfma_f32_16x16x32_bf16 v[44:47], v[136:139], v[176:179], v[44:47]
	v_mfma_f32_16x16x32_bf16 v[32:35], v[128:131], v[184:187], v[32:35]
	v_mfma_f32_16x16x32_bf16 v[28:31], v[136:139], v[184:187], v[28:31]
	v_mfma_f32_16x16x32_bf16 v[16:19], v[128:131], v[204:207], v[16:19]
	v_mfma_f32_16x16x32_bf16 v[12:15], v[136:139], v[204:207], v[12:15]
	v_mfma_f32_16x16x32_bf16 v[56:59], v[140:143], v[164:167], v[56:59]
	v_mfma_f32_16x16x32_bf16 v[52:55], v[148:151], v[164:167], v[52:55]
	v_mfma_f32_16x16x32_bf16 v[40:43], v[140:143], v[172:175], v[40:43]
	v_mfma_f32_16x16x32_bf16 v[36:39], v[148:151], v[172:175], v[36:39]
	v_mfma_f32_16x16x32_bf16 v[24:27], v[140:143], v[180:183], v[24:27]
	v_mfma_f32_16x16x32_bf16 v[20:23], v[148:151], v[180:183], v[20:23]
	v_mfma_f32_16x16x32_bf16 v[8:11], v[140:143], v[188:191], v[8:11]
	v_mfma_f32_16x16x32_bf16 v[4:7], v[148:151], v[188:191], v[4:7]
	v_mfma_f32_16x16x32_bf16 v[56:59], v[144:147], v[168:171], v[56:59]
	v_mfma_f32_16x16x32_bf16 v[52:55], v[152:155], v[168:171], v[52:55]
	v_mfma_f32_16x16x32_bf16 v[40:43], v[144:147], v[176:179], v[40:43]
	v_mfma_f32_16x16x32_bf16 v[36:39], v[152:155], v[176:179], v[36:39]
	v_mfma_f32_16x16x32_bf16 v[24:27], v[144:147], v[184:187], v[24:27]
	v_mfma_f32_16x16x32_bf16 v[20:23], v[152:155], v[184:187], v[20:23]
	v_mfma_f32_16x16x32_bf16 v[8:11], v[144:147], v[204:207], v[8:11]
	v_mfma_f32_16x16x32_bf16 v[4:7], v[152:155], v[204:207], v[4:7]
	s_barrier
	s_setprio 1
	ds_read_b128 v[116:119], v225 offset:32768
	ds_read_b128 v[128:131], v225 offset:33792
	ds_read_b128 v[132:135], v225 offset:34816
	ds_read_b128 v[136:139], v225 offset:35840
	ds_read_b128 v[140:143], v225 offset:49152
	ds_read_b128 v[144:147], v225 offset:50176
	ds_read_b128 v[148:151], v225 offset:51200
	ds_read_b128 v[152:155], v225 offset:52224
	s_add_u32 s16, s16, 0x20000
	s_addc_u32 s17, s17, 0
	s_mov_b32 m0, s45
	v_lshl_add_u64 v[216:217], s[16:17], 0, v[198:199]
	ds_read_b128 v[164:167], v224 offset:32768
	ds_read_b128 v[168:171], v224 offset:33792
	ds_read_b128 v[172:175], v224 offset:34816
	ds_read_b128 v[176:179], v224 offset:35840
	ds_read_b128 v[180:183], v224 offset:36864
	ds_read_b128 v[184:187], v224 offset:37888
	ds_read_b128 v[188:191], v224 offset:38912
	ds_read_b128 v[204:207], v224 offset:39936
	global_load_lds_dwordx4 v[216:217], off
	v_lshl_add_u64 v[216:217], s[16:17], 0, v[194:195]
	s_mov_b32 m0, s46
	s_nop 0
	global_load_lds_dwordx4 v[216:217], off
	s_waitcnt vmcnt(8)
	s_waitcnt lgkmcnt(0)
	s_setprio 0
	s_barrier
	v_mfma_f32_16x16x32_bf16 v[160:163], v[116:119], v[164:167], v[160:163]
	v_mfma_f32_16x16x32_bf16 v[156:159], v[132:135], v[164:167], v[156:159]
	v_mfma_f32_16x16x32_bf16 v[112:115], v[116:119], v[172:175], v[112:115]
	v_mfma_f32_16x16x32_bf16 v[108:111], v[132:135], v[172:175], v[108:111]
	v_mfma_f32_16x16x32_bf16 v[96:99], v[116:119], v[180:183], v[96:99]
	v_mfma_f32_16x16x32_bf16 v[92:95], v[132:135], v[180:183], v[92:95]
	v_mfma_f32_16x16x32_bf16 v[80:83], v[116:119], v[188:191], v[80:83]
	v_mfma_f32_16x16x32_bf16 v[76:79], v[132:135], v[188:191], v[76:79]
	v_mfma_f32_16x16x32_bf16 v[160:163], v[128:131], v[168:171], v[160:163]
	v_mfma_f32_16x16x32_bf16 v[156:159], v[136:139], v[168:171], v[156:159]
	v_mfma_f32_16x16x32_bf16 v[112:115], v[128:131], v[176:179], v[112:115]
	v_mfma_f32_16x16x32_bf16 v[108:111], v[136:139], v[176:179], v[108:111]
	v_mfma_f32_16x16x32_bf16 v[96:99], v[128:131], v[184:187], v[96:99]
	v_mfma_f32_16x16x32_bf16 v[92:95], v[136:139], v[184:187], v[92:95]
	v_mfma_f32_16x16x32_bf16 v[80:83], v[128:131], v[204:207], v[80:83]
	v_mfma_f32_16x16x32_bf16 v[76:79], v[136:139], v[204:207], v[76:79]
	v_mfma_f32_16x16x32_bf16 v[124:127], v[140:143], v[164:167], v[124:127]
	v_mfma_f32_16x16x32_bf16 v[120:123], v[148:151], v[164:167], v[120:123]
	v_mfma_f32_16x16x32_bf16 v[104:107], v[140:143], v[172:175], v[104:107]
	v_mfma_f32_16x16x32_bf16 v[100:103], v[148:151], v[172:175], v[100:103]
	v_mfma_f32_16x16x32_bf16 v[88:91], v[140:143], v[180:183], v[88:91]
	v_mfma_f32_16x16x32_bf16 v[84:87], v[148:151], v[180:183], v[84:87]
	v_mfma_f32_16x16x32_bf16 v[72:75], v[140:143], v[188:191], v[72:75]
	v_mfma_f32_16x16x32_bf16 v[68:71], v[148:151], v[188:191], v[68:71]
	v_mfma_f32_16x16x32_bf16 v[124:127], v[144:147], v[168:171], v[124:127]
	v_mfma_f32_16x16x32_bf16 v[120:123], v[152:155], v[168:171], v[120:123]
	v_mfma_f32_16x16x32_bf16 v[104:107], v[144:147], v[176:179], v[104:107]
	v_mfma_f32_16x16x32_bf16 v[100:103], v[152:155], v[176:179], v[100:103]
	v_mfma_f32_16x16x32_bf16 v[88:91], v[144:147], v[184:187], v[88:91]
	v_mfma_f32_16x16x32_bf16 v[84:87], v[152:155], v[184:187], v[84:87]
	v_mfma_f32_16x16x32_bf16 v[72:75], v[144:147], v[204:207], v[72:75]
	v_mfma_f32_16x16x32_bf16 v[68:71], v[152:155], v[204:207], v[68:71]
	s_barrier
; #define PG8_STAGE(bufoff, gbase, voff) do { _Pragma("unroll") for (int _i = 0; _i < 2; ++_i) \
;         __builtin_amdgcn_global_load_lds((const unsigned*)((const char*)(gbase) + (voff)[_i]), (LAS unsigned*)(lds + (bufoff) + ldsw + _i * 8192), 16, 0, 0); } while (0)
; #define PG8_LDA(dst, b, h) do { _Pragma("unroll") for (int m = 0; m < 4; ++m) _Pragma("unroll") for (int k = 0; k < 2; ++k) dst[m][k] = *(const LAS bf16x8*)(pA + PG8_SA(b, h) + m * 2048 + k * 1024); } while (0)
; #define PG8_MMA(ai, bj, At, Bt) do { __builtin_amdgcn_s_setprio(1); _Pragma("unroll") for (int m = 0; m < 4; ++m) _Pragma("unroll") for (int n = 0; n < 2; ++n) _Pragma("unroll") for (int k = 0; k < 2; ++k) \
;         acc[ai][bj][m][n] = __builtin_amdgcn_mfma_f32_16x16x32_bf16(Bt[n][k], At[m][k], acc[ai][bj][m][n], 0, 0, 0); __builtin_amdgcn_s_setprio(0); } while (0)
; #define PG8_WAIT_V(n) asm volatile("s_waitcnt vmcnt(" #n ")" ::: "memory")
; #define PG8_WAIT_L(n) asm volatile("s_waitcnt lgkmcnt(" #n ")" ::: "memory")
; #define PG8_BAR __builtin_amdgcn_s_barrier()
; #define PG8_SCHED __builtin_amdgcn_sched_barrier(0)
; template <class Desc, class Epi, bool ALIGN_EPI>
; __device__ __forceinline__ void gemm_phase(LAS unsigned char* lds, const Desc& D, const Epi& E, int G, int c) {
;     ...
;             PG8_LDA(At, 1, 1); PG8_STAGE(PG8_SB(1, 0), b3, voffB); PG8_STAGE(PG8_SB(1, 1), b3 + hstepB, voffB); PG8_STAGE(PG8_SA(1, 0), a3, voffA);
;             PG8_WAIT_V(8); PG8_WAIT_L(0); PG8_BAR; PG8_MMA(1, 0, At, B0); PG8_MMA(1, 1, At, B1); PG8_BAR; PG8_SCHED;
;         }
	s_setprio 1
	s_mov_b32 m0, s47
	v_lshl_add_u64 v[208:209], v[208:209], 0, s[76:77]
	s_add_u32 s12, s12, 0x20080
	ds_read_b128 v[164:167], v224 offset:49152
	ds_read_b128 v[168:171], v224 offset:50176
	ds_read_b128 v[172:175], v224 offset:51200
	ds_read_b128 v[176:179], v224 offset:52224
	ds_read_b128 v[180:183], v224 offset:53248
	ds_read_b128 v[184:187], v224 offset:54272
	ds_read_b128 v[188:191], v224 offset:55296
	ds_read_b128 v[204:207], v224 offset:56320
	global_load_lds_dwordx4 v[208:209], off
	v_lshl_add_u64 v[208:209], v[210:211], 0, s[76:77]
	s_mov_b32 m0, s48
	s_addc_u32 s13, s13, 0
	global_load_lds_dwordx4 v[208:209], off
	v_lshl_add_u64 v[208:209], s[12:13], 0, v[196:197]
	s_mov_b32 m0, s51
	s_nop 0
	global_load_lds_dwordx4 v[208:209], off
	v_lshl_add_u64 v[208:209], s[12:13], 0, v[192:193]
	s_mov_b32 m0, s52
	s_nop 0
	global_load_lds_dwordx4 v[208:209], off
	v_lshl_add_u64 v[208:209], v[212:213], 0, s[76:77]
	s_mov_b32 m0, s49
	s_nop 0
	global_load_lds_dwordx4 v[208:209], off
	v_lshl_add_u64 v[208:209], v[214:215], 0, s[76:77]
	s_mov_b32 m0, s50
	s_nop 0
	global_load_lds_dwordx4 v[208:209], off
	s_waitcnt vmcnt(8)
	s_waitcnt lgkmcnt(0)
	s_setprio 0
	s_barrier
	v_mfma_f32_16x16x32_bf16 v[64:67], v[116:119], v[164:167], v[64:67]
	v_mfma_f32_16x16x32_bf16 v[60:63], v[132:135], v[164:167], v[60:63]
	v_mfma_f32_16x16x32_bf16 v[48:51], v[116:119], v[172:175], v[48:51]
	v_mfma_f32_16x16x32_bf16 v[44:47], v[132:135], v[172:175], v[44:47]
	v_mfma_f32_16x16x32_bf16 v[32:35], v[116:119], v[180:183], v[32:35]
	v_mfma_f32_16x16x32_bf16 v[28:31], v[132:135], v[180:183], v[28:31]
	v_mfma_f32_16x16x32_bf16 v[16:19], v[116:119], v[188:191], v[16:19]
	v_mfma_f32_16x16x32_bf16 v[12:15], v[132:135], v[188:191], v[12:15]
	v_mfma_f32_16x16x32_bf16 v[64:67], v[128:131], v[168:171], v[64:67]
	v_mfma_f32_16x16x32_bf16 v[60:63], v[136:139], v[168:171], v[60:63]
	v_mfma_f32_16x16x32_bf16 v[48:51], v[128:131], v[176:179], v[48:51]
	v_mfma_f32_16x16x32_bf16 v[44:47], v[136:139], v[176:179], v[44:47]
	v_mfma_f32_16x16x32_bf16 v[32:35], v[128:131], v[184:187], v[32:35]
	v_mfma_f32_16x16x32_bf16 v[28:31], v[136:139], v[184:187], v[28:31]
	v_mfma_f32_16x16x32_bf16 v[16:19], v[128:131], v[204:207], v[16:19]
	v_mfma_f32_16x16x32_bf16 v[12:15], v[136:139], v[204:207], v[12:15]
	v_mfma_f32_16x16x32_bf16 v[56:59], v[140:143], v[164:167], v[56:59]
	v_mfma_f32_16x16x32_bf16 v[52:55], v[148:151], v[164:167], v[52:55]
	v_mfma_f32_16x16x32_bf16 v[40:43], v[140:143], v[172:175], v[40:43]
	v_mfma_f32_16x16x32_bf16 v[36:39], v[148:151], v[172:175], v[36:39]
	v_mfma_f32_16x16x32_bf16 v[24:27], v[140:143], v[180:183], v[24:27]
	v_mfma_f32_16x16x32_bf16 v[20:23], v[148:151], v[180:183], v[20:23]
	v_mfma_f32_16x16x32_bf16 v[8:11], v[140:143], v[188:191], v[8:11]
	v_mfma_f32_16x16x32_bf16 v[4:7], v[148:151], v[188:191], v[4:7]
	v_mfma_f32_16x16x32_bf16 v[56:59], v[144:147], v[168:171], v[56:59]
	v_mfma_f32_16x16x32_bf16 v[52:55], v[152:155], v[168:171], v[52:55]
	v_mfma_f32_16x16x32_bf16 v[40:43], v[144:147], v[176:179], v[40:43]
	v_mfma_f32_16x16x32_bf16 v[36:39], v[152:155], v[176:179], v[36:39]
	v_mfma_f32_16x16x32_bf16 v[24:27], v[144:147], v[184:187], v[24:27]
	v_mfma_f32_16x16x32_bf16 v[20:23], v[152:155], v[184:187], v[20:23]
	v_mfma_f32_16x16x32_bf16 v[8:11], v[144:147], v[204:207], v[8:11]
	v_mfma_f32_16x16x32_bf16 v[4:7], v[152:155], v[204:207], v[4:7]
	s_barrier
	s_setprio 1
	s_add_i32 s54, s54, 2
	s_add_u32 s0, s0, 0x100
	s_addc_u32 s1, s1, 0
	s_add_u32 s27, s27, 0x100
	s_addc_u32 s33, s33, 0
	s_cmp_gt_u32 s54, 5
	s_cbranch_scc0 .LBB0_1517
	s_and_b64 vcc, exec, s[10:11]
	s_cbranch_vccz .LBB0_1520
	s_barrier

; #define PG8_STAGE(bufoff, gbase, voff) do { _Pragma("unroll") for (int _i = 0; _i < 2; ++_i) \
;         __builtin_amdgcn_global_load_lds((const unsigned*)((const char*)(gbase) + (voff)[_i]), (LAS unsigned*)(lds + (bufoff) + ldsw + _i * 8192), 16, 0, 0); } while (0)
; #define PG8_LDA(dst, b, h) do { _Pragma("unroll") for (int m = 0; m < 4; ++m) _Pragma("unroll") for (int k = 0; k < 2; ++k) dst[m][k] = *(const LAS bf16x8*)(pA + PG8_SA(b, h) + m * 2048 + k * 1024); } while (0)
; #define PG8_LDB(dst, b, h) do { _Pragma("unroll") for (int n = 0; n < 2; ++n) _Pragma("unroll") for (int k = 0; k < 2; ++k) dst[n][k] = *(const LAS bf16x8*)(pB + (PG8_SB(b, h) - 4 * HTB) + n * 2048 + k * 1024); } while (0)
; #define PG8_MMA(ai, bj, At, Bt) do { __builtin_amdgcn_s_setprio(1); _Pragma("unroll") for (int m = 0; m < 4; ++m) _Pragma("unroll") for (int n = 0; n < 2; ++n) _Pragma("unroll") for (int k = 0; k < 2; ++k) \
;         acc[ai][bj][m][n] = __builtin_amdgcn_mfma_f32_16x16x32_bf16(Bt[n][k], At[m][k], acc[ai][bj][m][n], 0, 0, 0); __builtin_amdgcn_s_setprio(0); } while (0)
; #define PG8_WAIT_V(n) asm volatile("s_waitcnt vmcnt(" #n ")" ::: "memory")
; #define PG8_WAIT_L(n) asm volatile("s_waitcnt lgkmcnt(" #n ")" ::: "memory")
; #define PG8_BAR __builtin_amdgcn_s_barrier()
; #define PG8_SCHED __builtin_amdgcn_sched_barrier(0)
; template <class Desc, class Epi, bool ALIGN_EPI>
; __device__ __forceinline__ void gemm_phase(LAS unsigned char* lds, const Desc& D, const Epi& E, int G, int c) {
;     ...
;             if (last && has_next) PG8_AWAIT(nxt);
;             const char* a1 = cA + (size_t)(t + 1) * kstep;
;             const char* a2 = last ? nA : cA + (size_t)(t + 2) * kstep; const char* b2 = last ? nB : cB + (size_t)(t + 2) * kstep;
;             const char* a3 = a2 + kstep; const char* b3 = b2 + kstep;
;             PG8_LDB(B0, 0, 0); PG8_LDB(B1, 0, 1); PG8_SCHED; PG8_LDA(At, 0, 0); PG8_STAGE(PG8_SA(1, 1), a1 + hstepA, voffA);
;             PG8_WAIT_V(8); PG8_WAIT_L(0); PG8_BAR; PG8_MMA(0, 0, At, B0); PG8_MMA(0, 1, At, B1); PG8_BAR; PG8_SCHED;
;             PG8_LDA(At, 0, 1); PG8_STAGE(PG8_SB(0, 0), b2, voffB); PG8_STAGE(PG8_SB(0, 1), b2 + hstepB, voffB); PG8_STAGE(PG8_SA(0, 0), a2, voffA);
;             PG8_WAIT_V(8); PG8_WAIT_L(0); PG8_BAR; PG8_MMA(1, 0, At, B0); PG8_MMA(1, 1, At, B1); PG8_BAR; PG8_SCHED;
.LBB0_1580:
	s_or_b32 s14, s30, 1
	s_add_i32 s30, s30, 2
	s_mov_b32 s31, s15
	s_lshl_b64 s[72:73], s[14:15], 7
	s_lshl_b64 s[74:75], s[30:31], 7
	s_add_u32 s14, s18, s74
	ds_read_b128 v[140:143], v163
	ds_read_b128 v[144:147], v163 offset:1024
	ds_read_b128 v[148:151], v163 offset:2048
	ds_read_b128 v[152:155], v163 offset:3072
	ds_read_b128 v[156:159], v163 offset:16384
	ds_read_b128 v[166:169], v163 offset:17408
	ds_read_b128 v[170:173], v163 offset:18432
	ds_read_b128 v[174:177], v163 offset:19456
	s_addc_u32 s31, s19, s75
	s_and_b64 s[46:47], s[34:35], exec
	s_cselect_b32 s47, s43, s31
	s_cselect_b32 s46, s42, s14
	s_add_u32 s14, s20, s74
	s_addc_u32 s31, s21, s75
	s_and_b64 s[34:35], s[34:35], exec
	s_cselect_b32 s35, s3, s31
	s_cselect_b32 s34, s13, s14
	s_add_u32 s14, s18, s72
	s_addc_u32 s31, s19, s73
	s_add_u32 s72, s14, 0x100000
	s_addc_u32 s73, s31, 0
	s_add_i32 m0, s52, 0xc000
	ds_read_b128 v[178:181], v162
	ds_read_b128 v[182:185], v162 offset:1024
	ds_read_b128 v[186:189], v162 offset:2048
	ds_read_b128 v[190:193], v162 offset:3072
	ds_read_b128 v[194:197], v162 offset:4096
	ds_read_b128 v[198:201], v162 offset:5120
	ds_read_b128 v[202:205], v162 offset:6144
	ds_read_b128 v[206:209], v162 offset:7168
	global_load_lds_dwordx4 v132, s[72:73]
	s_add_i32 m0, s52, 0xe000
	s_nop 0
	global_load_lds_dwordx4 v136, s[72:73]
	s_waitcnt vmcnt(8)
	s_waitcnt lgkmcnt(0)
	s_setprio 0
	s_barrier
	v_mfma_f32_16x16x32_bf16 v[128:131], v[140:143], v[178:181], v[128:131]
	v_mfma_f32_16x16x32_bf16 v[124:127], v[148:151], v[178:181], v[124:127]
	v_mfma_f32_16x16x32_bf16 v[120:123], v[140:143], v[186:189], v[120:123]
	v_mfma_f32_16x16x32_bf16 v[116:119], v[148:151], v[186:189], v[116:119]
	v_mfma_f32_16x16x32_bf16 v[112:115], v[140:143], v[194:197], v[112:115]
	v_mfma_f32_16x16x32_bf16 v[108:111], v[148:151], v[194:197], v[108:111]
	v_mfma_f32_16x16x32_bf16 v[104:107], v[140:143], v[202:205], v[104:107]
	v_mfma_f32_16x16x32_bf16 v[100:103], v[148:151], v[202:205], v[100:103]
	v_mfma_f32_16x16x32_bf16 v[128:131], v[144:147], v[182:185], v[128:131]
	v_mfma_f32_16x16x32_bf16 v[124:127], v[152:155], v[182:185], v[124:127]
	v_mfma_f32_16x16x32_bf16 v[120:123], v[144:147], v[190:193], v[120:123]
	v_mfma_f32_16x16x32_bf16 v[116:119], v[152:155], v[190:193], v[116:119]
	v_mfma_f32_16x16x32_bf16 v[112:115], v[144:147], v[198:201], v[112:115]
	v_mfma_f32_16x16x32_bf16 v[108:111], v[152:155], v[198:201], v[108:111]
	v_mfma_f32_16x16x32_bf16 v[104:107], v[144:147], v[206:209], v[104:107]
	v_mfma_f32_16x16x32_bf16 v[100:103], v[152:155], v[206:209], v[100:103]
	v_mfma_f32_16x16x32_bf16 v[96:99], v[156:159], v[178:181], v[96:99]
	v_mfma_f32_16x16x32_bf16 v[92:95], v[170:173], v[178:181], v[92:95]
	v_mfma_f32_16x16x32_bf16 v[88:91], v[156:159], v[186:189], v[88:91]
	v_mfma_f32_16x16x32_bf16 v[84:87], v[170:173], v[186:189], v[84:87]
	v_mfma_f32_16x16x32_bf16 v[80:83], v[156:159], v[194:197], v[80:83]
	v_mfma_f32_16x16x32_bf16 v[76:79], v[170:173], v[194:197], v[76:79]
	v_mfma_f32_16x16x32_bf16 v[72:75], v[156:159], v[202:205], v[72:75]
	v_mfma_f32_16x16x32_bf16 v[68:71], v[170:173], v[202:205], v[68:71]
	v_mfma_f32_16x16x32_bf16 v[96:99], v[166:169], v[182:185], v[96:99]
	v_mfma_f32_16x16x32_bf16 v[92:95], v[174:177], v[182:185], v[92:95]
	v_mfma_f32_16x16x32_bf16 v[88:91], v[166:169], v[190:193], v[88:91]
	v_mfma_f32_16x16x32_bf16 v[84:87], v[174:177], v[190:193], v[84:87]
	v_mfma_f32_16x16x32_bf16 v[80:83], v[166:169], v[198:201], v[80:83]
	v_mfma_f32_16x16x32_bf16 v[76:79], v[174:177], v[198:201], v[76:79]
	v_mfma_f32_16x16x32_bf16 v[72:75], v[166:169], v[206:209], v[72:75]
	v_mfma_f32_16x16x32_bf16 v[68:71], v[174:177], v[206:209], v[68:71]
	s_barrier
	s_setprio 1
	s_mov_b32 m0, s53
	s_add_u32 s72, s34, 0x100000
	s_addc_u32 s73, s35, 0
	ds_read_b128 v[178:181], v162 offset:16384
	ds_read_b128 v[182:185], v162 offset:17408
	ds_read_b128 v[186:189], v162 offset:18432
	ds_read_b128 v[190:193], v162 offset:19456
	ds_read_b128 v[194:197], v162 offset:20480
	ds_read_b128 v[198:201], v162 offset:21504
	ds_read_b128 v[202:205], v162 offset:22528
	ds_read_b128 v[206:209], v162 offset:23552
	global_load_lds_dwordx4 v134, s[34:35]
	s_mov_b32 m0, s54
	s_nop 0
	global_load_lds_dwordx4 v138, s[34:35]
	s_mov_b32 m0, s55
	s_nop 0
	global_load_lds_dwordx4 v134, s[72:73]
	s_mov_b32 m0, s56
	s_nop 0
	global_load_lds_dwordx4 v138, s[72:73]
	s_mov_b32 m0, s52
	s_nop 0
	global_load_lds_dwordx4 v132, s[46:47]
	s_mov_b32 m0, s57
	s_nop 0
	global_load_lds_dwordx4 v136, s[46:47]
	s_waitcnt vmcnt(8)
	s_waitcnt lgkmcnt(0)
	s_setprio 0
	s_barrier
; #define PG8_STAGE(bufoff, gbase, voff) do { _Pragma("unroll") for (int _i = 0; _i < 2; ++_i) \
;         __builtin_amdgcn_global_load_lds((const unsigned*)((const char*)(gbase) + (voff)[_i]), (LAS unsigned*)(lds + (bufoff) + ldsw + _i * 8192), 16, 0, 0); } while (0)
; #define PG8_LDA(dst, b, h) do { _Pragma("unroll") for (int m = 0; m < 4; ++m) _Pragma("unroll") for (int k = 0; k < 2; ++k) dst[m][k] = *(const LAS bf16x8*)(pA + PG8_SA(b, h) + m * 2048 + k * 1024); } while (0)
; #define PG8_LDB(dst, b, h) do { _Pragma("unroll") for (int n = 0; n < 2; ++n) _Pragma("unroll") for (int k = 0; k < 2; ++k) dst[n][k] = *(const LAS bf16x8*)(pB + (PG8_SB(b, h) - 4 * HTB) + n * 2048 + k * 1024); } while (0)
; #define PG8_MMA(ai, bj, At, Bt) do { __builtin_amdgcn_s_setprio(1); _Pragma("unroll") for (int m = 0; m < 4; ++m) _Pragma("unroll") for (int n = 0; n < 2; ++n) _Pragma("unroll") for (int k = 0; k < 2; ++k) \
;         acc[ai][bj][m][n] = __builtin_amdgcn_mfma_f32_16x16x32_bf16(Bt[n][k], At[m][k], acc[ai][bj][m][n], 0, 0, 0); __builtin_amdgcn_s_setprio(0); } while (0)
; #define PG8_WAIT_V(n) asm volatile("s_waitcnt vmcnt(" #n ")" ::: "memory")
; #define PG8_WAIT_L(n) asm volatile("s_waitcnt lgkmcnt(" #n ")" ::: "memory")
; #define PG8_BAR __builtin_amdgcn_s_barrier()
; #define PG8_SCHED __builtin_amdgcn_sched_barrier(0)
; template <class Desc, class Epi, bool ALIGN_EPI>
; __device__ __forceinline__ void gemm_phase(LAS unsigned char* lds, const Desc& D, const Epi& E, int G, int c) {
;     ...
;             PG8_LDA(At, 0, 1); PG8_STAGE(PG8_SB(0, 0), b2, voffB); PG8_STAGE(PG8_SB(0, 1), b2 + hstepB, voffB); PG8_STAGE(PG8_SA(0, 0), a2, voffA);
;             PG8_WAIT_V(8); PG8_WAIT_L(0); PG8_BAR; PG8_MMA(1, 0, At, B0); PG8_MMA(1, 1, At, B1); PG8_BAR; PG8_SCHED;
;             PG8_LDB(B0, 1, 0); PG8_LDB(B1, 1, 1); PG8_SCHED; PG8_LDA(At, 1, 0); PG8_STAGE(PG8_SA(0, 1), a2 + hstepA, voffA);
;             PG8_WAIT_V(8); PG8_WAIT_L(0); PG8_BAR; PG8_MMA(0, 0, At, B0); PG8_MMA(0, 1, At, B1); PG8_BAR; PG8_SCHED;
	v_mfma_f32_16x16x32_bf16 v[64:67], v[140:143], v[178:181], v[64:67]
	v_mfma_f32_16x16x32_bf16 v[52:55], v[148:151], v[178:181], v[52:55]
	v_mfma_f32_16x16x32_bf16 v[32:35], v[140:143], v[186:189], v[32:35]
	v_mfma_f32_16x16x32_bf16 v[20:23], v[148:151], v[186:189], v[20:23]
	v_mfma_f32_16x16x32_bf16 v[16:19], v[140:143], v[194:197], v[16:19]
	v_mfma_f32_16x16x32_bf16 v[12:15], v[148:151], v[194:197], v[12:15]
	v_mfma_f32_16x16x32_bf16 v[8:11], v[140:143], v[202:205], v[8:11]
	v_mfma_f32_16x16x32_bf16 v[4:7], v[148:151], v[202:205], v[4:7]
	v_mfma_f32_16x16x32_bf16 v[64:67], v[144:147], v[182:185], v[64:67]
	v_mfma_f32_16x16x32_bf16 v[52:55], v[152:155], v[182:185], v[52:55]
	v_mfma_f32_16x16x32_bf16 v[32:35], v[144:147], v[190:193], v[32:35]
	v_mfma_f32_16x16x32_bf16 v[20:23], v[152:155], v[190:193], v[20:23]
	v_mfma_f32_16x16x32_bf16 v[16:19], v[144:147], v[198:201], v[16:19]
	v_mfma_f32_16x16x32_bf16 v[12:15], v[152:155], v[198:201], v[12:15]
	v_mfma_f32_16x16x32_bf16 v[8:11], v[144:147], v[206:209], v[8:11]
	v_mfma_f32_16x16x32_bf16 v[4:7], v[152:155], v[206:209], v[4:7]
	v_mfma_f32_16x16x32_bf16 v[60:63], v[156:159], v[178:181], v[60:63]
	v_mfma_f32_16x16x32_bf16 v[56:59], v[170:173], v[178:181], v[56:59]
	v_mfma_f32_16x16x32_bf16 v[48:51], v[156:159], v[186:189], v[48:51]
	v_mfma_f32_16x16x32_bf16 v[44:47], v[170:173], v[186:189], v[44:47]
	v_mfma_f32_16x16x32_bf16 v[40:43], v[156:159], v[194:197], v[40:43]
	v_mfma_f32_16x16x32_bf16 v[36:39], v[170:173], v[194:197], v[36:39]
	v_mfma_f32_16x16x32_bf16 v[28:31], v[156:159], v[202:205], v[28:31]
	v_mfma_f32_16x16x32_bf16 v[24:27], v[170:173], v[202:205], v[24:27]
	v_mfma_f32_16x16x32_bf16 v[60:63], v[166:169], v[182:185], v[60:63]
	v_mfma_f32_16x16x32_bf16 v[56:59], v[174:177], v[182:185], v[56:59]
	v_mfma_f32_16x16x32_bf16 v[48:51], v[166:169], v[190:193], v[48:51]
	v_mfma_f32_16x16x32_bf16 v[44:47], v[174:177], v[190:193], v[44:47]
	v_mfma_f32_16x16x32_bf16 v[40:43], v[166:169], v[198:201], v[40:43]
	v_mfma_f32_16x16x32_bf16 v[36:39], v[174:177], v[198:201], v[36:39]
	v_mfma_f32_16x16x32_bf16 v[28:31], v[166:169], v[206:209], v[28:31]
	v_mfma_f32_16x16x32_bf16 v[24:27], v[174:177], v[206:209], v[24:27]
	s_barrier
	s_setprio 1
	ds_read_b128 v[140:143], v163 offset:32768
	ds_read_b128 v[144:147], v163 offset:33792
	ds_read_b128 v[148:151], v163 offset:34816
	ds_read_b128 v[152:155], v163 offset:35840
	ds_read_b128 v[156:159], v163 offset:49152
	ds_read_b128 v[166:169], v163 offset:50176
	ds_read_b128 v[170:173], v163 offset:51200
	ds_read_b128 v[174:177], v163 offset:52224
	s_add_u32 s46, s46, 0x100000
	s_addc_u32 s47, s47, 0
	s_mov_b32 m0, s58
	ds_read_b128 v[178:181], v162 offset:32768
	ds_read_b128 v[182:185], v162 offset:33792
	ds_read_b128 v[186:189], v162 offset:34816
	ds_read_b128 v[190:193], v162 offset:35840
	ds_read_b128 v[194:197], v162 offset:36864
	ds_read_b128 v[198:201], v162 offset:37888
	ds_read_b128 v[202:205], v162 offset:38912
	ds_read_b128 v[206:209], v162 offset:39936
	global_load_lds_dwordx4 v132, s[46:47]
	s_mov_b32 m0, s59
	s_nop 0
	global_load_lds_dwordx4 v136, s[46:47]
	s_waitcnt vmcnt(8)
	s_waitcnt lgkmcnt(0)
	s_setprio 0
	s_barrier
	v_mfma_f32_16x16x32_bf16 v[128:131], v[140:143], v[178:181], v[128:131]
	v_mfma_f32_16x16x32_bf16 v[124:127], v[148:151], v[178:181], v[124:127]
	v_mfma_f32_16x16x32_bf16 v[120:123], v[140:143], v[186:189], v[120:123]
	v_mfma_f32_16x16x32_bf16 v[116:119], v[148:151], v[186:189], v[116:119]
	v_mfma_f32_16x16x32_bf16 v[112:115], v[140:143], v[194:197], v[112:115]
	v_mfma_f32_16x16x32_bf16 v[108:111], v[148:151], v[194:197], v[108:111]
	v_mfma_f32_16x16x32_bf16 v[104:107], v[140:143], v[202:205], v[104:107]
	v_mfma_f32_16x16x32_bf16 v[100:103], v[148:151], v[202:205], v[100:103]
	v_mfma_f32_16x16x32_bf16 v[128:131], v[144:147], v[182:185], v[128:131]
	v_mfma_f32_16x16x32_bf16 v[124:127], v[152:155], v[182:185], v[124:127]
	v_mfma_f32_16x16x32_bf16 v[120:123], v[144:147], v[190:193], v[120:123]
	v_mfma_f32_16x16x32_bf16 v[116:119], v[152:155], v[190:193], v[116:119]
	v_mfma_f32_16x16x32_bf16 v[112:115], v[144:147], v[198:201], v[112:115]
	v_mfma_f32_16x16x32_bf16 v[108:111], v[152:155], v[198:201], v[108:111]
	v_mfma_f32_16x16x32_bf16 v[104:107], v[144:147], v[206:209], v[104:107]
	v_mfma_f32_16x16x32_bf16 v[100:103], v[152:155], v[206:209], v[100:103]
	v_mfma_f32_16x16x32_bf16 v[96:99], v[156:159], v[178:181], v[96:99]
	v_mfma_f32_16x16x32_bf16 v[92:95], v[170:173], v[178:181], v[92:95]
	v_mfma_f32_16x16x32_bf16 v[88:91], v[156:159], v[186:189], v[88:91]
	v_mfma_f32_16x16x32_bf16 v[84:87], v[170:173], v[186:189], v[84:87]
	v_mfma_f32_16x16x32_bf16 v[80:83], v[156:159], v[194:197], v[80:83]
	v_mfma_f32_16x16x32_bf16 v[76:79], v[170:173], v[194:197], v[76:79]
	v_mfma_f32_16x16x32_bf16 v[72:75], v[156:159], v[202:205], v[72:75]
	v_mfma_f32_16x16x32_bf16 v[68:71], v[170:173], v[202:205], v[68:71]
	v_mfma_f32_16x16x32_bf16 v[96:99], v[166:169], v[182:185], v[96:99]
	v_mfma_f32_16x16x32_bf16 v[92:95], v[174:177], v[182:185], v[92:95]
	v_mfma_f32_16x16x32_bf16 v[88:91], v[166:169], v[190:193], v[88:91]
	v_mfma_f32_16x16x32_bf16 v[84:87], v[174:177], v[190:193], v[84:87]
	v_mfma_f32_16x16x32_bf16 v[80:83], v[166:169], v[198:201], v[80:83]
	v_mfma_f32_16x16x32_bf16 v[76:79], v[174:177], v[198:201], v[76:79]
	v_mfma_f32_16x16x32_bf16 v[72:75], v[166:169], v[206:209], v[72:75]
	v_mfma_f32_16x16x32_bf16 v[68:71], v[174:177], v[206:209], v[68:71]
	s_barrier
; #define PG8_STAGE(bufoff, gbase, voff) do { _Pragma("unroll") for (int _i = 0; _i < 2; ++_i) \
;         __builtin_amdgcn_global_load_lds((const unsigned*)((const char*)(gbase) + (voff)[_i]), (LAS unsigned*)(lds + (bufoff) + ldsw + _i * 8192), 16, 0, 0); } while (0)
; #define PG8_LDA(dst, b, h) do { _Pragma("unroll") for (int m = 0; m < 4; ++m) _Pragma("unroll") for (int k = 0; k < 2; ++k) dst[m][k] = *(const LAS bf16x8*)(pA + PG8_SA(b, h) + m * 2048 + k * 1024); } while (0)
; #define PG8_MMA(ai, bj, At, Bt) do { __builtin_amdgcn_s_setprio(1); _Pragma("unroll") for (int m = 0; m < 4; ++m) _Pragma("unroll") for (int n = 0; n < 2; ++n) _Pragma("unroll") for (int k = 0; k < 2; ++k) \
;         acc[ai][bj][m][n] = __builtin_amdgcn_mfma_f32_16x16x32_bf16(Bt[n][k], At[m][k], acc[ai][bj][m][n], 0, 0, 0); __builtin_amdgcn_s_setprio(0); } while (0)
; #define PG8_WAIT_V(n) asm volatile("s_waitcnt vmcnt(" #n ")" ::: "memory")
; #define PG8_WAIT_L(n) asm volatile("s_waitcnt lgkmcnt(" #n ")" ::: "memory")
; #define PG8_BAR __builtin_amdgcn_s_barrier()
; #define PG8_SCHED __builtin_amdgcn_sched_barrier(0)
; template <class Desc, class Epi, bool ALIGN_EPI>
; __device__ __forceinline__ void gemm_phase(LAS unsigned char* lds, const Desc& D, const Epi& E, int G, int c) {
;     ...
;             PG8_LDA(At, 1, 1); PG8_STAGE(PG8_SB(1, 0), b3, voffB); PG8_STAGE(PG8_SB(1, 1), b3 + hstepB, voffB); PG8_STAGE(PG8_SA(1, 0), a3, voffA);
;             PG8_WAIT_V(8); PG8_WAIT_L(0); PG8_BAR; PG8_MMA(1, 0, At, B0); PG8_MMA(1, 1, At, B1); PG8_BAR; PG8_SCHED;
;         }
	s_setprio 1
	s_mov_b32 m0, s61
	s_add_u32 s74, s34, 0x80
	s_addc_u32 s75, s35, 0
	s_add_u32 s34, s34, 0x100080
	s_addc_u32 s35, s35, 0
	ds_read_b128 v[178:181], v162 offset:49152
	ds_read_b128 v[182:185], v162 offset:50176
	ds_read_b128 v[186:189], v162 offset:51200
	ds_read_b128 v[190:193], v162 offset:52224
	ds_read_b128 v[194:197], v162 offset:53248
	ds_read_b128 v[198:201], v162 offset:54272
	ds_read_b128 v[202:205], v162 offset:55296
	ds_read_b128 v[206:209], v162 offset:56320
	global_load_lds_dwordx4 v134, s[74:75]
	s_mov_b32 m0, s62
	s_nop 0
	global_load_lds_dwordx4 v138, s[74:75]
	s_mov_b32 m0, s65
	s_nop 0
	global_load_lds_dwordx4 v134, s[34:35]
	s_mov_b32 m0, s67
	s_nop 0
	global_load_lds_dwordx4 v138, s[34:35]
	s_sub_u32 s74, s46, 0xfff80
	s_subb_u32 s75, s47, 0
	s_mov_b32 m0, s63
	s_nop 0
	global_load_lds_dwordx4 v132, s[74:75]
	s_mov_b32 m0, s64
	s_nop 0
	global_load_lds_dwordx4 v136, s[74:75]
	s_waitcnt vmcnt(8)
	s_waitcnt lgkmcnt(0)
	s_setprio 0
	s_barrier
	v_mfma_f32_16x16x32_bf16 v[64:67], v[140:143], v[178:181], v[64:67]
	v_mfma_f32_16x16x32_bf16 v[52:55], v[148:151], v[178:181], v[52:55]
	v_mfma_f32_16x16x32_bf16 v[32:35], v[140:143], v[186:189], v[32:35]
	v_mfma_f32_16x16x32_bf16 v[20:23], v[148:151], v[186:189], v[20:23]
	v_mfma_f32_16x16x32_bf16 v[16:19], v[140:143], v[194:197], v[16:19]
	v_mfma_f32_16x16x32_bf16 v[12:15], v[148:151], v[194:197], v[12:15]
	v_mfma_f32_16x16x32_bf16 v[8:11], v[140:143], v[202:205], v[8:11]
	v_mfma_f32_16x16x32_bf16 v[4:7], v[148:151], v[202:205], v[4:7]
	v_mfma_f32_16x16x32_bf16 v[64:67], v[144:147], v[182:185], v[64:67]
	v_mfma_f32_16x16x32_bf16 v[52:55], v[152:155], v[182:185], v[52:55]
	v_mfma_f32_16x16x32_bf16 v[32:35], v[144:147], v[190:193], v[32:35]
	v_mfma_f32_16x16x32_bf16 v[20:23], v[152:155], v[190:193], v[20:23]
	v_mfma_f32_16x16x32_bf16 v[16:19], v[144:147], v[198:201], v[16:19]
	v_mfma_f32_16x16x32_bf16 v[12:15], v[152:155], v[198:201], v[12:15]
	v_mfma_f32_16x16x32_bf16 v[8:11], v[144:147], v[206:209], v[8:11]
	v_mfma_f32_16x16x32_bf16 v[4:7], v[152:155], v[206:209], v[4:7]
	v_mfma_f32_16x16x32_bf16 v[60:63], v[156:159], v[178:181], v[60:63]
	v_mfma_f32_16x16x32_bf16 v[56:59], v[170:173], v[178:181], v[56:59]
	v_mfma_f32_16x16x32_bf16 v[48:51], v[156:159], v[186:189], v[48:51]
	v_mfma_f32_16x16x32_bf16 v[44:47], v[170:173], v[186:189], v[44:47]
	v_mfma_f32_16x16x32_bf16 v[40:43], v[156:159], v[194:197], v[40:43]
	v_mfma_f32_16x16x32_bf16 v[36:39], v[170:173], v[194:197], v[36:39]
	v_mfma_f32_16x16x32_bf16 v[28:31], v[156:159], v[202:205], v[28:31]
	v_mfma_f32_16x16x32_bf16 v[24:27], v[170:173], v[202:205], v[24:27]
	v_mfma_f32_16x16x32_bf16 v[60:63], v[166:169], v[182:185], v[60:63]
	v_mfma_f32_16x16x32_bf16 v[56:59], v[174:177], v[182:185], v[56:59]
	v_mfma_f32_16x16x32_bf16 v[48:51], v[166:169], v[190:193], v[48:51]
	v_mfma_f32_16x16x32_bf16 v[44:47], v[174:177], v[190:193], v[44:47]
	v_mfma_f32_16x16x32_bf16 v[40:43], v[166:169], v[198:201], v[40:43]
	v_mfma_f32_16x16x32_bf16 v[36:39], v[174:177], v[198:201], v[36:39]
	v_mfma_f32_16x16x32_bf16 v[28:31], v[166:169], v[206:209], v[28:31]
	v_mfma_f32_16x16x32_bf16 v[24:27], v[174:177], v[206:209], v[24:27]
	s_barrier
	s_setprio 1
	s_cmp_ge_u32 s30, s2
	s_cbranch_scc1 .LBB0_1591

; #define PG8_STAGE(bufoff, gbase, voff) do { _Pragma("unroll") for (int _i = 0; _i < 2; ++_i) \
;         __builtin_amdgcn_global_load_lds((const unsigned*)((const char*)(gbase) + (voff)[_i]), (LAS unsigned*)(lds + (bufoff) + ldsw + _i * 8192), 16, 0, 0); } while (0)
; #define PG8_LDA(dst, b, h) do { _Pragma("unroll") for (int m = 0; m < 4; ++m) _Pragma("unroll") for (int k = 0; k < 2; ++k) dst[m][k] = *(const LAS bf16x8*)(pA + PG8_SA(b, h) + m * 2048 + k * 1024); } while (0)
; #define PG8_LDB(dst, b, h) do { _Pragma("unroll") for (int n = 0; n < 2; ++n) _Pragma("unroll") for (int k = 0; k < 2; ++k) dst[n][k] = *(const LAS bf16x8*)(pB + (PG8_SB(b, h) - 4 * HTB) + n * 2048 + k * 1024); } while (0)
; #define PG8_MMA(ai, bj, At, Bt) do { __builtin_amdgcn_s_setprio(1); _Pragma("unroll") for (int m = 0; m < 4; ++m) _Pragma("unroll") for (int n = 0; n < 2; ++n) _Pragma("unroll") for (int k = 0; k < 2; ++k) \
;         acc[ai][bj][m][n] = __builtin_amdgcn_mfma_f32_16x16x32_bf16(Bt[n][k], At[m][k], acc[ai][bj][m][n], 0, 0, 0); __builtin_amdgcn_s_setprio(0); } while (0)
; #define PG8_WAIT_V(n) asm volatile("s_waitcnt vmcnt(" #n ")" ::: "memory")
; #define PG8_WAIT_L(n) asm volatile("s_waitcnt lgkmcnt(" #n ")" ::: "memory")
; #define PG8_BAR __builtin_amdgcn_s_barrier()
; #define PG8_SCHED __builtin_amdgcn_sched_barrier(0)
; template <class Desc, class Epi, bool ALIGN_EPI>
; __device__ __forceinline__ void gemm_phase(LAS unsigned char* lds, const Desc& D, const Epi& E, int G, int c) {
;     ...
;             if (last && has_next) PG8_AWAIT(nxt);
;             const char* a1 = cA + (size_t)(t + 1) * kstep;
;             const char* a2 = last ? nA : cA + (size_t)(t + 2) * kstep; const char* b2 = last ? nB : cB + (size_t)(t + 2) * kstep;
;             const char* a3 = a2 + kstep; const char* b3 = b2 + kstep;
;             PG8_LDB(B0, 0, 0); PG8_LDB(B1, 0, 1); PG8_SCHED; PG8_LDA(At, 0, 0); PG8_STAGE(PG8_SA(1, 1), a1 + hstepA, voffA);
;             PG8_WAIT_V(8); PG8_WAIT_L(0); PG8_BAR; PG8_MMA(0, 0, At, B0); PG8_MMA(0, 1, At, B1); PG8_BAR; PG8_SCHED;
;             PG8_LDA(At, 0, 1); PG8_STAGE(PG8_SB(0, 0), b2, voffB); PG8_STAGE(PG8_SB(0, 1), b2 + hstepB, voffB); PG8_STAGE(PG8_SA(0, 0), a2, voffA);
;             PG8_WAIT_V(8); PG8_WAIT_L(0); PG8_BAR; PG8_MMA(1, 0, At, B0); PG8_MMA(1, 1, At, B1); PG8_BAR; PG8_SCHED;
.LBB0_1765:
	s_or_b32 s14, s39, 1
	s_lshl_b64 s[40:41], s[14:15], 7
	s_add_i32 s14, s39, 2
	s_lshl_b64 s[42:43], s[14:15], 7
	s_add_u32 s39, s12, s42
	s_waitcnt lgkmcnt(0)
	ds_read_b128 v[132:135], v248
	ds_read_b128 v[136:139], v248 offset:1024
	ds_read_b128 v[140:143], v248 offset:2048
	ds_read_b128 v[144:147], v248 offset:3072
	ds_read_b128 v[148:151], v248 offset:16384
	ds_read_b128 v[152:155], v248 offset:17408
	ds_read_b128 v[156:159], v248 offset:18432
	ds_read_b128 v[160:163], v248 offset:19456
	s_addc_u32 s78, s13, s43
	s_and_b64 s[30:31], s[20:21], exec
	s_cselect_b32 s31, s49, s78
	s_cselect_b32 s30, s48, s39
	s_add_u32 s39, s16, s42
	s_addc_u32 s42, s17, s43
	s_and_b64 s[20:21], s[20:21], exec
	s_cselect_b32 s21, s51, s42
	s_cselect_b32 s20, s50, s39
	s_add_u32 s39, s12, s40
	s_addc_u32 s41, s13, s41
	s_add_u32 s40, s39, 0x2b0000
	s_addc_u32 s41, s41, 0
	v_lshl_add_u64 v[196:197], s[40:41], 0, v[200:201]
	s_add_i32 m0, s56, 0xc000
	ds_read_b128 v[164:167], v247
	ds_read_b128 v[168:171], v247 offset:1024
	ds_read_b128 v[172:175], v247 offset:2048
	ds_read_b128 v[176:179], v247 offset:3072
	ds_read_b128 v[180:183], v247 offset:4096
	ds_read_b128 v[184:187], v247 offset:5120
	ds_read_b128 v[188:191], v247 offset:6144
	ds_read_b128 v[192:195], v247 offset:7168
	global_load_lds_dwordx4 v[196:197], off
	v_lshl_add_u64 v[196:197], s[40:41], 0, v[204:205]
	s_add_i32 m0, s56, 0xe000
	s_nop 0
	global_load_lds_dwordx4 v[196:197], off
	s_waitcnt vmcnt(8)
	s_waitcnt lgkmcnt(0)
	s_setprio 0
	s_barrier
	v_mfma_f32_16x16x32_bf16 v[128:131], v[132:135], v[164:167], v[128:131]
	v_mfma_f32_16x16x32_bf16 v[124:127], v[140:143], v[164:167], v[124:127]
	v_mfma_f32_16x16x32_bf16 v[120:123], v[132:135], v[172:175], v[120:123]
	v_mfma_f32_16x16x32_bf16 v[116:119], v[140:143], v[172:175], v[116:119]
	v_mfma_f32_16x16x32_bf16 v[112:115], v[132:135], v[180:183], v[112:115]
	v_mfma_f32_16x16x32_bf16 v[108:111], v[140:143], v[180:183], v[108:111]
	v_mfma_f32_16x16x32_bf16 v[104:107], v[132:135], v[188:191], v[104:107]
	v_mfma_f32_16x16x32_bf16 v[100:103], v[140:143], v[188:191], v[100:103]
	v_mfma_f32_16x16x32_bf16 v[128:131], v[136:139], v[168:171], v[128:131]
	v_mfma_f32_16x16x32_bf16 v[124:127], v[144:147], v[168:171], v[124:127]
	v_mfma_f32_16x16x32_bf16 v[120:123], v[136:139], v[176:179], v[120:123]
	v_mfma_f32_16x16x32_bf16 v[116:119], v[144:147], v[176:179], v[116:119]
	v_mfma_f32_16x16x32_bf16 v[112:115], v[136:139], v[184:187], v[112:115]
	v_mfma_f32_16x16x32_bf16 v[108:111], v[144:147], v[184:187], v[108:111]
	v_mfma_f32_16x16x32_bf16 v[104:107], v[136:139], v[192:195], v[104:107]
	v_mfma_f32_16x16x32_bf16 v[100:103], v[144:147], v[192:195], v[100:103]
	v_mfma_f32_16x16x32_bf16 v[96:99], v[148:151], v[164:167], v[96:99]
	v_mfma_f32_16x16x32_bf16 v[92:95], v[156:159], v[164:167], v[92:95]
	v_mfma_f32_16x16x32_bf16 v[88:91], v[148:151], v[172:175], v[88:91]
	v_mfma_f32_16x16x32_bf16 v[80:83], v[156:159], v[172:175], v[80:83]
	v_mfma_f32_16x16x32_bf16 v[64:67], v[148:151], v[180:183], v[64:67]
	v_mfma_f32_16x16x32_bf16 v[52:55], v[156:159], v[180:183], v[52:55]
	v_mfma_f32_16x16x32_bf16 v[32:35], v[148:151], v[188:191], v[32:35]
	v_mfma_f32_16x16x32_bf16 v[20:23], v[156:159], v[188:191], v[20:23]
	v_mfma_f32_16x16x32_bf16 v[96:99], v[152:155], v[168:171], v[96:99]
	v_mfma_f32_16x16x32_bf16 v[92:95], v[160:163], v[168:171], v[92:95]
	v_mfma_f32_16x16x32_bf16 v[88:91], v[152:155], v[176:179], v[88:91]
	v_mfma_f32_16x16x32_bf16 v[80:83], v[160:163], v[176:179], v[80:83]
	v_mfma_f32_16x16x32_bf16 v[64:67], v[152:155], v[184:187], v[64:67]
	v_mfma_f32_16x16x32_bf16 v[52:55], v[160:163], v[184:187], v[52:55]
	v_mfma_f32_16x16x32_bf16 v[32:35], v[152:155], v[192:195], v[32:35]
	v_mfma_f32_16x16x32_bf16 v[20:23], v[160:163], v[192:195], v[20:23]
	s_barrier
	s_setprio 1
	s_mov_b32 m0, s57
	v_lshl_add_u64 v[196:197], s[20:21], 0, v[202:203]
	s_add_u32 s40, s20, 0x2b0000
	ds_read_b128 v[164:167], v247 offset:16384
	ds_read_b128 v[168:171], v247 offset:17408
	ds_read_b128 v[172:175], v247 offset:18432
	ds_read_b128 v[176:179], v247 offset:19456
	ds_read_b128 v[180:183], v247 offset:20480
	ds_read_b128 v[184:187], v247 offset:21504
	ds_read_b128 v[188:191], v247 offset:22528
	ds_read_b128 v[192:195], v247 offset:23552
	global_load_lds_dwordx4 v[196:197], off
	v_lshl_add_u64 v[198:199], s[20:21], 0, v[206:207]
	s_mov_b32 m0, s58
	s_addc_u32 s41, s21, 0
	global_load_lds_dwordx4 v[198:199], off
	v_lshl_add_u64 v[208:209], s[40:41], 0, v[202:203]
	s_mov_b32 m0, s59
	v_lshl_add_u64 v[210:211], s[30:31], 0, v[204:205]
	global_load_lds_dwordx4 v[208:209], off
	v_lshl_add_u64 v[208:209], s[40:41], 0, v[206:207]
	s_mov_b32 m0, s60
	s_nop 0
	global_load_lds_dwordx4 v[208:209], off
	v_lshl_add_u64 v[208:209], s[30:31], 0, v[200:201]
	s_mov_b32 m0, s56
	s_nop 0
	global_load_lds_dwordx4 v[208:209], off
	s_mov_b32 m0, s61
	s_nop 0
	global_load_lds_dwordx4 v[210:211], off
	s_waitcnt vmcnt(8)
	s_waitcnt lgkmcnt(0)
	s_setprio 0
	s_barrier
; #define PG8_STAGE(bufoff, gbase, voff) do { _Pragma("unroll") for (int _i = 0; _i < 2; ++_i) \
;         __builtin_amdgcn_global_load_lds((const unsigned*)((const char*)(gbase) + (voff)[_i]), (LAS unsigned*)(lds + (bufoff) + ldsw + _i * 8192), 16, 0, 0); } while (0)
; #define PG8_LDA(dst, b, h) do { _Pragma("unroll") for (int m = 0; m < 4; ++m) _Pragma("unroll") for (int k = 0; k < 2; ++k) dst[m][k] = *(const LAS bf16x8*)(pA + PG8_SA(b, h) + m * 2048 + k * 1024); } while (0)
; #define PG8_LDB(dst, b, h) do { _Pragma("unroll") for (int n = 0; n < 2; ++n) _Pragma("unroll") for (int k = 0; k < 2; ++k) dst[n][k] = *(const LAS bf16x8*)(pB + (PG8_SB(b, h) - 4 * HTB) + n * 2048 + k * 1024); } while (0)
; #define PG8_MMA(ai, bj, At, Bt) do { __builtin_amdgcn_s_setprio(1); _Pragma("unroll") for (int m = 0; m < 4; ++m) _Pragma("unroll") for (int n = 0; n < 2; ++n) _Pragma("unroll") for (int k = 0; k < 2; ++k) \
;         acc[ai][bj][m][n] = __builtin_amdgcn_mfma_f32_16x16x32_bf16(Bt[n][k], At[m][k], acc[ai][bj][m][n], 0, 0, 0); __builtin_amdgcn_s_setprio(0); } while (0)
; #define PG8_WAIT_V(n) asm volatile("s_waitcnt vmcnt(" #n ")" ::: "memory")
; #define PG8_WAIT_L(n) asm volatile("s_waitcnt lgkmcnt(" #n ")" ::: "memory")
; #define PG8_BAR __builtin_amdgcn_s_barrier()
; #define PG8_SCHED __builtin_amdgcn_sched_barrier(0)
; template <class Desc, class Epi, bool ALIGN_EPI>
; __device__ __forceinline__ void gemm_phase(LAS unsigned char* lds, const Desc& D, const Epi& E, int G, int c) {
;     ...
;             PG8_LDA(At, 0, 1); PG8_STAGE(PG8_SB(0, 0), b2, voffB); PG8_STAGE(PG8_SB(0, 1), b2 + hstepB, voffB); PG8_STAGE(PG8_SA(0, 0), a2, voffA);
;             PG8_WAIT_V(8); PG8_WAIT_L(0); PG8_BAR; PG8_MMA(1, 0, At, B0); PG8_MMA(1, 1, At, B1); PG8_BAR; PG8_SCHED;
;             PG8_LDB(B0, 1, 0); PG8_LDB(B1, 1, 1); PG8_SCHED; PG8_LDA(At, 1, 0); PG8_STAGE(PG8_SA(0, 1), a2 + hstepA, voffA);
;             PG8_WAIT_V(8); PG8_WAIT_L(0); PG8_BAR; PG8_MMA(0, 0, At, B0); PG8_MMA(0, 1, At, B1); PG8_BAR; PG8_SCHED;
	v_mfma_f32_16x16x32_bf16 v[84:87], v[132:135], v[164:167], v[84:87]
	v_mfma_f32_16x16x32_bf16 v[76:79], v[140:143], v[164:167], v[76:79]
	v_mfma_f32_16x16x32_bf16 v[72:75], v[132:135], v[172:175], v[72:75]
	v_mfma_f32_16x16x32_bf16 v[68:71], v[140:143], v[172:175], v[68:71]
	v_mfma_f32_16x16x32_bf16 v[60:63], v[132:135], v[180:183], v[60:63]
	v_mfma_f32_16x16x32_bf16 v[56:59], v[140:143], v[180:183], v[56:59]
	v_mfma_f32_16x16x32_bf16 v[48:51], v[132:135], v[188:191], v[48:51]
	v_mfma_f32_16x16x32_bf16 v[44:47], v[140:143], v[188:191], v[44:47]
	v_mfma_f32_16x16x32_bf16 v[84:87], v[136:139], v[168:171], v[84:87]
	v_mfma_f32_16x16x32_bf16 v[76:79], v[144:147], v[168:171], v[76:79]
	v_mfma_f32_16x16x32_bf16 v[72:75], v[136:139], v[176:179], v[72:75]
	v_mfma_f32_16x16x32_bf16 v[68:71], v[144:147], v[176:179], v[68:71]
	v_mfma_f32_16x16x32_bf16 v[60:63], v[136:139], v[184:187], v[60:63]
	v_mfma_f32_16x16x32_bf16 v[56:59], v[144:147], v[184:187], v[56:59]
	v_mfma_f32_16x16x32_bf16 v[48:51], v[136:139], v[192:195], v[48:51]
	v_mfma_f32_16x16x32_bf16 v[44:47], v[144:147], v[192:195], v[44:47]
	v_mfma_f32_16x16x32_bf16 v[40:43], v[148:151], v[164:167], v[40:43]
	v_mfma_f32_16x16x32_bf16 v[36:39], v[156:159], v[164:167], v[36:39]
	v_mfma_f32_16x16x32_bf16 v[28:31], v[148:151], v[172:175], v[28:31]
	v_mfma_f32_16x16x32_bf16 v[24:27], v[156:159], v[172:175], v[24:27]
	v_mfma_f32_16x16x32_bf16 v[16:19], v[148:151], v[180:183], v[16:19]
	v_mfma_f32_16x16x32_bf16 v[12:15], v[156:159], v[180:183], v[12:15]
	v_mfma_f32_16x16x32_bf16 v[8:11], v[148:151], v[188:191], v[8:11]
	v_mfma_f32_16x16x32_bf16 v[4:7], v[156:159], v[188:191], v[4:7]
	v_mfma_f32_16x16x32_bf16 v[40:43], v[152:155], v[168:171], v[40:43]
	v_mfma_f32_16x16x32_bf16 v[36:39], v[160:163], v[168:171], v[36:39]
	v_mfma_f32_16x16x32_bf16 v[28:31], v[152:155], v[176:179], v[28:31]
	v_mfma_f32_16x16x32_bf16 v[24:27], v[160:163], v[176:179], v[24:27]
	v_mfma_f32_16x16x32_bf16 v[16:19], v[152:155], v[184:187], v[16:19]
	v_mfma_f32_16x16x32_bf16 v[12:15], v[160:163], v[184:187], v[12:15]
	v_mfma_f32_16x16x32_bf16 v[8:11], v[152:155], v[192:195], v[8:11]
	v_mfma_f32_16x16x32_bf16 v[4:7], v[160:163], v[192:195], v[4:7]
	s_barrier
	s_setprio 1
	ds_read_b128 v[132:135], v248 offset:32768
	ds_read_b128 v[136:139], v248 offset:33792
	ds_read_b128 v[140:143], v248 offset:34816
	ds_read_b128 v[144:147], v248 offset:35840
	ds_read_b128 v[148:151], v248 offset:49152
	ds_read_b128 v[152:155], v248 offset:50176
	ds_read_b128 v[156:159], v248 offset:51200
	ds_read_b128 v[160:163], v248 offset:52224
	s_add_u32 s30, s30, 0x2b0000
	s_addc_u32 s31, s31, 0
	s_mov_b32 m0, s62
	v_lshl_add_u64 v[212:213], s[30:31], 0, v[200:201]
	ds_read_b128 v[164:167], v247 offset:32768
	ds_read_b128 v[168:171], v247 offset:33792
	ds_read_b128 v[172:175], v247 offset:34816
	ds_read_b128 v[176:179], v247 offset:35840
	ds_read_b128 v[180:183], v247 offset:36864
	ds_read_b128 v[184:187], v247 offset:37888
	ds_read_b128 v[188:191], v247 offset:38912
	ds_read_b128 v[192:195], v247 offset:39936
	global_load_lds_dwordx4 v[212:213], off
	v_lshl_add_u64 v[212:213], s[30:31], 0, v[204:205]
	s_mov_b32 m0, s63
	s_nop 0
	global_load_lds_dwordx4 v[212:213], off
	s_waitcnt vmcnt(8)
	s_waitcnt lgkmcnt(0)
	s_setprio 0
	s_barrier
	v_mfma_f32_16x16x32_bf16 v[128:131], v[132:135], v[164:167], v[128:131]
	v_mfma_f32_16x16x32_bf16 v[124:127], v[140:143], v[164:167], v[124:127]
	v_mfma_f32_16x16x32_bf16 v[120:123], v[132:135], v[172:175], v[120:123]
	v_mfma_f32_16x16x32_bf16 v[116:119], v[140:143], v[172:175], v[116:119]
	v_mfma_f32_16x16x32_bf16 v[112:115], v[132:135], v[180:183], v[112:115]
	v_mfma_f32_16x16x32_bf16 v[108:111], v[140:143], v[180:183], v[108:111]
	v_mfma_f32_16x16x32_bf16 v[104:107], v[132:135], v[188:191], v[104:107]
	v_mfma_f32_16x16x32_bf16 v[100:103], v[140:143], v[188:191], v[100:103]
	v_mfma_f32_16x16x32_bf16 v[128:131], v[136:139], v[168:171], v[128:131]
	v_mfma_f32_16x16x32_bf16 v[124:127], v[144:147], v[168:171], v[124:127]
	v_mfma_f32_16x16x32_bf16 v[120:123], v[136:139], v[176:179], v[120:123]
	v_mfma_f32_16x16x32_bf16 v[116:119], v[144:147], v[176:179], v[116:119]
	v_mfma_f32_16x16x32_bf16 v[112:115], v[136:139], v[184:187], v[112:115]
	v_mfma_f32_16x16x32_bf16 v[108:111], v[144:147], v[184:187], v[108:111]
	v_mfma_f32_16x16x32_bf16 v[104:107], v[136:139], v[192:195], v[104:107]
	v_mfma_f32_16x16x32_bf16 v[100:103], v[144:147], v[192:195], v[100:103]
	v_mfma_f32_16x16x32_bf16 v[96:99], v[148:151], v[164:167], v[96:99]
	v_mfma_f32_16x16x32_bf16 v[92:95], v[156:159], v[164:167], v[92:95]
	v_mfma_f32_16x16x32_bf16 v[88:91], v[148:151], v[172:175], v[88:91]
	v_mfma_f32_16x16x32_bf16 v[80:83], v[156:159], v[172:175], v[80:83]
	v_mfma_f32_16x16x32_bf16 v[64:67], v[148:151], v[180:183], v[64:67]
	v_mfma_f32_16x16x32_bf16 v[52:55], v[156:159], v[180:183], v[52:55]
	v_mfma_f32_16x16x32_bf16 v[32:35], v[148:151], v[188:191], v[32:35]
	v_mfma_f32_16x16x32_bf16 v[20:23], v[156:159], v[188:191], v[20:23]
	v_mfma_f32_16x16x32_bf16 v[96:99], v[152:155], v[168:171], v[96:99]
	v_mfma_f32_16x16x32_bf16 v[92:95], v[160:163], v[168:171], v[92:95]
	v_mfma_f32_16x16x32_bf16 v[88:91], v[152:155], v[176:179], v[88:91]
	v_mfma_f32_16x16x32_bf16 v[80:83], v[160:163], v[176:179], v[80:83]
	v_mfma_f32_16x16x32_bf16 v[64:67], v[152:155], v[184:187], v[64:67]
	v_mfma_f32_16x16x32_bf16 v[52:55], v[160:163], v[184:187], v[52:55]
	v_mfma_f32_16x16x32_bf16 v[32:35], v[152:155], v[192:195], v[32:35]
	v_mfma_f32_16x16x32_bf16 v[20:23], v[160:163], v[192:195], v[20:23]
	s_barrier
; #define PG8_STAGE(bufoff, gbase, voff) do { _Pragma("unroll") for (int _i = 0; _i < 2; ++_i) \
;         __builtin_amdgcn_global_load_lds((const unsigned*)((const char*)(gbase) + (voff)[_i]), (LAS unsigned*)(lds + (bufoff) + ldsw + _i * 8192), 16, 0, 0); } while (0)
; #define PG8_LDA(dst, b, h) do { _Pragma("unroll") for (int m = 0; m < 4; ++m) _Pragma("unroll") for (int k = 0; k < 2; ++k) dst[m][k] = *(const LAS bf16x8*)(pA + PG8_SA(b, h) + m * 2048 + k * 1024); } while (0)
; #define PG8_MMA(ai, bj, At, Bt) do { __builtin_amdgcn_s_setprio(1); _Pragma("unroll") for (int m = 0; m < 4; ++m) _Pragma("unroll") for (int n = 0; n < 2; ++n) _Pragma("unroll") for (int k = 0; k < 2; ++k) \
;         acc[ai][bj][m][n] = __builtin_amdgcn_mfma_f32_16x16x32_bf16(Bt[n][k], At[m][k], acc[ai][bj][m][n], 0, 0, 0); __builtin_amdgcn_s_setprio(0); } while (0)
; #define PG8_WAIT_V(n) asm volatile("s_waitcnt vmcnt(" #n ")" ::: "memory")
; #define PG8_WAIT_L(n) asm volatile("s_waitcnt lgkmcnt(" #n ")" ::: "memory")
; #define PG8_BAR __builtin_amdgcn_s_barrier()
; #define PG8_SCHED __builtin_amdgcn_sched_barrier(0)
; template <class Desc, class Epi, bool ALIGN_EPI>
; __device__ __forceinline__ void gemm_phase(LAS unsigned char* lds, const Desc& D, const Epi& E, int G, int c) {
;     ...
;             PG8_LDA(At, 1, 1); PG8_STAGE(PG8_SB(1, 0), b3, voffB); PG8_STAGE(PG8_SB(1, 1), b3 + hstepB, voffB); PG8_STAGE(PG8_SA(1, 0), a3, voffA);
;             PG8_WAIT_V(8); PG8_WAIT_L(0); PG8_BAR; PG8_MMA(1, 0, At, B0); PG8_MMA(1, 1, At, B1); PG8_BAR; PG8_SCHED;
;         }
	s_setprio 1
	s_mov_b32 m0, s64
	v_lshl_add_u64 v[196:197], v[196:197], 0, s[76:77]
	s_add_u32 s20, s20, 0x2b0080
	ds_read_b128 v[164:167], v247 offset:49152
	ds_read_b128 v[168:171], v247 offset:50176
	ds_read_b128 v[172:175], v247 offset:51200
	ds_read_b128 v[176:179], v247 offset:52224
	ds_read_b128 v[180:183], v247 offset:53248
	ds_read_b128 v[184:187], v247 offset:54272
	ds_read_b128 v[188:191], v247 offset:55296
	ds_read_b128 v[192:195], v247 offset:56320
	global_load_lds_dwordx4 v[196:197], off
	v_lshl_add_u64 v[196:197], v[198:199], 0, s[76:77]
	s_mov_b32 m0, s65
	s_addc_u32 s21, s21, 0
	global_load_lds_dwordx4 v[196:197], off
	v_lshl_add_u64 v[196:197], s[20:21], 0, v[202:203]
	s_mov_b32 m0, s69
	s_nop 0
	global_load_lds_dwordx4 v[196:197], off
	v_lshl_add_u64 v[196:197], s[20:21], 0, v[206:207]
	s_mov_b32 m0, s70
	s_nop 0
	global_load_lds_dwordx4 v[196:197], off
	v_lshl_add_u64 v[196:197], v[208:209], 0, s[76:77]
	s_mov_b32 m0, s66
	s_nop 0
	global_load_lds_dwordx4 v[196:197], off
	v_lshl_add_u64 v[196:197], v[210:211], 0, s[76:77]
	s_mov_b32 m0, s67
	s_nop 0
	global_load_lds_dwordx4 v[196:197], off
	s_waitcnt vmcnt(8)
	s_waitcnt lgkmcnt(0)
	s_setprio 0
	s_barrier
	v_mfma_f32_16x16x32_bf16 v[84:87], v[132:135], v[164:167], v[84:87]
	v_mfma_f32_16x16x32_bf16 v[76:79], v[140:143], v[164:167], v[76:79]
	v_mfma_f32_16x16x32_bf16 v[72:75], v[132:135], v[172:175], v[72:75]
	v_mfma_f32_16x16x32_bf16 v[68:71], v[140:143], v[172:175], v[68:71]
	v_mfma_f32_16x16x32_bf16 v[60:63], v[132:135], v[180:183], v[60:63]
	v_mfma_f32_16x16x32_bf16 v[56:59], v[140:143], v[180:183], v[56:59]
	v_mfma_f32_16x16x32_bf16 v[48:51], v[132:135], v[188:191], v[48:51]
	v_mfma_f32_16x16x32_bf16 v[44:47], v[140:143], v[188:191], v[44:47]
	v_mfma_f32_16x16x32_bf16 v[84:87], v[136:139], v[168:171], v[84:87]
	v_mfma_f32_16x16x32_bf16 v[76:79], v[144:147], v[168:171], v[76:79]
	v_mfma_f32_16x16x32_bf16 v[72:75], v[136:139], v[176:179], v[72:75]
	v_mfma_f32_16x16x32_bf16 v[68:71], v[144:147], v[176:179], v[68:71]
	v_mfma_f32_16x16x32_bf16 v[60:63], v[136:139], v[184:187], v[60:63]
	v_mfma_f32_16x16x32_bf16 v[56:59], v[144:147], v[184:187], v[56:59]
	v_mfma_f32_16x16x32_bf16 v[48:51], v[136:139], v[192:195], v[48:51]
	v_mfma_f32_16x16x32_bf16 v[44:47], v[144:147], v[192:195], v[44:47]
	v_mfma_f32_16x16x32_bf16 v[40:43], v[148:151], v[164:167], v[40:43]
	v_mfma_f32_16x16x32_bf16 v[36:39], v[156:159], v[164:167], v[36:39]
	v_mfma_f32_16x16x32_bf16 v[28:31], v[148:151], v[172:175], v[28:31]
	v_mfma_f32_16x16x32_bf16 v[24:27], v[156:159], v[172:175], v[24:27]
	v_mfma_f32_16x16x32_bf16 v[16:19], v[148:151], v[180:183], v[16:19]
	v_mfma_f32_16x16x32_bf16 v[12:15], v[156:159], v[180:183], v[12:15]
	v_mfma_f32_16x16x32_bf16 v[8:11], v[148:151], v[188:191], v[8:11]
	v_mfma_f32_16x16x32_bf16 v[4:7], v[156:159], v[188:191], v[4:7]
	v_mfma_f32_16x16x32_bf16 v[40:43], v[152:155], v[168:171], v[40:43]
	v_mfma_f32_16x16x32_bf16 v[36:39], v[160:163], v[168:171], v[36:39]
	v_mfma_f32_16x16x32_bf16 v[28:31], v[152:155], v[176:179], v[28:31]
	v_mfma_f32_16x16x32_bf16 v[24:27], v[160:163], v[176:179], v[24:27]
	v_mfma_f32_16x16x32_bf16 v[16:19], v[152:155], v[184:187], v[16:19]
	v_mfma_f32_16x16x32_bf16 v[12:15], v[160:163], v[184:187], v[12:15]
	v_mfma_f32_16x16x32_bf16 v[8:11], v[152:155], v[192:195], v[8:11]
	v_mfma_f32_16x16x32_bf16 v[4:7], v[160:163], v[192:195], v[4:7]
	s_barrier
	s_setprio 1
	s_cmp_ge_u32 s14, s24
	s_mov_b32 s39, s14
	s_cbranch_scc1 .LBB0_1776
